# address setup that followed the last MFMA of GEMM phases 2,4,6 moved behind the closing barrier
# speedup vs baseline: 1.0091x; 1.0013x over previous
; #define PG8_STAGE(bufoff, gbase, voff) do { _Pragma("unroll") for (int _i = 0; _i < 2; ++_i) \
;     __builtin_amdgcn_global_load_lds((const unsigned*)((const char*)(gbase) + (voff)[_i]), (PG8_LAS unsigned*)(lds + (bufoff) + ldsw + _i * 8192), 16, 0, 0); } while (0)
; #define PG8_LDA(dst, b, h) do { _Pragma("unroll") for (int m = 0; m < 4; ++m) _Pragma("unroll") for (int k = 0; k < 2; ++k) dst[m][k] = *(const PG8_LAS bf16x8*)(lds + PG8_SA(b, h) + aoff + m * 2048 + k * 1024); } while (0)
; #define PG8_LDB(dst, b, h) do { _Pragma("unroll") for (int n = 0; n < 2; ++n) _Pragma("unroll") for (int k = 0; k < 2; ++k) dst[n][k] = *(const PG8_LAS bf16x8*)(lds + PG8_SB(b, h) + boff + n * 2048 + k * 1024); } while (0)
; #define PG8_MMA(ai, bj, At, Bt) do { __builtin_amdgcn_s_setprio(1); _Pragma("unroll") for (int m = 0; m < 4; ++m) _Pragma("unroll") for (int n = 0; n < 2; ++n) _Pragma("unroll") for (int k = 0; k < 2; ++k) \
;     acc[ai][bj][m][n] = __builtin_amdgcn_mfma_f32_16x16x32_bf16(Bt[n][k], At[m][k], acc[ai][bj][m][n], 0, 0, 0); __builtin_amdgcn_s_setprio(0); } while (0)
; #define PG8_WAIT_L(n) asm volatile("s_waitcnt lgkmcnt(" #n ")" ::: "memory")
; #define PG8_BAR __builtin_amdgcn_s_barrier()
; #define PG8_SCHED __builtin_amdgcn_sched_barrier(0)
; template <class Epi, class Sched>
; __device__ __forceinline__ void gemm_phase(PG8_LAS unsigned char* lds, const int lda, const int ldb, const Sched& S, const Epi& E) {
;     ...
;     for (int t = 0; t < nt; t += 2) {
;       const bool last = (t == nt - 2);
;       const char* a1 = cA + (size_t)(t + 1) * kstep;
;       const char* a2 = last ? nA : cA + (size_t)(t + 2) * kstep; const char* b2 = last ? nB : cB + (size_t)(t + 2) * kstep;
;       const char* a3 = a2 + kstep; const char* b3 = b2 + kstep;
;       PG8_LDB(B0, 0, 0); PG8_SCHED; PG8_LDA(At, 0, 0); PG8_STAGE(PG8_SA(1, 1), a1 + hstepA, voffA);
;       PG8_WAIT_L(8); PG8_BAR; PG8_WAIT_L(0); PG8_MMA(0, 0, At, B0); PG8_BAR; PG8_SCHED;
;       PG8_LDB(B1, 0, 1); PG8_STAGE(PG8_SB(0, 0), b2, voffB);
;       PG8_BAR; PG8_WAIT_L(0); PG8_MMA(0, 1, At, B1); PG8_BAR;
;       PG8_LDA(At, 0, 1); PG8_STAGE(PG8_SA(0, 0), a2, voffA);
;       PG8_BAR; PG8_WAIT_L(0); PG8_MMA(1, 0, At, B0); PG8_BAR; PG8_SCHED;
.LBB0_335:
	s_add_u32 s10, s8, 0xfffc0080
	s_addc_u32 s11, s9, -1
	s_add_i32 s31, 0, 0x10000
	v_add_u32_e32 v156, s31, v131
	ds_read_b128 v[144:147], v156
	ds_read_b128 v[148:151], v156 offset:1024
	ds_read_b128 v[152:155], v156 offset:2048
	ds_read_b128 v[200:203], v156 offset:3072
	s_cmp_eq_u32 s30, 12
	s_cselect_b32 s25, s17, s11
	s_cselect_b32 s24, s26, s10
	s_cselect_b32 s11, s15, s29
	s_cselect_b32 s10, s27, s28
	v_lshl_add_u64 v[156:157], s[8:9], 0, v[140:141]
	s_add_i32 m0, s40, 0xc000
	ds_read_b128 v[204:207], v172
	ds_read_b128 v[208:211], v172 offset:1024
	ds_read_b128 v[212:215], v172 offset:2048
	ds_read_b128 v[216:219], v172 offset:3072
	ds_read_b128 v[220:223], v172 offset:4096
	ds_read_b128 v[224:227], v172 offset:5120
	ds_read_b128 v[228:231], v172 offset:6144
	ds_read_b128 v[232:235], v172 offset:7168
	global_load_lds_dwordx4 v[156:157], off
	v_lshl_add_u64 v[156:157], s[8:9], 0, v[142:143]
	s_add_i32 m0, s40, 0xe000
	s_nop 0
	global_load_lds_dwordx4 v[156:157], off
	s_waitcnt lgkmcnt(8)
	s_barrier
	s_waitcnt lgkmcnt(0)
	v_mfma_f32_16x16x32_bf16 v[126:129], v[144:147], v[204:207], v[126:129]
	v_mfma_f32_16x16x32_bf16 v[122:125], v[152:155], v[204:207], v[122:125]
	v_mfma_f32_16x16x32_bf16 v[110:113], v[144:147], v[212:215], v[110:113]
	v_mfma_f32_16x16x32_bf16 v[106:109], v[152:155], v[212:215], v[106:109]
	v_mfma_f32_16x16x32_bf16 v[94:97], v[144:147], v[220:223], v[94:97]
	v_mfma_f32_16x16x32_bf16 v[90:93], v[152:155], v[220:223], v[90:93]
	v_mfma_f32_16x16x32_bf16 v[78:81], v[144:147], v[228:231], v[78:81]
	v_mfma_f32_16x16x32_bf16 v[74:77], v[152:155], v[228:231], v[74:77]
	v_mfma_f32_16x16x32_bf16 v[126:129], v[148:151], v[208:211], v[126:129]
	v_mfma_f32_16x16x32_bf16 v[122:125], v[200:203], v[208:211], v[122:125]
	v_mfma_f32_16x16x32_bf16 v[110:113], v[148:151], v[216:219], v[110:113]
	v_mfma_f32_16x16x32_bf16 v[106:109], v[200:203], v[216:219], v[106:109]
	v_mfma_f32_16x16x32_bf16 v[94:97], v[148:151], v[224:227], v[94:97]
	v_mfma_f32_16x16x32_bf16 v[90:93], v[200:203], v[224:227], v[90:93]
	v_mfma_f32_16x16x32_bf16 v[78:81], v[148:151], v[232:235], v[78:81]
	v_mfma_f32_16x16x32_bf16 v[74:77], v[200:203], v[232:235], v[74:77]
	s_barrier
	s_add_i32 s33, 0, 0x14000
	v_add_u32_e32 v156, s33, v131
	s_add_i32 s31, s31, s39
	ds_read_b128 v[236:239], v156
	ds_read_b128 v[240:243], v156 offset:1024
	ds_read_b128 v[244:247], v156 offset:2048
	ds_read_b128 v[248:251], v156 offset:3072
	v_lshl_add_u64 v[156:157], s[10:11], 0, v[134:135]
	s_mov_b32 m0, s31
	v_lshl_add_u64 v[174:175], s[10:11], 0, v[132:133]
	global_load_lds_dwordx4 v[156:157], off
	s_add_i32 m0, s31, 0x2000
	s_nop 0
	global_load_lds_dwordx4 v[174:175], off
	s_barrier
	s_waitcnt lgkmcnt(0)
	v_mfma_f32_16x16x32_bf16 v[118:121], v[236:239], v[204:207], v[118:121]
	v_mfma_f32_16x16x32_bf16 v[114:117], v[244:247], v[204:207], v[114:117]
	v_mfma_f32_16x16x32_bf16 v[102:105], v[236:239], v[212:215], v[102:105]
	v_mfma_f32_16x16x32_bf16 v[98:101], v[244:247], v[212:215], v[98:101]
	v_mfma_f32_16x16x32_bf16 v[86:89], v[236:239], v[220:223], v[86:89]
	v_mfma_f32_16x16x32_bf16 v[82:85], v[244:247], v[220:223], v[82:85]
	v_mfma_f32_16x16x32_bf16 v[70:73], v[236:239], v[228:231], v[70:73]
	v_mfma_f32_16x16x32_bf16 v[66:69], v[244:247], v[228:231], v[66:69]
	v_mfma_f32_16x16x32_bf16 v[118:121], v[240:243], v[208:211], v[118:121]
	v_mfma_f32_16x16x32_bf16 v[114:117], v[248:251], v[208:211], v[114:117]
	v_mfma_f32_16x16x32_bf16 v[102:105], v[240:243], v[216:219], v[102:105]
	v_mfma_f32_16x16x32_bf16 v[98:101], v[248:251], v[216:219], v[98:101]
	v_mfma_f32_16x16x32_bf16 v[86:89], v[240:243], v[224:227], v[86:89]
	v_mfma_f32_16x16x32_bf16 v[82:85], v[248:251], v[224:227], v[82:85]
	v_mfma_f32_16x16x32_bf16 v[70:73], v[240:243], v[232:235], v[70:73]
	v_mfma_f32_16x16x32_bf16 v[66:69], v[248:251], v[232:235], v[66:69]
	s_barrier
	s_mov_b32 m0, s40
	v_lshl_add_u64 v[182:183], s[24:25], 0, v[134:135]
	ds_read_b128 v[204:207], v172 offset:16384
	ds_read_b128 v[208:211], v172 offset:17408
	ds_read_b128 v[212:215], v172 offset:18432
	ds_read_b128 v[216:219], v172 offset:19456
	ds_read_b128 v[220:223], v172 offset:20480
	ds_read_b128 v[224:227], v172 offset:21504
	ds_read_b128 v[228:231], v172 offset:22528
	ds_read_b128 v[232:235], v172 offset:23552
	global_load_lds_dwordx4 v[182:183], off
	v_lshl_add_u64 v[184:185], s[24:25], 0, v[132:133]
	s_mov_b32 m0, s41
	s_nop 0
	global_load_lds_dwordx4 v[184:185], off
	s_barrier
	s_waitcnt lgkmcnt(0)
	v_mfma_f32_16x16x32_bf16 v[62:65], v[144:147], v[204:207], v[62:65]
	v_mfma_f32_16x16x32_bf16 v[58:61], v[152:155], v[204:207], v[58:61]
	v_mfma_f32_16x16x32_bf16 v[46:49], v[144:147], v[212:215], v[46:49]
	v_mfma_f32_16x16x32_bf16 v[42:45], v[152:155], v[212:215], v[42:45]
	v_mfma_f32_16x16x32_bf16 v[30:33], v[144:147], v[220:223], v[30:33]
	v_mfma_f32_16x16x32_bf16 v[26:29], v[152:155], v[220:223], v[26:29]
	v_mfma_f32_16x16x32_bf16 v[14:17], v[144:147], v[228:231], v[14:17]
	v_mfma_f32_16x16x32_bf16 v[10:13], v[152:155], v[228:231], v[10:13]
	v_mfma_f32_16x16x32_bf16 v[62:65], v[148:151], v[208:211], v[62:65]
	v_mfma_f32_16x16x32_bf16 v[58:61], v[200:203], v[208:211], v[58:61]
	v_mfma_f32_16x16x32_bf16 v[46:49], v[148:151], v[216:219], v[46:49]
	v_mfma_f32_16x16x32_bf16 v[42:45], v[200:203], v[216:219], v[42:45]
	v_mfma_f32_16x16x32_bf16 v[30:33], v[148:151], v[224:227], v[30:33]
	v_mfma_f32_16x16x32_bf16 v[26:29], v[200:203], v[224:227], v[26:29]
	v_mfma_f32_16x16x32_bf16 v[14:17], v[148:151], v[232:235], v[14:17]
	v_mfma_f32_16x16x32_bf16 v[10:13], v[200:203], v[232:235], v[10:13]
	s_barrier
; #define PG8_STAGE(bufoff, gbase, voff) do { _Pragma("unroll") for (int _i = 0; _i < 2; ++_i) \
;     __builtin_amdgcn_global_load_lds((const unsigned*)((const char*)(gbase) + (voff)[_i]), (PG8_LAS unsigned*)(lds + (bufoff) + ldsw + _i * 8192), 16, 0, 0); } while (0)
; #define PG8_LDA(dst, b, h) do { _Pragma("unroll") for (int m = 0; m < 4; ++m) _Pragma("unroll") for (int k = 0; k < 2; ++k) dst[m][k] = *(const PG8_LAS bf16x8*)(lds + PG8_SA(b, h) + aoff + m * 2048 + k * 1024); } while (0)
; #define PG8_LDB(dst, b, h) do { _Pragma("unroll") for (int n = 0; n < 2; ++n) _Pragma("unroll") for (int k = 0; k < 2; ++k) dst[n][k] = *(const PG8_LAS bf16x8*)(lds + PG8_SB(b, h) + boff + n * 2048 + k * 1024); } while (0)
; #define PG8_MMA(ai, bj, At, Bt) do { __builtin_amdgcn_s_setprio(1); _Pragma("unroll") for (int m = 0; m < 4; ++m) _Pragma("unroll") for (int n = 0; n < 2; ++n) _Pragma("unroll") for (int k = 0; k < 2; ++k) \
;     acc[ai][bj][m][n] = __builtin_amdgcn_mfma_f32_16x16x32_bf16(Bt[n][k], At[m][k], acc[ai][bj][m][n], 0, 0, 0); __builtin_amdgcn_s_setprio(0); } while (0)
; #define PG8_WAIT_V(n) asm volatile("s_waitcnt vmcnt(" #n ")" ::: "memory")
; #define PG8_WAIT_L(n) asm volatile("s_waitcnt lgkmcnt(" #n ")" ::: "memory")
; #define PG8_BAR __builtin_amdgcn_s_barrier()
; #define PG8_SCHED __builtin_amdgcn_sched_barrier(0)
; template <class Epi, class Sched>
; __device__ __forceinline__ void gemm_phase(PG8_LAS unsigned char* lds, const int lda, const int ldb, const Sched& S, const Epi& E) {
;     ...
;       PG8_STAGE(PG8_SB(0, 1), b2 + hstepB, voffB);
;       PG8_WAIT_V(6); PG8_BAR; PG8_MMA(1, 1, At, B1); PG8_BAR;
;       PG8_LDB(B0, 1, 0); PG8_SCHED; PG8_LDA(At, 1, 0); PG8_STAGE(PG8_SA(0, 1), a2 + hstepA, voffA);
;       PG8_WAIT_L(8); PG8_BAR; PG8_WAIT_L(0); PG8_MMA(0, 0, At, B0); PG8_BAR; PG8_SCHED;
;       PG8_LDB(B1, 1, 1); PG8_STAGE(PG8_SB(1, 0), b3, voffB);
;       PG8_BAR; PG8_WAIT_L(0); PG8_MMA(0, 1, At, B1); PG8_BAR;
;       PG8_LDA(At, 1, 1); PG8_STAGE(PG8_SA(1, 0), a3, voffA);
;       PG8_BAR; PG8_WAIT_L(0); PG8_MMA(1, 0, At, B0); PG8_BAR; PG8_SCHED;
;       PG8_STAGE(PG8_SB(1, 1), b3 + hstepB, voffB);
	s_add_u32 s34, s10, 0x40000
	s_addc_u32 s35, s11, 0
	s_add_i32 s31, s33, s39
	v_lshl_add_u64 v[144:145], s[34:35], 0, v[134:135]
	s_mov_b32 m0, s31
	s_nop 0
	global_load_lds_dwordx4 v[144:145], off
	v_lshl_add_u64 v[144:145], s[34:35], 0, v[132:133]
	s_add_i32 m0, s31, 0x2000
	s_nop 0
	global_load_lds_dwordx4 v[144:145], off
	s_waitcnt vmcnt(6)
	s_barrier
	v_mfma_f32_16x16x32_bf16 v[54:57], v[236:239], v[204:207], v[54:57]
	v_mfma_f32_16x16x32_bf16 v[50:53], v[244:247], v[204:207], v[50:53]
	v_mfma_f32_16x16x32_bf16 v[38:41], v[236:239], v[212:215], v[38:41]
	v_mfma_f32_16x16x32_bf16 v[34:37], v[244:247], v[212:215], v[34:37]
	v_mfma_f32_16x16x32_bf16 v[22:25], v[236:239], v[220:223], v[22:25]
	v_mfma_f32_16x16x32_bf16 v[18:21], v[244:247], v[220:223], v[18:21]
	v_mfma_f32_16x16x32_bf16 v[6:9], v[236:239], v[228:231], v[6:9]
	v_mfma_f32_16x16x32_bf16 v[2:5], v[244:247], v[228:231], v[2:5]
	v_mfma_f32_16x16x32_bf16 v[54:57], v[240:243], v[208:211], v[54:57]
	v_mfma_f32_16x16x32_bf16 v[50:53], v[248:251], v[208:211], v[50:53]
	v_mfma_f32_16x16x32_bf16 v[38:41], v[240:243], v[216:219], v[38:41]
	v_mfma_f32_16x16x32_bf16 v[34:37], v[248:251], v[216:219], v[34:37]
	v_mfma_f32_16x16x32_bf16 v[22:25], v[240:243], v[224:227], v[22:25]
	v_mfma_f32_16x16x32_bf16 v[18:21], v[248:251], v[224:227], v[18:21]
	v_mfma_f32_16x16x32_bf16 v[6:9], v[240:243], v[232:235], v[6:9]
	v_mfma_f32_16x16x32_bf16 v[2:5], v[248:251], v[232:235], v[2:5]
	s_barrier
	s_add_i32 s31, 0, 0x18000
	v_add_u32_e32 v173, s31, v131
	ds_read_b128 v[144:147], v173
	ds_read_b128 v[148:151], v173 offset:1024
	ds_read_b128 v[152:155], v173 offset:2048
	ds_read_b128 v[200:203], v173 offset:3072
	s_add_u32 s24, s24, 0x40000
	s_addc_u32 s25, s25, 0
	s_mov_b32 m0, s42
	v_lshl_add_u64 v[236:237], s[24:25], 0, v[134:135]
	ds_read_b128 v[204:207], v172 offset:32768
	ds_read_b128 v[208:211], v172 offset:33792
	ds_read_b128 v[212:215], v172 offset:34816
	ds_read_b128 v[216:219], v172 offset:35840
	ds_read_b128 v[220:223], v172 offset:36864
	ds_read_b128 v[224:227], v172 offset:37888
	ds_read_b128 v[228:231], v172 offset:38912
	ds_read_b128 v[232:235], v172 offset:39936
	global_load_lds_dwordx4 v[236:237], off
	v_lshl_add_u64 v[236:237], s[24:25], 0, v[132:133]
	s_mov_b32 m0, s43
	s_nop 0
	global_load_lds_dwordx4 v[236:237], off
	s_waitcnt lgkmcnt(8)
	s_barrier
	s_waitcnt lgkmcnt(0)
	v_mfma_f32_16x16x32_bf16 v[126:129], v[144:147], v[204:207], v[126:129]
	v_mfma_f32_16x16x32_bf16 v[122:125], v[152:155], v[204:207], v[122:125]
	v_mfma_f32_16x16x32_bf16 v[110:113], v[144:147], v[212:215], v[110:113]
	v_mfma_f32_16x16x32_bf16 v[106:109], v[152:155], v[212:215], v[106:109]
	v_mfma_f32_16x16x32_bf16 v[94:97], v[144:147], v[220:223], v[94:97]
	v_mfma_f32_16x16x32_bf16 v[90:93], v[152:155], v[220:223], v[90:93]
	v_mfma_f32_16x16x32_bf16 v[78:81], v[144:147], v[228:231], v[78:81]
	v_mfma_f32_16x16x32_bf16 v[74:77], v[152:155], v[228:231], v[74:77]
	v_mfma_f32_16x16x32_bf16 v[126:129], v[148:151], v[208:211], v[126:129]
	v_mfma_f32_16x16x32_bf16 v[122:125], v[200:203], v[208:211], v[122:125]
	v_mfma_f32_16x16x32_bf16 v[110:113], v[148:151], v[216:219], v[110:113]
	v_mfma_f32_16x16x32_bf16 v[106:109], v[200:203], v[216:219], v[106:109]
	v_mfma_f32_16x16x32_bf16 v[94:97], v[148:151], v[224:227], v[94:97]
	v_mfma_f32_16x16x32_bf16 v[90:93], v[200:203], v[224:227], v[90:93]
	v_mfma_f32_16x16x32_bf16 v[78:81], v[148:151], v[232:235], v[78:81]
	v_mfma_f32_16x16x32_bf16 v[74:77], v[200:203], v[232:235], v[74:77]
	s_barrier
	s_add_i32 s24, 0, 0x1c000
	s_add_i32 s25, s31, s39
	v_add_u32_e32 v173, s24, v131
	v_lshl_add_u64 v[156:157], v[156:157], 0, s[86:87]
	s_mov_b32 m0, s25
	ds_read_b128 v[236:239], v173
	ds_read_b128 v[240:243], v173 offset:1024
	ds_read_b128 v[244:247], v173 offset:2048
	ds_read_b128 v[248:251], v173 offset:3072
	global_load_lds_dwordx4 v[156:157], off
	v_lshl_add_u64 v[156:157], v[174:175], 0, s[86:87]
	s_add_i32 m0, s25, 0x2000
	s_nop 0
	global_load_lds_dwordx4 v[156:157], off
	s_barrier
	s_waitcnt lgkmcnt(0)
	v_mfma_f32_16x16x32_bf16 v[118:121], v[236:239], v[204:207], v[118:121]
	v_mfma_f32_16x16x32_bf16 v[114:117], v[244:247], v[204:207], v[114:117]
	v_mfma_f32_16x16x32_bf16 v[102:105], v[236:239], v[212:215], v[102:105]
	v_mfma_f32_16x16x32_bf16 v[98:101], v[244:247], v[212:215], v[98:101]
	v_mfma_f32_16x16x32_bf16 v[86:89], v[236:239], v[220:223], v[86:89]
	v_mfma_f32_16x16x32_bf16 v[82:85], v[244:247], v[220:223], v[82:85]
	v_mfma_f32_16x16x32_bf16 v[70:73], v[236:239], v[228:231], v[70:73]
	v_mfma_f32_16x16x32_bf16 v[66:69], v[244:247], v[228:231], v[66:69]
	v_mfma_f32_16x16x32_bf16 v[118:121], v[240:243], v[208:211], v[118:121]
	v_mfma_f32_16x16x32_bf16 v[114:117], v[248:251], v[208:211], v[114:117]
	v_mfma_f32_16x16x32_bf16 v[102:105], v[240:243], v[216:219], v[102:105]
	v_mfma_f32_16x16x32_bf16 v[98:101], v[248:251], v[216:219], v[98:101]
	v_mfma_f32_16x16x32_bf16 v[86:89], v[240:243], v[224:227], v[86:89]
	v_mfma_f32_16x16x32_bf16 v[82:85], v[248:251], v[224:227], v[82:85]
	v_mfma_f32_16x16x32_bf16 v[70:73], v[240:243], v[232:235], v[70:73]
	v_mfma_f32_16x16x32_bf16 v[66:69], v[248:251], v[232:235], v[66:69]
	s_barrier
	s_mov_b32 m0, s45
	v_lshl_add_u64 v[156:157], v[182:183], 0, s[86:87]
	ds_read_b128 v[204:207], v172 offset:49152
	ds_read_b128 v[208:211], v172 offset:50176
	ds_read_b128 v[212:215], v172 offset:51200
	ds_read_b128 v[216:219], v172 offset:52224
	ds_read_b128 v[220:223], v172 offset:53248
	ds_read_b128 v[224:227], v172 offset:54272
	ds_read_b128 v[228:231], v172 offset:55296
	ds_read_b128 v[232:235], v172 offset:56320
	global_load_lds_dwordx4 v[156:157], off
	v_lshl_add_u64 v[156:157], v[184:185], 0, s[86:87]
	s_mov_b32 m0, s46
	s_nop 0
	global_load_lds_dwordx4 v[156:157], off
	s_barrier
; #define PG8_WAIT_V(n) asm volatile("s_waitcnt vmcnt(" #n ")" ::: "memory")
; #define PG8_BAR __builtin_amdgcn_s_barrier()
; template <class Epi, class Sched>
; __device__ __forceinline__ void gemm_phase(PG8_LAS unsigned char* lds, const int lda, const int ldb, const Sched& S, const Epi& E) {
;     ...
;       PG8_WAIT_V(6); PG8_BAR; PG8_MMA(1, 1, At, B1); PG8_BAR;
;     }
;   __device__ __forceinline__ void operator()(const f32x4 (&acc)[2][2][4][2], const Unit& u, int wr, int wc, int fr, int fq) const {
; #pragma unroll
;     for (int ai = 0; ai < 2; ++ai)
; #pragma unroll
;       for (int m = 0; m < 4; ++m) {
;         const int r = u.pm * 256 + ai * 128 + wr * 64 + m * 16 + fr;
; #pragma unroll
;         for (int bj = 0; bj < 2; ++bj)
; #pragma unroll
;           for (int n = 0; n < 2; ++n) {
;             const f32x4 v = acc[ai][bj][m][n];
;             const int c = u.pn * 256 + bj * 128 + wc * 32 + n * 16 + 4 * fq;
;             if (u.pn < 7) {
;               uint2 w; w.x = pack2(v[0], v[1]); w.y = pack2(v[2], v[3]);
;               *reinterpret_cast<uint2*>(PB + (size_t)r * PBW + c) = w;
;             } else {
;               const int nn = c - 1792, part = nn >> 8, ch = nn & 255;
;               if (u.pn == 7 && bj == 0 && wc == 1 && n == 1) {
;                 *reinterpret_cast<float4*>(AB + (size_t)r * 16 + 4 * fq) = make_float4(v[0], v[1], v[2], v[3]);
;               } else {
;                 u16* d; int cstride;
;                 if (r < ML) { const int b = r >> 11, tt = r & 2047; d = FT + ((size_t)(b * 256)) * 4096 + part * 2048 + tt; cstride = 4096; }
;                 else { const int rc = r - ML, b = rc >> 8, tt = rc & 255; d = FTC + ((size_t)(b * 256)) * 512 + part * 256 + tt; cstride = 512; }
; #pragma unroll
;                 for (int e = 0; e < 4; ++e) d[(size_t)(ch + e) * cstride] = f2bf(v[e]);
;                 if (u.pn == 7 && bj == 0 && wc == 0) {
; #pragma unroll
;                   for (int e = 0; e < 4; ++e) {
;                     const int kc = n * 16 + 4 * fq + e;
;                     if (kc >= 1 && kc <= 16) d[(size_t)(64 - kc) * cstride] = f2bf(v[e]);
;                   }
;                 }
	s_waitcnt lgkmcnt(0)
	v_mfma_f32_16x16x32_bf16 v[62:65], v[144:147], v[204:207], v[62:65]
	v_mfma_f32_16x16x32_bf16 v[58:61], v[152:155], v[204:207], v[58:61]
	v_mfma_f32_16x16x32_bf16 v[46:49], v[144:147], v[212:215], v[46:49]
	v_mfma_f32_16x16x32_bf16 v[42:45], v[152:155], v[212:215], v[42:45]
	v_mfma_f32_16x16x32_bf16 v[30:33], v[144:147], v[220:223], v[30:33]
	v_mfma_f32_16x16x32_bf16 v[26:29], v[152:155], v[220:223], v[26:29]
	v_mfma_f32_16x16x32_bf16 v[14:17], v[144:147], v[228:231], v[14:17]
	v_mfma_f32_16x16x32_bf16 v[10:13], v[152:155], v[228:231], v[10:13]
	v_mfma_f32_16x16x32_bf16 v[62:65], v[148:151], v[208:211], v[62:65]
	v_mfma_f32_16x16x32_bf16 v[58:61], v[200:203], v[208:211], v[58:61]
	v_mfma_f32_16x16x32_bf16 v[46:49], v[148:151], v[216:219], v[46:49]
	v_mfma_f32_16x16x32_bf16 v[42:45], v[200:203], v[216:219], v[42:45]
	v_mfma_f32_16x16x32_bf16 v[30:33], v[148:151], v[224:227], v[30:33]
	v_mfma_f32_16x16x32_bf16 v[26:29], v[200:203], v[224:227], v[26:29]
	v_mfma_f32_16x16x32_bf16 v[14:17], v[148:151], v[232:235], v[14:17]
	v_mfma_f32_16x16x32_bf16 v[10:13], v[200:203], v[232:235], v[10:13]
	s_barrier
	s_add_u32 s10, s10, 0x40080
	s_addc_u32 s11, s11, 0
	s_add_i32 s24, s24, s39
	v_lshl_add_u64 v[144:145], s[10:11], 0, v[134:135]
	s_mov_b32 m0, s24
	s_nop 0
	global_load_lds_dwordx4 v[144:145], off
	v_lshl_add_u64 v[144:145], s[10:11], 0, v[132:133]
	s_add_i32 m0, s24, 0x2000
	s_nop 0
	global_load_lds_dwordx4 v[144:145], off
	s_waitcnt vmcnt(6)
	s_barrier
	v_mfma_f32_16x16x32_bf16 v[54:57], v[236:239], v[204:207], v[54:57]
	v_mfma_f32_16x16x32_bf16 v[50:53], v[244:247], v[204:207], v[50:53]
	v_mfma_f32_16x16x32_bf16 v[38:41], v[236:239], v[212:215], v[38:41]
	v_mfma_f32_16x16x32_bf16 v[34:37], v[244:247], v[212:215], v[34:37]
	v_mfma_f32_16x16x32_bf16 v[22:25], v[236:239], v[220:223], v[22:25]
	v_mfma_f32_16x16x32_bf16 v[18:21], v[244:247], v[220:223], v[18:21]
	v_mfma_f32_16x16x32_bf16 v[6:9], v[236:239], v[228:231], v[6:9]
	v_mfma_f32_16x16x32_bf16 v[2:5], v[244:247], v[228:231], v[2:5]
	v_mfma_f32_16x16x32_bf16 v[54:57], v[240:243], v[208:211], v[54:57]
	v_mfma_f32_16x16x32_bf16 v[50:53], v[248:251], v[208:211], v[50:53]
	v_mfma_f32_16x16x32_bf16 v[38:41], v[240:243], v[216:219], v[38:41]
	v_mfma_f32_16x16x32_bf16 v[34:37], v[248:251], v[216:219], v[34:37]
	v_mfma_f32_16x16x32_bf16 v[22:25], v[240:243], v[224:227], v[22:25]
	v_mfma_f32_16x16x32_bf16 v[18:21], v[248:251], v[224:227], v[18:21]
	v_mfma_f32_16x16x32_bf16 v[6:9], v[240:243], v[232:235], v[6:9]
	v_mfma_f32_16x16x32_bf16 v[2:5], v[248:251], v[232:235], v[2:5]
	s_add_i32 s30, s30, 2
	s_add_u32 s8, s8, 0x100
	s_addc_u32 s9, s9, 0
	s_add_u32 s28, s28, 0x100
	s_addc_u32 s29, s29, 0
	s_cmp_gt_u32 s30, 13
	s_barrier
	s_cbranch_scc0 .LBB0_335
	s_lshl_b32 s15, s2, 8
	s_add_i32 s15, s15, s44
	v_or_b32_e32 v152, s15, v1
	s_mov_b32 s2, 0xffff
	v_cmp_lt_i32_e64 s[10:11], s2, v152
	s_and_b32 s2, s15, 0xffffff00
	s_add_i32 s2, s2, 0xffff0000
	s_lshl_b64 s[28:29], s[2:3], 10
	s_ashr_i32 s2, s15, 3
	s_and_b32 s8, s2, 0xffffff00
	s_ashr_i32 s9, s8, 31
	s_lshl_b64 s[26:27], s[8:9], 13
	s_lshl_b32 s24, s48, 8
	s_cmp_gt_i32 s48, 6
	s_cselect_b64 s[30:31], -1, 0
	v_bitop3_b32 v146, s15, v186, v1 bitop3:0xc8
	v_bitop3_b32 v148, s15, v187, v1 bitop3:0xc8
	s_mov_b64 s[8:9], -1
	s_and_b64 vcc, exec, s[30:31]
	s_cbranch_vccz .LBB0_346
	s_and_saveexec_b64 s[8:9], s[10:11]
	s_xor_b64 s[8:9], exec, s[8:9]
	s_add_u32 s34, s54, s28
	s_addc_u32 s35, s55, s29
	s_or_saveexec_b64 s[8:9], s[8:9]
	s_add_i32 s2, s24, 0xfffff900
	v_mov_b64_e32 v[144:145], 0x200
	v_mov_b32_e32 v150, s2
	v_mov_b64_e32 v[154:155], s[34:35]
	v_mov_b64_e32 v[156:157], v[146:147]
	s_xor_b64 exec, exec, s[8:9]
	s_add_u32 s34, s69, s26
	s_addc_u32 s35, s52, s27
	s_lshl_b32 s2, s2, 3
	v_mov_b64_e32 v[144:145], 0x1000
	v_mov_b32_e32 v150, s2
	v_mov_b64_e32 v[154:155], s[34:35]
	v_mov_b64_e32 v[156:157], v[148:149]
	s_or_b64 exec, exec, s[8:9]
	v_ashrrev_i32_e32 v151, 31, v150
	v_lshl_add_u64 v[150:151], v[150:151], 1, v[154:155]
	v_lshlrev_b32_e32 v154, 1, v156
	v_mov_b32_e32 v155, v0
	v_mul_u32_u24_e32 v145, v144, v136
	v_lshl_add_u64 v[150:151], v[150:151], 0, v[154:155]
	v_lshlrev_b32_e32 v154, 1, v145
	v_cvt_pk_bf16_f32 v149, v126, s0
	v_lshl_add_u64 v[154:155], v[150:151], 0, v[154:155]
	v_mul_u32_u24_e32 v147, v144, v166
	global_store_short v[154:155], v149, off
	v_lshlrev_b32_e32 v154, 1, v147
	v_mov_b32_e32 v155, v0
	v_cvt_pk_bf16_f32 v145, v127, s0
	v_lshl_add_u64 v[154:155], v[150:151], 0, v[154:155]
	v_mul_u32_u24_e32 v153, v144, v167
	global_store_short v[154:155], v145, off
	v_lshlrev_b32_e32 v154, 1, v153
	v_mov_b32_e32 v155, v0
	s_cmp_lg_u32 s48, 7
	v_cvt_pk_bf16_f32 v147, v128, s0
	v_lshl_add_u64 v[154:155], v[150:151], 0, v[154:155]
	s_cselect_b64 s[8:9], -1, 0
	global_store_short v[154:155], v147, off
	v_mul_u32_u24_e32 v154, v144, v168
	s_xor_b64 s[34:35], s[12:13], -1
	v_lshlrev_b32_e32 v154, 1, v154
	v_mov_b32_e32 v155, v0
	s_or_b64 s[8:9], s[34:35], s[8:9]
	v_cvt_pk_bf16_f32 v153, v129, s0
	v_lshl_add_u64 v[154:155], v[150:151], 0, v[154:155]
	s_and_b64 vcc, exec, s[8:9]
	global_store_short v[154:155], v153, off
	s_cbranch_vccnz .LBB0_345
	s_and_saveexec_b64 s[8:9], s[4:5]
	s_cbranch_execz .LBB0_344
	v_mul_u32_u24_e32 v154, v144, v158
	v_lshlrev_b32_e32 v154, 1, v154
	v_mov_b32_e32 v155, v0
	v_lshl_add_u64 v[154:155], v[150:151], 0, v[154:155]
	global_store_short v[154:155], v149, off

; #define PG8_STAGE(bufoff, gbase, voff) do { _Pragma("unroll") for (int _i = 0; _i < 2; ++_i) \
;     __builtin_amdgcn_global_load_lds((const unsigned*)((const char*)(gbase) + (voff)[_i]), (PG8_LAS unsigned*)(lds + (bufoff) + ldsw + _i * 8192), 16, 0, 0); } while (0)
; #define PG8_LDA(dst, b, h) do { _Pragma("unroll") for (int m = 0; m < 4; ++m) _Pragma("unroll") for (int k = 0; k < 2; ++k) dst[m][k] = *(const PG8_LAS bf16x8*)(lds + PG8_SA(b, h) + aoff + m * 2048 + k * 1024); } while (0)
; #define PG8_LDB(dst, b, h) do { _Pragma("unroll") for (int n = 0; n < 2; ++n) _Pragma("unroll") for (int k = 0; k < 2; ++k) dst[n][k] = *(const PG8_LAS bf16x8*)(lds + PG8_SB(b, h) + boff + n * 2048 + k * 1024); } while (0)
; #define PG8_MMA(ai, bj, At, Bt) do { __builtin_amdgcn_s_setprio(1); _Pragma("unroll") for (int m = 0; m < 4; ++m) _Pragma("unroll") for (int n = 0; n < 2; ++n) _Pragma("unroll") for (int k = 0; k < 2; ++k) \
;     acc[ai][bj][m][n] = __builtin_amdgcn_mfma_f32_16x16x32_bf16(Bt[n][k], At[m][k], acc[ai][bj][m][n], 0, 0, 0); __builtin_amdgcn_s_setprio(0); } while (0)
; #define PG8_WAIT_L(n) asm volatile("s_waitcnt lgkmcnt(" #n ")" ::: "memory")
; #define PG8_BAR __builtin_amdgcn_s_barrier()
; #define PG8_SCHED __builtin_amdgcn_sched_barrier(0)
; template <class Epi, class Sched>
; __device__ __forceinline__ void gemm_phase(PG8_LAS unsigned char* lds, const int lda, const int ldb, const Sched& S, const Epi& E) {
;     ...
;     for (int t = 0; t < nt; t += 2) {
;       const bool last = (t == nt - 2);
;       const char* a1 = cA + (size_t)(t + 1) * kstep;
;       const char* a2 = last ? nA : cA + (size_t)(t + 2) * kstep; const char* b2 = last ? nB : cB + (size_t)(t + 2) * kstep;
;       const char* a3 = a2 + kstep; const char* b3 = b2 + kstep;
;       PG8_LDB(B0, 0, 0); PG8_SCHED; PG8_LDA(At, 0, 0); PG8_STAGE(PG8_SA(1, 1), a1 + hstepA, voffA);
;       PG8_WAIT_L(8); PG8_BAR; PG8_WAIT_L(0); PG8_MMA(0, 0, At, B0); PG8_BAR; PG8_SCHED;
;       PG8_LDB(B1, 0, 1); PG8_STAGE(PG8_SB(0, 0), b2, voffB);
;       PG8_BAR; PG8_WAIT_L(0); PG8_MMA(0, 1, At, B1); PG8_BAR;
;       PG8_LDA(At, 0, 1); PG8_STAGE(PG8_SA(0, 0), a2, voffA);
;       PG8_BAR; PG8_WAIT_L(0); PG8_MMA(1, 0, At, B0); PG8_BAR; PG8_SCHED;
.LBB0_685:
	s_add_u32 s12, s10, 0xfffc0080
	s_addc_u32 s13, s11, -1
	s_add_i32 s31, 0, 0x10000
	v_add_u32_e32 v156, s31, v131
	ds_read_b128 v[144:147], v156
	ds_read_b128 v[148:151], v156 offset:1024
	ds_read_b128 v[152:155], v156 offset:2048
	ds_read_b128 v[200:203], v156 offset:3072
	s_cmp_eq_u32 s30, 12
	s_cselect_b32 s25, s19, s13
	s_cselect_b32 s24, s26, s12
	s_cselect_b32 s13, s17, s29
	s_cselect_b32 s12, s27, s28
	v_lshl_add_u64 v[156:157], s[10:11], 0, v[140:141]
	s_add_i32 m0, s40, 0xc000
	ds_read_b128 v[204:207], v172
	ds_read_b128 v[208:211], v172 offset:1024
	ds_read_b128 v[212:215], v172 offset:2048
	ds_read_b128 v[216:219], v172 offset:3072
	ds_read_b128 v[220:223], v172 offset:4096
	ds_read_b128 v[224:227], v172 offset:5120
	ds_read_b128 v[228:231], v172 offset:6144
	ds_read_b128 v[232:235], v172 offset:7168
	global_load_lds_dwordx4 v[156:157], off
	v_lshl_add_u64 v[156:157], s[10:11], 0, v[142:143]
	s_add_i32 m0, s40, 0xe000
	s_nop 0
	global_load_lds_dwordx4 v[156:157], off
	s_waitcnt lgkmcnt(8)
	s_barrier
	s_waitcnt lgkmcnt(0)
	v_mfma_f32_16x16x32_bf16 v[126:129], v[144:147], v[204:207], v[126:129]
	v_mfma_f32_16x16x32_bf16 v[122:125], v[152:155], v[204:207], v[122:125]
	v_mfma_f32_16x16x32_bf16 v[110:113], v[144:147], v[212:215], v[110:113]
	v_mfma_f32_16x16x32_bf16 v[106:109], v[152:155], v[212:215], v[106:109]
	v_mfma_f32_16x16x32_bf16 v[94:97], v[144:147], v[220:223], v[94:97]
	v_mfma_f32_16x16x32_bf16 v[90:93], v[152:155], v[220:223], v[90:93]
	v_mfma_f32_16x16x32_bf16 v[78:81], v[144:147], v[228:231], v[78:81]
	v_mfma_f32_16x16x32_bf16 v[74:77], v[152:155], v[228:231], v[74:77]
	v_mfma_f32_16x16x32_bf16 v[126:129], v[148:151], v[208:211], v[126:129]
	v_mfma_f32_16x16x32_bf16 v[122:125], v[200:203], v[208:211], v[122:125]
	v_mfma_f32_16x16x32_bf16 v[110:113], v[148:151], v[216:219], v[110:113]
	v_mfma_f32_16x16x32_bf16 v[106:109], v[200:203], v[216:219], v[106:109]
	v_mfma_f32_16x16x32_bf16 v[94:97], v[148:151], v[224:227], v[94:97]
	v_mfma_f32_16x16x32_bf16 v[90:93], v[200:203], v[224:227], v[90:93]
	v_mfma_f32_16x16x32_bf16 v[78:81], v[148:151], v[232:235], v[78:81]
	v_mfma_f32_16x16x32_bf16 v[74:77], v[200:203], v[232:235], v[74:77]
	s_barrier
	s_add_i32 s33, 0, 0x14000
	v_add_u32_e32 v156, s33, v131
	s_add_i32 s31, s31, s39
	ds_read_b128 v[236:239], v156
	ds_read_b128 v[240:243], v156 offset:1024
	ds_read_b128 v[244:247], v156 offset:2048
	ds_read_b128 v[248:251], v156 offset:3072
	v_lshl_add_u64 v[156:157], s[12:13], 0, v[134:135]
	s_mov_b32 m0, s31
	v_lshl_add_u64 v[174:175], s[12:13], 0, v[132:133]
	global_load_lds_dwordx4 v[156:157], off
	s_add_i32 m0, s31, 0x2000
	s_nop 0
	global_load_lds_dwordx4 v[174:175], off
	s_barrier
	s_waitcnt lgkmcnt(0)
	v_mfma_f32_16x16x32_bf16 v[118:121], v[236:239], v[204:207], v[118:121]
	v_mfma_f32_16x16x32_bf16 v[114:117], v[244:247], v[204:207], v[114:117]
	v_mfma_f32_16x16x32_bf16 v[102:105], v[236:239], v[212:215], v[102:105]
	v_mfma_f32_16x16x32_bf16 v[98:101], v[244:247], v[212:215], v[98:101]
	v_mfma_f32_16x16x32_bf16 v[86:89], v[236:239], v[220:223], v[86:89]
	v_mfma_f32_16x16x32_bf16 v[82:85], v[244:247], v[220:223], v[82:85]
	v_mfma_f32_16x16x32_bf16 v[70:73], v[236:239], v[228:231], v[70:73]
	v_mfma_f32_16x16x32_bf16 v[66:69], v[244:247], v[228:231], v[66:69]
	v_mfma_f32_16x16x32_bf16 v[118:121], v[240:243], v[208:211], v[118:121]
	v_mfma_f32_16x16x32_bf16 v[114:117], v[248:251], v[208:211], v[114:117]
	v_mfma_f32_16x16x32_bf16 v[102:105], v[240:243], v[216:219], v[102:105]
	v_mfma_f32_16x16x32_bf16 v[98:101], v[248:251], v[216:219], v[98:101]
	v_mfma_f32_16x16x32_bf16 v[86:89], v[240:243], v[224:227], v[86:89]
	v_mfma_f32_16x16x32_bf16 v[82:85], v[248:251], v[224:227], v[82:85]
	v_mfma_f32_16x16x32_bf16 v[70:73], v[240:243], v[232:235], v[70:73]
	v_mfma_f32_16x16x32_bf16 v[66:69], v[248:251], v[232:235], v[66:69]
	s_barrier
	s_mov_b32 m0, s40
	v_lshl_add_u64 v[182:183], s[24:25], 0, v[134:135]
	ds_read_b128 v[204:207], v172 offset:16384
	ds_read_b128 v[208:211], v172 offset:17408
	ds_read_b128 v[212:215], v172 offset:18432
	ds_read_b128 v[216:219], v172 offset:19456
	ds_read_b128 v[220:223], v172 offset:20480
	ds_read_b128 v[224:227], v172 offset:21504
	ds_read_b128 v[228:231], v172 offset:22528
	ds_read_b128 v[232:235], v172 offset:23552
	global_load_lds_dwordx4 v[182:183], off
	v_lshl_add_u64 v[184:185], s[24:25], 0, v[132:133]
	s_mov_b32 m0, s41
	s_nop 0
	global_load_lds_dwordx4 v[184:185], off
	s_barrier
	s_waitcnt lgkmcnt(0)
	v_mfma_f32_16x16x32_bf16 v[62:65], v[144:147], v[204:207], v[62:65]
	v_mfma_f32_16x16x32_bf16 v[58:61], v[152:155], v[204:207], v[58:61]
	v_mfma_f32_16x16x32_bf16 v[46:49], v[144:147], v[212:215], v[46:49]
	v_mfma_f32_16x16x32_bf16 v[42:45], v[152:155], v[212:215], v[42:45]
	v_mfma_f32_16x16x32_bf16 v[30:33], v[144:147], v[220:223], v[30:33]
	v_mfma_f32_16x16x32_bf16 v[26:29], v[152:155], v[220:223], v[26:29]
	v_mfma_f32_16x16x32_bf16 v[14:17], v[144:147], v[228:231], v[14:17]
	v_mfma_f32_16x16x32_bf16 v[10:13], v[152:155], v[228:231], v[10:13]
	v_mfma_f32_16x16x32_bf16 v[62:65], v[148:151], v[208:211], v[62:65]
	v_mfma_f32_16x16x32_bf16 v[58:61], v[200:203], v[208:211], v[58:61]
	v_mfma_f32_16x16x32_bf16 v[46:49], v[148:151], v[216:219], v[46:49]
	v_mfma_f32_16x16x32_bf16 v[42:45], v[200:203], v[216:219], v[42:45]
	v_mfma_f32_16x16x32_bf16 v[30:33], v[148:151], v[224:227], v[30:33]
	v_mfma_f32_16x16x32_bf16 v[26:29], v[200:203], v[224:227], v[26:29]
	v_mfma_f32_16x16x32_bf16 v[14:17], v[148:151], v[232:235], v[14:17]
	v_mfma_f32_16x16x32_bf16 v[10:13], v[200:203], v[232:235], v[10:13]
	s_barrier
; #define PG8_STAGE(bufoff, gbase, voff) do { _Pragma("unroll") for (int _i = 0; _i < 2; ++_i) \
;     __builtin_amdgcn_global_load_lds((const unsigned*)((const char*)(gbase) + (voff)[_i]), (PG8_LAS unsigned*)(lds + (bufoff) + ldsw + _i * 8192), 16, 0, 0); } while (0)
; #define PG8_LDA(dst, b, h) do { _Pragma("unroll") for (int m = 0; m < 4; ++m) _Pragma("unroll") for (int k = 0; k < 2; ++k) dst[m][k] = *(const PG8_LAS bf16x8*)(lds + PG8_SA(b, h) + aoff + m * 2048 + k * 1024); } while (0)
; #define PG8_LDB(dst, b, h) do { _Pragma("unroll") for (int n = 0; n < 2; ++n) _Pragma("unroll") for (int k = 0; k < 2; ++k) dst[n][k] = *(const PG8_LAS bf16x8*)(lds + PG8_SB(b, h) + boff + n * 2048 + k * 1024); } while (0)
; #define PG8_MMA(ai, bj, At, Bt) do { __builtin_amdgcn_s_setprio(1); _Pragma("unroll") for (int m = 0; m < 4; ++m) _Pragma("unroll") for (int n = 0; n < 2; ++n) _Pragma("unroll") for (int k = 0; k < 2; ++k) \
;     acc[ai][bj][m][n] = __builtin_amdgcn_mfma_f32_16x16x32_bf16(Bt[n][k], At[m][k], acc[ai][bj][m][n], 0, 0, 0); __builtin_amdgcn_s_setprio(0); } while (0)
; #define PG8_WAIT_V(n) asm volatile("s_waitcnt vmcnt(" #n ")" ::: "memory")
; #define PG8_WAIT_L(n) asm volatile("s_waitcnt lgkmcnt(" #n ")" ::: "memory")
; #define PG8_BAR __builtin_amdgcn_s_barrier()
; #define PG8_SCHED __builtin_amdgcn_sched_barrier(0)
; template <class Epi, class Sched>
; __device__ __forceinline__ void gemm_phase(PG8_LAS unsigned char* lds, const int lda, const int ldb, const Sched& S, const Epi& E) {
;     ...
;       PG8_STAGE(PG8_SB(0, 1), b2 + hstepB, voffB);
;       PG8_WAIT_V(6); PG8_BAR; PG8_MMA(1, 1, At, B1); PG8_BAR;
;       PG8_LDB(B0, 1, 0); PG8_SCHED; PG8_LDA(At, 1, 0); PG8_STAGE(PG8_SA(0, 1), a2 + hstepA, voffA);
;       PG8_WAIT_L(8); PG8_BAR; PG8_WAIT_L(0); PG8_MMA(0, 0, At, B0); PG8_BAR; PG8_SCHED;
;       PG8_LDB(B1, 1, 1); PG8_STAGE(PG8_SB(1, 0), b3, voffB);
;       PG8_BAR; PG8_WAIT_L(0); PG8_MMA(0, 1, At, B1); PG8_BAR;
;       PG8_LDA(At, 1, 1); PG8_STAGE(PG8_SA(1, 0), a3, voffA);
;       PG8_BAR; PG8_WAIT_L(0); PG8_MMA(1, 0, At, B0); PG8_BAR; PG8_SCHED;
;       PG8_STAGE(PG8_SB(1, 1), b3 + hstepB, voffB);
	s_add_u32 s34, s12, 0x40000
	s_addc_u32 s35, s13, 0
	s_add_i32 s31, s33, s39
	v_lshl_add_u64 v[144:145], s[34:35], 0, v[134:135]
	s_mov_b32 m0, s31
	s_nop 0
	global_load_lds_dwordx4 v[144:145], off
	v_lshl_add_u64 v[144:145], s[34:35], 0, v[132:133]
	s_add_i32 m0, s31, 0x2000
	s_nop 0
	global_load_lds_dwordx4 v[144:145], off
	s_waitcnt vmcnt(6)
	s_barrier
	v_mfma_f32_16x16x32_bf16 v[54:57], v[236:239], v[204:207], v[54:57]
	v_mfma_f32_16x16x32_bf16 v[50:53], v[244:247], v[204:207], v[50:53]
	v_mfma_f32_16x16x32_bf16 v[38:41], v[236:239], v[212:215], v[38:41]
	v_mfma_f32_16x16x32_bf16 v[34:37], v[244:247], v[212:215], v[34:37]
	v_mfma_f32_16x16x32_bf16 v[22:25], v[236:239], v[220:223], v[22:25]
	v_mfma_f32_16x16x32_bf16 v[18:21], v[244:247], v[220:223], v[18:21]
	v_mfma_f32_16x16x32_bf16 v[6:9], v[236:239], v[228:231], v[6:9]
	v_mfma_f32_16x16x32_bf16 v[2:5], v[244:247], v[228:231], v[2:5]
	v_mfma_f32_16x16x32_bf16 v[54:57], v[240:243], v[208:211], v[54:57]
	v_mfma_f32_16x16x32_bf16 v[50:53], v[248:251], v[208:211], v[50:53]
	v_mfma_f32_16x16x32_bf16 v[38:41], v[240:243], v[216:219], v[38:41]
	v_mfma_f32_16x16x32_bf16 v[34:37], v[248:251], v[216:219], v[34:37]
	v_mfma_f32_16x16x32_bf16 v[22:25], v[240:243], v[224:227], v[22:25]
	v_mfma_f32_16x16x32_bf16 v[18:21], v[248:251], v[224:227], v[18:21]
	v_mfma_f32_16x16x32_bf16 v[6:9], v[240:243], v[232:235], v[6:9]
	v_mfma_f32_16x16x32_bf16 v[2:5], v[248:251], v[232:235], v[2:5]
	s_barrier
	s_add_i32 s31, 0, 0x18000
	v_add_u32_e32 v173, s31, v131
	ds_read_b128 v[144:147], v173
	ds_read_b128 v[148:151], v173 offset:1024
	ds_read_b128 v[152:155], v173 offset:2048
	ds_read_b128 v[200:203], v173 offset:3072
	s_add_u32 s24, s24, 0x40000
	s_addc_u32 s25, s25, 0
	s_mov_b32 m0, s42
	v_lshl_add_u64 v[236:237], s[24:25], 0, v[134:135]
	ds_read_b128 v[204:207], v172 offset:32768
	ds_read_b128 v[208:211], v172 offset:33792
	ds_read_b128 v[212:215], v172 offset:34816
	ds_read_b128 v[216:219], v172 offset:35840
	ds_read_b128 v[220:223], v172 offset:36864
	ds_read_b128 v[224:227], v172 offset:37888
	ds_read_b128 v[228:231], v172 offset:38912
	ds_read_b128 v[232:235], v172 offset:39936
	global_load_lds_dwordx4 v[236:237], off
	v_lshl_add_u64 v[236:237], s[24:25], 0, v[132:133]
	s_mov_b32 m0, s43
	s_nop 0
	global_load_lds_dwordx4 v[236:237], off
	s_waitcnt lgkmcnt(8)
	s_barrier
	s_waitcnt lgkmcnt(0)
	v_mfma_f32_16x16x32_bf16 v[126:129], v[144:147], v[204:207], v[126:129]
	v_mfma_f32_16x16x32_bf16 v[122:125], v[152:155], v[204:207], v[122:125]
	v_mfma_f32_16x16x32_bf16 v[110:113], v[144:147], v[212:215], v[110:113]
	v_mfma_f32_16x16x32_bf16 v[106:109], v[152:155], v[212:215], v[106:109]
	v_mfma_f32_16x16x32_bf16 v[94:97], v[144:147], v[220:223], v[94:97]
	v_mfma_f32_16x16x32_bf16 v[90:93], v[152:155], v[220:223], v[90:93]
	v_mfma_f32_16x16x32_bf16 v[78:81], v[144:147], v[228:231], v[78:81]
	v_mfma_f32_16x16x32_bf16 v[74:77], v[152:155], v[228:231], v[74:77]
	v_mfma_f32_16x16x32_bf16 v[126:129], v[148:151], v[208:211], v[126:129]
	v_mfma_f32_16x16x32_bf16 v[122:125], v[200:203], v[208:211], v[122:125]
	v_mfma_f32_16x16x32_bf16 v[110:113], v[148:151], v[216:219], v[110:113]
	v_mfma_f32_16x16x32_bf16 v[106:109], v[200:203], v[216:219], v[106:109]
	v_mfma_f32_16x16x32_bf16 v[94:97], v[148:151], v[224:227], v[94:97]
	v_mfma_f32_16x16x32_bf16 v[90:93], v[200:203], v[224:227], v[90:93]
	v_mfma_f32_16x16x32_bf16 v[78:81], v[148:151], v[232:235], v[78:81]
	v_mfma_f32_16x16x32_bf16 v[74:77], v[200:203], v[232:235], v[74:77]
	s_barrier
	s_add_i32 s24, 0, 0x1c000
	s_add_i32 s25, s31, s39
	v_add_u32_e32 v173, s24, v131
	v_lshl_add_u64 v[156:157], v[156:157], 0, s[86:87]
	s_mov_b32 m0, s25
	ds_read_b128 v[236:239], v173
	ds_read_b128 v[240:243], v173 offset:1024
	ds_read_b128 v[244:247], v173 offset:2048
	ds_read_b128 v[248:251], v173 offset:3072
	global_load_lds_dwordx4 v[156:157], off
	v_lshl_add_u64 v[156:157], v[174:175], 0, s[86:87]
	s_add_i32 m0, s25, 0x2000
	s_nop 0
	global_load_lds_dwordx4 v[156:157], off
	s_barrier
	s_waitcnt lgkmcnt(0)
	v_mfma_f32_16x16x32_bf16 v[118:121], v[236:239], v[204:207], v[118:121]
	v_mfma_f32_16x16x32_bf16 v[114:117], v[244:247], v[204:207], v[114:117]
	v_mfma_f32_16x16x32_bf16 v[102:105], v[236:239], v[212:215], v[102:105]
	v_mfma_f32_16x16x32_bf16 v[98:101], v[244:247], v[212:215], v[98:101]
	v_mfma_f32_16x16x32_bf16 v[86:89], v[236:239], v[220:223], v[86:89]
	v_mfma_f32_16x16x32_bf16 v[82:85], v[244:247], v[220:223], v[82:85]
	v_mfma_f32_16x16x32_bf16 v[70:73], v[236:239], v[228:231], v[70:73]
	v_mfma_f32_16x16x32_bf16 v[66:69], v[244:247], v[228:231], v[66:69]
	v_mfma_f32_16x16x32_bf16 v[118:121], v[240:243], v[208:211], v[118:121]
	v_mfma_f32_16x16x32_bf16 v[114:117], v[248:251], v[208:211], v[114:117]
	v_mfma_f32_16x16x32_bf16 v[102:105], v[240:243], v[216:219], v[102:105]
	v_mfma_f32_16x16x32_bf16 v[98:101], v[248:251], v[216:219], v[98:101]
	v_mfma_f32_16x16x32_bf16 v[86:89], v[240:243], v[224:227], v[86:89]
	v_mfma_f32_16x16x32_bf16 v[82:85], v[248:251], v[224:227], v[82:85]
	v_mfma_f32_16x16x32_bf16 v[70:73], v[240:243], v[232:235], v[70:73]
	v_mfma_f32_16x16x32_bf16 v[66:69], v[248:251], v[232:235], v[66:69]
	s_barrier
	s_mov_b32 m0, s45
	v_lshl_add_u64 v[156:157], v[182:183], 0, s[86:87]
	ds_read_b128 v[204:207], v172 offset:49152
	ds_read_b128 v[208:211], v172 offset:50176
	ds_read_b128 v[212:215], v172 offset:51200
	ds_read_b128 v[216:219], v172 offset:52224
	ds_read_b128 v[220:223], v172 offset:53248
	ds_read_b128 v[224:227], v172 offset:54272
	ds_read_b128 v[228:231], v172 offset:55296
	ds_read_b128 v[232:235], v172 offset:56320
	global_load_lds_dwordx4 v[156:157], off
	v_lshl_add_u64 v[156:157], v[184:185], 0, s[86:87]
	s_mov_b32 m0, s46
	s_nop 0
	global_load_lds_dwordx4 v[156:157], off
	s_barrier
; #define PG8_STAGE(bufoff, gbase, voff) do { _Pragma("unroll") for (int _i = 0; _i < 2; ++_i) \
;     __builtin_amdgcn_global_load_lds((const unsigned*)((const char*)(gbase) + (voff)[_i]), (PG8_LAS unsigned*)(lds + (bufoff) + ldsw + _i * 8192), 16, 0, 0); } while (0)
; #define PG8_MMA(ai, bj, At, Bt) do { __builtin_amdgcn_s_setprio(1); _Pragma("unroll") for (int m = 0; m < 4; ++m) _Pragma("unroll") for (int n = 0; n < 2; ++n) _Pragma("unroll") for (int k = 0; k < 2; ++k) \
;     acc[ai][bj][m][n] = __builtin_amdgcn_mfma_f32_16x16x32_bf16(Bt[n][k], At[m][k], acc[ai][bj][m][n], 0, 0, 0); __builtin_amdgcn_s_setprio(0); } while (0)
; #define PG8_WAIT_V(n) asm volatile("s_waitcnt vmcnt(" #n ")" ::: "memory")
; #define PG8_WAIT_L(n) asm volatile("s_waitcnt lgkmcnt(" #n ")" ::: "memory")
; #define PG8_BAR __builtin_amdgcn_s_barrier()
; #define PG8_SCHED __builtin_amdgcn_sched_barrier(0)
; template <class Epi, class Sched>
; __device__ __forceinline__ void gemm_phase(PG8_LAS unsigned char* lds, const int lda, const int ldb, const Sched& S, const Epi& E) {
;     ...
;       PG8_BAR; PG8_WAIT_L(0); PG8_MMA(1, 0, At, B0); PG8_BAR; PG8_SCHED;
;       PG8_STAGE(PG8_SB(1, 1), b3 + hstepB, voffB);
;       PG8_WAIT_V(6); PG8_BAR; PG8_MMA(1, 1, At, B1); PG8_BAR;
;   __device__ __forceinline__ void operator()(const f32x4 (&acc)[2][2][4][2], const Unit& u, int wr, int wc, int fr, int fq) const {
;     ...
;               const int nn = c - 1792, part = nn >> 8, ch = nn & 255;
;               if (u.pn == 7 && bj == 0 && wc == 1 && n == 1) {
;                 *reinterpret_cast<float4*>(AB + (size_t)r * 16 + 4 * fq) = make_float4(v[0], v[1], v[2], v[3]);
;               } else {
;                 u16* d; int cstride;
;                 if (r < ML) { const int b = r >> 11, tt = r & 2047; d = FT + ((size_t)(b * 256)) * 4096 + part * 2048 + tt; cstride = 4096; }
;                 else { const int rc = r - ML, b = rc >> 8, tt = rc & 255; d = FTC + ((size_t)(b * 256)) * 512 + part * 256 + tt; cstride = 512; }
; #pragma unroll
;                 for (int e = 0; e < 4; ++e) d[(size_t)(ch + e) * cstride] = f2bf(v[e]);
;                 if (u.pn == 7 && bj == 0 && wc == 0) {
; #pragma unroll
;                   for (int e = 0; e < 4; ++e) {
;                     const int kc = n * 16 + 4 * fq + e;
;                     if (kc >= 1 && kc <= 16) d[(size_t)(64 - kc) * cstride] = f2bf(v[e]);
	s_waitcnt lgkmcnt(0)
	v_mfma_f32_16x16x32_bf16 v[62:65], v[144:147], v[204:207], v[62:65]
	v_mfma_f32_16x16x32_bf16 v[58:61], v[152:155], v[204:207], v[58:61]
	v_mfma_f32_16x16x32_bf16 v[46:49], v[144:147], v[212:215], v[46:49]
	v_mfma_f32_16x16x32_bf16 v[42:45], v[152:155], v[212:215], v[42:45]
	v_mfma_f32_16x16x32_bf16 v[30:33], v[144:147], v[220:223], v[30:33]
	v_mfma_f32_16x16x32_bf16 v[26:29], v[152:155], v[220:223], v[26:29]
	v_mfma_f32_16x16x32_bf16 v[14:17], v[144:147], v[228:231], v[14:17]
	v_mfma_f32_16x16x32_bf16 v[10:13], v[152:155], v[228:231], v[10:13]
	v_mfma_f32_16x16x32_bf16 v[62:65], v[148:151], v[208:211], v[62:65]
	v_mfma_f32_16x16x32_bf16 v[58:61], v[200:203], v[208:211], v[58:61]
	v_mfma_f32_16x16x32_bf16 v[46:49], v[148:151], v[216:219], v[46:49]
	v_mfma_f32_16x16x32_bf16 v[42:45], v[200:203], v[216:219], v[42:45]
	v_mfma_f32_16x16x32_bf16 v[30:33], v[148:151], v[224:227], v[30:33]
	v_mfma_f32_16x16x32_bf16 v[26:29], v[200:203], v[224:227], v[26:29]
	v_mfma_f32_16x16x32_bf16 v[14:17], v[148:151], v[232:235], v[14:17]
	v_mfma_f32_16x16x32_bf16 v[10:13], v[200:203], v[232:235], v[10:13]
	s_barrier
	s_add_u32 s12, s12, 0x40080
	s_addc_u32 s13, s13, 0
	s_add_i32 s24, s24, s39
	v_lshl_add_u64 v[144:145], s[12:13], 0, v[134:135]
	s_mov_b32 m0, s24
	s_nop 0
	global_load_lds_dwordx4 v[144:145], off
	v_lshl_add_u64 v[144:145], s[12:13], 0, v[132:133]
	s_add_i32 m0, s24, 0x2000
	s_nop 0
	global_load_lds_dwordx4 v[144:145], off
	s_waitcnt vmcnt(6)
	s_barrier
	v_mfma_f32_16x16x32_bf16 v[54:57], v[236:239], v[204:207], v[54:57]
	v_mfma_f32_16x16x32_bf16 v[50:53], v[244:247], v[204:207], v[50:53]
	v_mfma_f32_16x16x32_bf16 v[38:41], v[236:239], v[212:215], v[38:41]
	v_mfma_f32_16x16x32_bf16 v[34:37], v[244:247], v[212:215], v[34:37]
	v_mfma_f32_16x16x32_bf16 v[22:25], v[236:239], v[220:223], v[22:25]
	v_mfma_f32_16x16x32_bf16 v[18:21], v[244:247], v[220:223], v[18:21]
	v_mfma_f32_16x16x32_bf16 v[6:9], v[236:239], v[228:231], v[6:9]
	v_mfma_f32_16x16x32_bf16 v[2:5], v[244:247], v[228:231], v[2:5]
	v_mfma_f32_16x16x32_bf16 v[54:57], v[240:243], v[208:211], v[54:57]
	v_mfma_f32_16x16x32_bf16 v[50:53], v[248:251], v[208:211], v[50:53]
	v_mfma_f32_16x16x32_bf16 v[38:41], v[240:243], v[216:219], v[38:41]
	v_mfma_f32_16x16x32_bf16 v[34:37], v[248:251], v[216:219], v[34:37]
	v_mfma_f32_16x16x32_bf16 v[22:25], v[240:243], v[224:227], v[22:25]
	v_mfma_f32_16x16x32_bf16 v[18:21], v[248:251], v[224:227], v[18:21]
	v_mfma_f32_16x16x32_bf16 v[6:9], v[240:243], v[232:235], v[6:9]
	v_mfma_f32_16x16x32_bf16 v[2:5], v[248:251], v[232:235], v[2:5]
	s_add_i32 s30, s30, 2
	s_add_u32 s10, s10, 0x100
	s_addc_u32 s11, s11, 0
	s_add_u32 s28, s28, 0x100
	s_addc_u32 s29, s29, 0
	s_cmp_gt_u32 s30, 13
	s_barrier
	s_cbranch_scc0 .LBB0_685
	s_lshl_b32 s17, s2, 8
	s_add_i32 s17, s17, s44
	v_or_b32_e32 v152, s17, v1
	s_mov_b32 s2, 0xffff
	v_cmp_lt_i32_e64 s[12:13], s2, v152
	s_and_b32 s2, s17, 0xffffff00
	s_add_i32 s2, s2, 0xffff0000
	s_lshl_b64 s[28:29], s[2:3], 10
	s_ashr_i32 s2, s17, 3
	s_and_b32 s10, s2, 0xffffff00
	s_ashr_i32 s11, s10, 31
	s_lshl_b64 s[26:27], s[10:11], 13
	s_lshl_b32 s24, s48, 8
	s_cmp_gt_i32 s48, 6
	s_cselect_b64 s[30:31], -1, 0
	v_bitop3_b32 v146, s17, v186, v1 bitop3:0xc8
	v_bitop3_b32 v148, s17, v187, v1 bitop3:0xc8
	s_mov_b64 s[10:11], -1
	s_and_b64 vcc, exec, s[30:31]
	s_cbranch_vccz .LBB0_696
	s_and_saveexec_b64 s[10:11], s[12:13]
	s_xor_b64 s[10:11], exec, s[10:11]
	s_add_u32 s34, s54, s28
	s_addc_u32 s35, s55, s29
	s_or_saveexec_b64 s[10:11], s[10:11]
	s_add_i32 s2, s24, 0xfffff900
	v_mov_b64_e32 v[144:145], 0x200
	v_mov_b32_e32 v150, s2
	v_mov_b64_e32 v[154:155], s[34:35]
	v_mov_b64_e32 v[156:157], v[146:147]
	s_xor_b64 exec, exec, s[10:11]
	s_add_u32 s34, s69, s26
	s_addc_u32 s35, s52, s27
	s_lshl_b32 s2, s2, 3
	v_mov_b64_e32 v[144:145], 0x1000
	v_mov_b32_e32 v150, s2
	v_mov_b64_e32 v[154:155], s[34:35]
	v_mov_b64_e32 v[156:157], v[148:149]
	s_or_b64 exec, exec, s[10:11]
	v_ashrrev_i32_e32 v151, 31, v150
	v_lshl_add_u64 v[150:151], v[150:151], 1, v[154:155]
	v_lshlrev_b32_e32 v154, 1, v156
	v_mov_b32_e32 v155, v0
	v_mul_u32_u24_e32 v145, v144, v136
	v_lshl_add_u64 v[150:151], v[150:151], 0, v[154:155]
	v_lshlrev_b32_e32 v154, 1, v145
	v_cvt_pk_bf16_f32 v149, v126, s0
	v_lshl_add_u64 v[154:155], v[150:151], 0, v[154:155]
	v_mul_u32_u24_e32 v147, v144, v166
	global_store_short v[154:155], v149, off
	v_lshlrev_b32_e32 v154, 1, v147
	v_mov_b32_e32 v155, v0
	v_cvt_pk_bf16_f32 v145, v127, s0
	v_lshl_add_u64 v[154:155], v[150:151], 0, v[154:155]
	v_mul_u32_u24_e32 v153, v144, v167
	global_store_short v[154:155], v145, off
	v_lshlrev_b32_e32 v154, 1, v153
	v_mov_b32_e32 v155, v0
	s_cmp_lg_u32 s48, 7
	v_cvt_pk_bf16_f32 v147, v128, s0
	v_lshl_add_u64 v[154:155], v[150:151], 0, v[154:155]
	s_cselect_b64 s[10:11], -1, 0
	global_store_short v[154:155], v147, off
	v_mul_u32_u24_e32 v154, v144, v168
	s_xor_b64 s[34:35], s[14:15], -1
	v_lshlrev_b32_e32 v154, 1, v154
	v_mov_b32_e32 v155, v0
	s_or_b64 s[10:11], s[34:35], s[10:11]
	v_cvt_pk_bf16_f32 v153, v129, s0
	v_lshl_add_u64 v[154:155], v[150:151], 0, v[154:155]
	s_and_b64 vcc, exec, s[10:11]
	global_store_short v[154:155], v153, off
	s_cbranch_vccnz .LBB0_695
	s_and_saveexec_b64 s[10:11], s[4:5]
	s_cbranch_execz .LBB0_694
	v_mul_u32_u24_e32 v154, v144, v158
	v_lshlrev_b32_e32 v154, 1, v154
	v_mov_b32_e32 v155, v0
	v_lshl_add_u64 v[154:155], v[150:151], 0, v[154:155]
	global_store_short v[154:155], v149, off

; #define PG8_STAGE(bufoff, gbase, voff) do { _Pragma("unroll") for (int _i = 0; _i < 2; ++_i) \
;     __builtin_amdgcn_global_load_lds((const unsigned*)((const char*)(gbase) + (voff)[_i]), (PG8_LAS unsigned*)(lds + (bufoff) + ldsw + _i * 8192), 16, 0, 0); } while (0)
; #define PG8_LDA(dst, b, h) do { _Pragma("unroll") for (int m = 0; m < 4; ++m) _Pragma("unroll") for (int k = 0; k < 2; ++k) dst[m][k] = *(const PG8_LAS bf16x8*)(lds + PG8_SA(b, h) + aoff + m * 2048 + k * 1024); } while (0)
; #define PG8_LDB(dst, b, h) do { _Pragma("unroll") for (int n = 0; n < 2; ++n) _Pragma("unroll") for (int k = 0; k < 2; ++k) dst[n][k] = *(const PG8_LAS bf16x8*)(lds + PG8_SB(b, h) + boff + n * 2048 + k * 1024); } while (0)
; #define PG8_MMA(ai, bj, At, Bt) do { __builtin_amdgcn_s_setprio(1); _Pragma("unroll") for (int m = 0; m < 4; ++m) _Pragma("unroll") for (int n = 0; n < 2; ++n) _Pragma("unroll") for (int k = 0; k < 2; ++k) \
;     acc[ai][bj][m][n] = __builtin_amdgcn_mfma_f32_16x16x32_bf16(Bt[n][k], At[m][k], acc[ai][bj][m][n], 0, 0, 0); __builtin_amdgcn_s_setprio(0); } while (0)
; #define PG8_WAIT_L(n) asm volatile("s_waitcnt lgkmcnt(" #n ")" ::: "memory")
; #define PG8_BAR __builtin_amdgcn_s_barrier()
; #define PG8_SCHED __builtin_amdgcn_sched_barrier(0)
; template <class Epi, class Sched>
; __device__ __forceinline__ void gemm_phase(PG8_LAS unsigned char* lds, const int lda, const int ldb, const Sched& S, const Epi& E) {
;     ...
;       PG8_LDB(B0, 0, 0); PG8_SCHED; PG8_LDA(At, 0, 0); PG8_STAGE(PG8_SA(1, 1), a1 + hstepA, voffA);
;       PG8_WAIT_L(8); PG8_BAR; PG8_WAIT_L(0); PG8_MMA(0, 0, At, B0); PG8_BAR; PG8_SCHED;
;       PG8_LDB(B1, 0, 1); PG8_STAGE(PG8_SB(0, 0), b2, voffB);
;       PG8_BAR; PG8_WAIT_L(0); PG8_MMA(0, 1, At, B1); PG8_BAR;
;       PG8_LDA(At, 0, 1); PG8_STAGE(PG8_SA(0, 0), a2, voffA);
;       PG8_BAR; PG8_WAIT_L(0); PG8_MMA(1, 0, At, B0); PG8_BAR; PG8_SCHED;
.LBB0_1088:
	s_add_u32 s16, s14, 0xfff00080
	s_addc_u32 s17, s15, -1
	s_add_i32 s33, 0, 0x10000
	v_add_u32_e32 v145, s33, v1
	ds_read_b128 v[152:155], v145
	ds_read_b128 v[156:159], v145 offset:1024
	ds_read_b128 v[160:163], v145 offset:2048
	ds_read_b128 v[164:167], v145 offset:3072
	s_cmp_eq_u32 s34, 60
	s_cselect_b32 s19, s7, s17
	s_cselect_b32 s18, s13, s16
	s_cselect_b32 s17, s1, s31
	s_cselect_b32 s16, s29, s30
	v_lshl_add_u64 v[182:183], s[14:15], 0, v[140:141]
	s_add_i32 m0, s21, 0xc000
	ds_read_b128 v[168:171], v131
	ds_read_b128 v[172:175], v131 offset:1024
	ds_read_b128 v[200:203], v131 offset:2048
	ds_read_b128 v[204:207], v131 offset:3072
	ds_read_b128 v[208:211], v131 offset:4096
	ds_read_b128 v[212:215], v131 offset:5120
	ds_read_b128 v[216:219], v131 offset:6144
	ds_read_b128 v[220:223], v131 offset:7168
	global_load_lds_dwordx4 v[182:183], off
	v_lshl_add_u64 v[182:183], s[14:15], 0, v[142:143]
	s_add_i32 m0, s21, 0xe000
	s_nop 0
	global_load_lds_dwordx4 v[182:183], off
	s_waitcnt lgkmcnt(8)
	s_barrier
	s_waitcnt lgkmcnt(0)
	v_mfma_f32_16x16x32_bf16 v[126:129], v[152:155], v[168:171], v[126:129]
	v_mfma_f32_16x16x32_bf16 v[122:125], v[160:163], v[168:171], v[122:125]
	v_mfma_f32_16x16x32_bf16 v[118:121], v[152:155], v[200:203], v[118:121]
	v_mfma_f32_16x16x32_bf16 v[114:117], v[160:163], v[200:203], v[114:117]
	v_mfma_f32_16x16x32_bf16 v[102:105], v[152:155], v[208:211], v[102:105]
	v_mfma_f32_16x16x32_bf16 v[98:101], v[160:163], v[208:211], v[98:101]
	v_mfma_f32_16x16x32_bf16 v[86:89], v[152:155], v[216:219], v[86:89]
	v_mfma_f32_16x16x32_bf16 v[82:85], v[160:163], v[216:219], v[82:85]
	v_mfma_f32_16x16x32_bf16 v[126:129], v[156:159], v[172:175], v[126:129]
	v_mfma_f32_16x16x32_bf16 v[122:125], v[164:167], v[172:175], v[122:125]
	v_mfma_f32_16x16x32_bf16 v[118:121], v[156:159], v[204:207], v[118:121]
	v_mfma_f32_16x16x32_bf16 v[114:117], v[164:167], v[204:207], v[114:117]
	v_mfma_f32_16x16x32_bf16 v[102:105], v[156:159], v[212:215], v[102:105]
	v_mfma_f32_16x16x32_bf16 v[98:101], v[164:167], v[212:215], v[98:101]
	v_mfma_f32_16x16x32_bf16 v[86:89], v[156:159], v[220:223], v[86:89]
	v_mfma_f32_16x16x32_bf16 v[82:85], v[164:167], v[220:223], v[82:85]
	s_barrier
	s_add_i32 s35, 0, 0x14000
	s_add_i32 s33, s33, s20
	v_add_u32_e32 v145, s35, v1
	v_lshl_add_u64 v[182:183], s[16:17], 0, v[134:135]
	s_mov_b32 m0, s33
	ds_read_b128 v[224:227], v145
	ds_read_b128 v[228:231], v145 offset:1024
	ds_read_b128 v[232:235], v145 offset:2048
	ds_read_b128 v[236:239], v145 offset:3072
	global_load_lds_dwordx4 v[182:183], off
	v_lshl_add_u64 v[184:185], s[16:17], 0, v[132:133]
	s_add_i32 m0, s33, 0x2000
	s_nop 0
	global_load_lds_dwordx4 v[184:185], off
	s_barrier
	s_waitcnt lgkmcnt(0)
	v_mfma_f32_16x16x32_bf16 v[110:113], v[224:227], v[168:171], v[110:113]
	v_mfma_f32_16x16x32_bf16 v[106:109], v[232:235], v[168:171], v[106:109]
	v_mfma_f32_16x16x32_bf16 v[94:97], v[224:227], v[200:203], v[94:97]
	v_mfma_f32_16x16x32_bf16 v[90:93], v[232:235], v[200:203], v[90:93]
	v_mfma_f32_16x16x32_bf16 v[78:81], v[224:227], v[208:211], v[78:81]
	v_mfma_f32_16x16x32_bf16 v[74:77], v[232:235], v[208:211], v[74:77]
	v_mfma_f32_16x16x32_bf16 v[70:73], v[224:227], v[216:219], v[70:73]
	v_mfma_f32_16x16x32_bf16 v[66:69], v[232:235], v[216:219], v[66:69]
	v_mfma_f32_16x16x32_bf16 v[110:113], v[228:231], v[172:175], v[110:113]
	v_mfma_f32_16x16x32_bf16 v[106:109], v[236:239], v[172:175], v[106:109]
	v_mfma_f32_16x16x32_bf16 v[94:97], v[228:231], v[204:207], v[94:97]
	v_mfma_f32_16x16x32_bf16 v[90:93], v[236:239], v[204:207], v[90:93]
	v_mfma_f32_16x16x32_bf16 v[78:81], v[228:231], v[212:215], v[78:81]
	v_mfma_f32_16x16x32_bf16 v[74:77], v[236:239], v[212:215], v[74:77]
	v_mfma_f32_16x16x32_bf16 v[70:73], v[228:231], v[220:223], v[70:73]
	v_mfma_f32_16x16x32_bf16 v[66:69], v[236:239], v[220:223], v[66:69]
	s_barrier
	s_mov_b32 m0, s21
	v_lshl_add_u64 v[240:241], s[18:19], 0, v[134:135]
	ds_read_b128 v[168:171], v131 offset:16384
	ds_read_b128 v[172:175], v131 offset:17408
	ds_read_b128 v[200:203], v131 offset:18432
	ds_read_b128 v[204:207], v131 offset:19456
	ds_read_b128 v[208:211], v131 offset:20480
	ds_read_b128 v[212:215], v131 offset:21504
	ds_read_b128 v[216:219], v131 offset:22528
	ds_read_b128 v[220:223], v131 offset:23552
	global_load_lds_dwordx4 v[240:241], off
	v_lshl_add_u64 v[242:243], s[18:19], 0, v[132:133]
	s_mov_b32 m0, s22
	s_nop 0
	global_load_lds_dwordx4 v[242:243], off
	s_barrier
	s_waitcnt lgkmcnt(0)
	v_mfma_f32_16x16x32_bf16 v[62:65], v[152:155], v[168:171], v[62:65]
	v_mfma_f32_16x16x32_bf16 v[58:61], v[160:163], v[168:171], v[58:61]
	v_mfma_f32_16x16x32_bf16 v[54:57], v[152:155], v[200:203], v[54:57]
	v_mfma_f32_16x16x32_bf16 v[46:49], v[160:163], v[200:203], v[46:49]
	v_mfma_f32_16x16x32_bf16 v[38:41], v[152:155], v[208:211], v[38:41]
	v_mfma_f32_16x16x32_bf16 v[34:37], v[160:163], v[208:211], v[34:37]
	v_mfma_f32_16x16x32_bf16 v[22:25], v[152:155], v[216:219], v[22:25]
	v_mfma_f32_16x16x32_bf16 v[18:21], v[160:163], v[216:219], v[18:21]
	v_mfma_f32_16x16x32_bf16 v[62:65], v[156:159], v[172:175], v[62:65]
	v_mfma_f32_16x16x32_bf16 v[58:61], v[164:167], v[172:175], v[58:61]
	v_mfma_f32_16x16x32_bf16 v[54:57], v[156:159], v[204:207], v[54:57]
	v_mfma_f32_16x16x32_bf16 v[46:49], v[164:167], v[204:207], v[46:49]
	v_mfma_f32_16x16x32_bf16 v[38:41], v[156:159], v[212:215], v[38:41]
	v_mfma_f32_16x16x32_bf16 v[34:37], v[164:167], v[212:215], v[34:37]
	v_mfma_f32_16x16x32_bf16 v[22:25], v[156:159], v[220:223], v[22:25]
	v_mfma_f32_16x16x32_bf16 v[18:21], v[164:167], v[220:223], v[18:21]
	s_barrier
; #define PG8_STAGE(bufoff, gbase, voff) do { _Pragma("unroll") for (int _i = 0; _i < 2; ++_i) \
;     __builtin_amdgcn_global_load_lds((const unsigned*)((const char*)(gbase) + (voff)[_i]), (PG8_LAS unsigned*)(lds + (bufoff) + ldsw + _i * 8192), 16, 0, 0); } while (0)
; #define PG8_LDA(dst, b, h) do { _Pragma("unroll") for (int m = 0; m < 4; ++m) _Pragma("unroll") for (int k = 0; k < 2; ++k) dst[m][k] = *(const PG8_LAS bf16x8*)(lds + PG8_SA(b, h) + aoff + m * 2048 + k * 1024); } while (0)
; #define PG8_LDB(dst, b, h) do { _Pragma("unroll") for (int n = 0; n < 2; ++n) _Pragma("unroll") for (int k = 0; k < 2; ++k) dst[n][k] = *(const PG8_LAS bf16x8*)(lds + PG8_SB(b, h) + boff + n * 2048 + k * 1024); } while (0)
; #define PG8_MMA(ai, bj, At, Bt) do { __builtin_amdgcn_s_setprio(1); _Pragma("unroll") for (int m = 0; m < 4; ++m) _Pragma("unroll") for (int n = 0; n < 2; ++n) _Pragma("unroll") for (int k = 0; k < 2; ++k) \
;     acc[ai][bj][m][n] = __builtin_amdgcn_mfma_f32_16x16x32_bf16(Bt[n][k], At[m][k], acc[ai][bj][m][n], 0, 0, 0); __builtin_amdgcn_s_setprio(0); } while (0)
; #define PG8_WAIT_V(n) asm volatile("s_waitcnt vmcnt(" #n ")" ::: "memory")
; #define PG8_WAIT_L(n) asm volatile("s_waitcnt lgkmcnt(" #n ")" ::: "memory")
; #define PG8_BAR __builtin_amdgcn_s_barrier()
; #define PG8_SCHED __builtin_amdgcn_sched_barrier(0)
; template <class Epi, class Sched>
; __device__ __forceinline__ void gemm_phase(PG8_LAS unsigned char* lds, const int lda, const int ldb, const Sched& S, const Epi& E) {
;     ...
;       PG8_STAGE(PG8_SB(0, 1), b2 + hstepB, voffB);
;       PG8_WAIT_V(6); PG8_BAR; PG8_MMA(1, 1, At, B1); PG8_BAR;
;       PG8_LDB(B0, 1, 0); PG8_SCHED; PG8_LDA(At, 1, 0); PG8_STAGE(PG8_SA(0, 1), a2 + hstepA, voffA);
;       PG8_WAIT_L(8); PG8_BAR; PG8_WAIT_L(0); PG8_MMA(0, 0, At, B0); PG8_BAR; PG8_SCHED;
;       PG8_LDB(B1, 1, 1); PG8_STAGE(PG8_SB(1, 0), b3, voffB);
;       PG8_BAR; PG8_WAIT_L(0); PG8_MMA(0, 1, At, B1); PG8_BAR;
;       PG8_LDA(At, 1, 1); PG8_STAGE(PG8_SA(1, 0), a3, voffA);
	s_add_u32 s36, s16, 0x100000
	s_addc_u32 s37, s17, 0
	s_add_i32 s33, s35, s20
	v_lshl_add_u64 v[152:153], s[36:37], 0, v[134:135]
	s_mov_b32 m0, s33
	s_nop 0
	global_load_lds_dwordx4 v[152:153], off
	v_lshl_add_u64 v[152:153], s[36:37], 0, v[132:133]
	s_add_i32 m0, s33, 0x2000
	s_nop 0
	global_load_lds_dwordx4 v[152:153], off
	s_waitcnt vmcnt(6)
	s_barrier
	v_mfma_f32_16x16x32_bf16 v[50:53], v[224:227], v[168:171], v[50:53]
	v_mfma_f32_16x16x32_bf16 v[42:45], v[232:235], v[168:171], v[42:45]
	v_mfma_f32_16x16x32_bf16 v[30:33], v[224:227], v[200:203], v[30:33]
	v_mfma_f32_16x16x32_bf16 v[26:29], v[232:235], v[200:203], v[26:29]
	v_mfma_f32_16x16x32_bf16 v[14:17], v[224:227], v[208:211], v[14:17]
	v_mfma_f32_16x16x32_bf16 v[10:13], v[232:235], v[208:211], v[10:13]
	v_mfma_f32_16x16x32_bf16 v[6:9], v[224:227], v[216:219], v[6:9]
	v_mfma_f32_16x16x32_bf16 v[2:5], v[232:235], v[216:219], v[2:5]
	v_mfma_f32_16x16x32_bf16 v[50:53], v[228:231], v[172:175], v[50:53]
	v_mfma_f32_16x16x32_bf16 v[42:45], v[236:239], v[172:175], v[42:45]
	v_mfma_f32_16x16x32_bf16 v[30:33], v[228:231], v[204:207], v[30:33]
	v_mfma_f32_16x16x32_bf16 v[26:29], v[236:239], v[204:207], v[26:29]
	v_mfma_f32_16x16x32_bf16 v[14:17], v[228:231], v[212:215], v[14:17]
	v_mfma_f32_16x16x32_bf16 v[10:13], v[236:239], v[212:215], v[10:13]
	v_mfma_f32_16x16x32_bf16 v[6:9], v[228:231], v[220:223], v[6:9]
	v_mfma_f32_16x16x32_bf16 v[2:5], v[236:239], v[220:223], v[2:5]
	s_barrier
	s_add_i32 s33, 0, 0x18000
	v_add_u32_e32 v145, s33, v1
	ds_read_b128 v[152:155], v145
	ds_read_b128 v[156:159], v145 offset:1024
	ds_read_b128 v[160:163], v145 offset:2048
	ds_read_b128 v[164:167], v145 offset:3072
	s_add_u32 s18, s18, 0x100000
	s_addc_u32 s19, s19, 0
	s_mov_b32 m0, s23
	v_lshl_add_u64 v[224:225], s[18:19], 0, v[134:135]
	ds_read_b128 v[168:171], v131 offset:32768
	ds_read_b128 v[172:175], v131 offset:33792
	ds_read_b128 v[200:203], v131 offset:34816
	ds_read_b128 v[204:207], v131 offset:35840
	ds_read_b128 v[208:211], v131 offset:36864
	ds_read_b128 v[212:215], v131 offset:37888
	ds_read_b128 v[216:219], v131 offset:38912
	ds_read_b128 v[220:223], v131 offset:39936
	global_load_lds_dwordx4 v[224:225], off
	v_lshl_add_u64 v[224:225], s[18:19], 0, v[132:133]
	s_mov_b32 m0, s24
	s_nop 0
	global_load_lds_dwordx4 v[224:225], off
	s_waitcnt lgkmcnt(8)
	s_barrier
	s_waitcnt lgkmcnt(0)
	v_mfma_f32_16x16x32_bf16 v[126:129], v[152:155], v[168:171], v[126:129]
	v_mfma_f32_16x16x32_bf16 v[122:125], v[160:163], v[168:171], v[122:125]
	v_mfma_f32_16x16x32_bf16 v[118:121], v[152:155], v[200:203], v[118:121]
	v_mfma_f32_16x16x32_bf16 v[114:117], v[160:163], v[200:203], v[114:117]
	v_mfma_f32_16x16x32_bf16 v[102:105], v[152:155], v[208:211], v[102:105]
	v_mfma_f32_16x16x32_bf16 v[98:101], v[160:163], v[208:211], v[98:101]
	v_mfma_f32_16x16x32_bf16 v[86:89], v[152:155], v[216:219], v[86:89]
	v_mfma_f32_16x16x32_bf16 v[82:85], v[160:163], v[216:219], v[82:85]
	v_mfma_f32_16x16x32_bf16 v[126:129], v[156:159], v[172:175], v[126:129]
	v_mfma_f32_16x16x32_bf16 v[122:125], v[164:167], v[172:175], v[122:125]
	v_mfma_f32_16x16x32_bf16 v[118:121], v[156:159], v[204:207], v[118:121]
	v_mfma_f32_16x16x32_bf16 v[114:117], v[164:167], v[204:207], v[114:117]
	v_mfma_f32_16x16x32_bf16 v[102:105], v[156:159], v[212:215], v[102:105]
	v_mfma_f32_16x16x32_bf16 v[98:101], v[164:167], v[212:215], v[98:101]
	v_mfma_f32_16x16x32_bf16 v[86:89], v[156:159], v[220:223], v[86:89]
	v_mfma_f32_16x16x32_bf16 v[82:85], v[164:167], v[220:223], v[82:85]
	s_barrier
	s_add_i32 s18, 0, 0x1c000
	s_add_i32 s19, s33, s20
	v_add_u32_e32 v145, s18, v1
	v_lshl_add_u64 v[182:183], v[182:183], 0, s[86:87]
	s_mov_b32 m0, s19
	ds_read_b128 v[224:227], v145
	ds_read_b128 v[228:231], v145 offset:1024
	ds_read_b128 v[232:235], v145 offset:2048
	ds_read_b128 v[236:239], v145 offset:3072
	global_load_lds_dwordx4 v[182:183], off
	v_lshl_add_u64 v[182:183], v[184:185], 0, s[86:87]
	s_add_i32 m0, s19, 0x2000
	s_nop 0
	global_load_lds_dwordx4 v[182:183], off
	s_barrier
	s_waitcnt lgkmcnt(0)
	v_mfma_f32_16x16x32_bf16 v[110:113], v[224:227], v[168:171], v[110:113]
	v_mfma_f32_16x16x32_bf16 v[106:109], v[232:235], v[168:171], v[106:109]
	v_mfma_f32_16x16x32_bf16 v[94:97], v[224:227], v[200:203], v[94:97]
	v_mfma_f32_16x16x32_bf16 v[90:93], v[232:235], v[200:203], v[90:93]
	v_mfma_f32_16x16x32_bf16 v[78:81], v[224:227], v[208:211], v[78:81]
	v_mfma_f32_16x16x32_bf16 v[74:77], v[232:235], v[208:211], v[74:77]
	v_mfma_f32_16x16x32_bf16 v[70:73], v[224:227], v[216:219], v[70:73]
	v_mfma_f32_16x16x32_bf16 v[66:69], v[232:235], v[216:219], v[66:69]
	v_mfma_f32_16x16x32_bf16 v[110:113], v[228:231], v[172:175], v[110:113]
	v_mfma_f32_16x16x32_bf16 v[106:109], v[236:239], v[172:175], v[106:109]
	v_mfma_f32_16x16x32_bf16 v[94:97], v[228:231], v[204:207], v[94:97]
	v_mfma_f32_16x16x32_bf16 v[90:93], v[236:239], v[204:207], v[90:93]
	v_mfma_f32_16x16x32_bf16 v[78:81], v[228:231], v[212:215], v[78:81]
	v_mfma_f32_16x16x32_bf16 v[74:77], v[236:239], v[212:215], v[74:77]
	v_mfma_f32_16x16x32_bf16 v[70:73], v[228:231], v[220:223], v[70:73]
	v_mfma_f32_16x16x32_bf16 v[66:69], v[236:239], v[220:223], v[66:69]
	s_barrier
	s_mov_b32 m0, s25
	v_lshl_add_u64 v[182:183], v[240:241], 0, s[86:87]
	ds_read_b128 v[168:171], v131 offset:49152
	ds_read_b128 v[172:175], v131 offset:50176
	ds_read_b128 v[200:203], v131 offset:51200
	ds_read_b128 v[204:207], v131 offset:52224
	ds_read_b128 v[208:211], v131 offset:53248
	ds_read_b128 v[212:215], v131 offset:54272
	ds_read_b128 v[216:219], v131 offset:55296
	ds_read_b128 v[220:223], v131 offset:56320
	global_load_lds_dwordx4 v[182:183], off
	v_lshl_add_u64 v[182:183], v[242:243], 0, s[86:87]
	s_mov_b32 m0, s26
	s_nop 0
	global_load_lds_dwordx4 v[182:183], off
	s_barrier
; #define PG8_STAGE(bufoff, gbase, voff) do { _Pragma("unroll") for (int _i = 0; _i < 2; ++_i) \
;     __builtin_amdgcn_global_load_lds((const unsigned*)((const char*)(gbase) + (voff)[_i]), (PG8_LAS unsigned*)(lds + (bufoff) + ldsw + _i * 8192), 16, 0, 0); } while (0)
; #define PG8_MMA(ai, bj, At, Bt) do { __builtin_amdgcn_s_setprio(1); _Pragma("unroll") for (int m = 0; m < 4; ++m) _Pragma("unroll") for (int n = 0; n < 2; ++n) _Pragma("unroll") for (int k = 0; k < 2; ++k) \
;     acc[ai][bj][m][n] = __builtin_amdgcn_mfma_f32_16x16x32_bf16(Bt[n][k], At[m][k], acc[ai][bj][m][n], 0, 0, 0); __builtin_amdgcn_s_setprio(0); } while (0)
; #define PG8_WAIT_V(n) asm volatile("s_waitcnt vmcnt(" #n ")" ::: "memory")
; #define PG8_WAIT_L(n) asm volatile("s_waitcnt lgkmcnt(" #n ")" ::: "memory")
; #define PG8_BAR __builtin_amdgcn_s_barrier()
; #define PG8_SCHED __builtin_amdgcn_sched_barrier(0)
; template <class Epi, class Sched>
; __device__ __forceinline__ void gemm_phase(PG8_LAS unsigned char* lds, const int lda, const int ldb, const Sched& S, const Epi& E) {
;     ...
;       PG8_BAR; PG8_WAIT_L(0); PG8_MMA(1, 0, At, B0); PG8_BAR; PG8_SCHED;
;       PG8_STAGE(PG8_SB(1, 1), b3 + hstepB, voffB);
;       PG8_WAIT_V(6); PG8_BAR; PG8_MMA(1, 1, At, B1); PG8_BAR;
	s_waitcnt lgkmcnt(0)
	v_mfma_f32_16x16x32_bf16 v[62:65], v[152:155], v[168:171], v[62:65]
	v_mfma_f32_16x16x32_bf16 v[58:61], v[160:163], v[168:171], v[58:61]
	v_mfma_f32_16x16x32_bf16 v[54:57], v[152:155], v[200:203], v[54:57]
	v_mfma_f32_16x16x32_bf16 v[46:49], v[160:163], v[200:203], v[46:49]
	v_mfma_f32_16x16x32_bf16 v[38:41], v[152:155], v[208:211], v[38:41]
	v_mfma_f32_16x16x32_bf16 v[34:37], v[160:163], v[208:211], v[34:37]
	v_mfma_f32_16x16x32_bf16 v[22:25], v[152:155], v[216:219], v[22:25]
	v_mfma_f32_16x16x32_bf16 v[18:21], v[160:163], v[216:219], v[18:21]
	v_mfma_f32_16x16x32_bf16 v[62:65], v[156:159], v[172:175], v[62:65]
	v_mfma_f32_16x16x32_bf16 v[58:61], v[164:167], v[172:175], v[58:61]
	v_mfma_f32_16x16x32_bf16 v[54:57], v[156:159], v[204:207], v[54:57]
	v_mfma_f32_16x16x32_bf16 v[46:49], v[164:167], v[204:207], v[46:49]
	v_mfma_f32_16x16x32_bf16 v[38:41], v[156:159], v[212:215], v[38:41]
	v_mfma_f32_16x16x32_bf16 v[34:37], v[164:167], v[212:215], v[34:37]
	v_mfma_f32_16x16x32_bf16 v[22:25], v[156:159], v[220:223], v[22:25]
	v_mfma_f32_16x16x32_bf16 v[18:21], v[164:167], v[220:223], v[18:21]
	s_barrier
	s_add_u32 s16, s16, 0x100080
	s_addc_u32 s17, s17, 0
	s_add_i32 s18, s18, s20
	v_lshl_add_u64 v[152:153], s[16:17], 0, v[134:135]
	s_mov_b32 m0, s18
	s_nop 0
	global_load_lds_dwordx4 v[152:153], off
	v_lshl_add_u64 v[152:153], s[16:17], 0, v[132:133]
	s_add_i32 m0, s18, 0x2000
	s_nop 0
	global_load_lds_dwordx4 v[152:153], off
	s_waitcnt vmcnt(6)
	s_barrier
	v_mfma_f32_16x16x32_bf16 v[50:53], v[224:227], v[168:171], v[50:53]
	v_mfma_f32_16x16x32_bf16 v[42:45], v[232:235], v[168:171], v[42:45]
	v_mfma_f32_16x16x32_bf16 v[30:33], v[224:227], v[200:203], v[30:33]
	v_mfma_f32_16x16x32_bf16 v[26:29], v[232:235], v[200:203], v[26:29]
	v_mfma_f32_16x16x32_bf16 v[14:17], v[224:227], v[208:211], v[14:17]
	v_mfma_f32_16x16x32_bf16 v[10:13], v[232:235], v[208:211], v[10:13]
	v_mfma_f32_16x16x32_bf16 v[6:9], v[224:227], v[216:219], v[6:9]
	v_mfma_f32_16x16x32_bf16 v[2:5], v[232:235], v[216:219], v[2:5]
	v_mfma_f32_16x16x32_bf16 v[50:53], v[228:231], v[172:175], v[50:53]
	v_mfma_f32_16x16x32_bf16 v[42:45], v[236:239], v[172:175], v[42:45]
	v_mfma_f32_16x16x32_bf16 v[30:33], v[228:231], v[204:207], v[30:33]
	v_mfma_f32_16x16x32_bf16 v[26:29], v[236:239], v[204:207], v[26:29]
	v_mfma_f32_16x16x32_bf16 v[14:17], v[228:231], v[212:215], v[14:17]
	v_mfma_f32_16x16x32_bf16 v[10:13], v[236:239], v[212:215], v[10:13]
	v_mfma_f32_16x16x32_bf16 v[6:9], v[228:231], v[220:223], v[6:9]
	v_mfma_f32_16x16x32_bf16 v[2:5], v[236:239], v[220:223], v[2:5]
	s_add_i32 s34, s34, 2
	s_add_u32 s14, s14, 0x100
	s_addc_u32 s15, s15, 0
	s_add_u32 s30, s30, 0x100
	s_addc_u32 s31, s31, 0
	s_cmp_gt_u32 s34, 61
	s_barrier
	s_cbranch_scc0 .LBB0_1088
; #define PG8_WAIT_V(n) asm volatile("s_waitcnt vmcnt(" #n ")" ::: "memory")
; #define PG8_BAR __builtin_amdgcn_s_barrier()
; template <class Epi, class Sched>
; __device__ __forceinline__ void gemm_phase(PG8_LAS unsigned char* lds, const int lda, const int ldb, const Sched& S, const Epi& E) {
;     ...
;   PG8_WAIT_V(0);
;   if (wr == 0) PG8_BAR;
;   __device__ __forceinline__ void operator()(const f32x4 (&acc)[2][2][4][2], const Unit& u, int wr, int wc, int fr, int fq) const {
;     ...
;         const size_t r = (size_t)rowbase + (size_t)u.pn * rows_per_b + u.pm * 256 + ai * 128 + wr * 64 + m * 16 + fr;
; #pragma unroll
;         for (int bj = 0; bj < 2; ++bj)
; #pragma unroll
;           for (int n = 0; n < 2; ++n) {
;             const f32x4 v = acc[ai][bj][m][n];
;             const int c = 256 + bj * 128 + wc * 32 + n * 16 + 4 * fq;
;             uint2 w; w.x = pack2(v[0], v[1]); w.y = pack2(v[2], v[3]);
;             *reinterpret_cast<uint2*>(Y + r * 1024 + c) = w;
	s_lshl_b32 s14, s28, 8
	s_ashr_i32 s15, s14, 31
	s_ashr_i32 s13, s12, 31
	v_lshl_add_u64 v[152:153], v[136:137], 0, s[14:15]
	s_lshl_b64 s[12:13], s[12:13], 22
	v_lshlrev_b64 v[152:153], 11, v[152:153]
	v_lshl_add_u64 v[152:153], v[152:153], 0, s[12:13]
	v_readlane_b32 s12, v253, 54
	v_readlane_b32 s13, v253, 55
	v_mov_b32_e32 v145, v0
	v_cvt_pk_bf16_f32 v109, v108, v109
	v_lshl_add_u64 v[154:155], s[12:13], 0, v[152:153]
	v_lshl_add_u64 v[156:157], v[154:155], 0, v[144:145]
	v_cvt_pk_bf16_f32 v108, v106, v107
	v_or_b32_e32 v106, 0x8000, v152
	v_mov_b32_e32 v107, v153
	s_mov_b64 s[12:13], 0x40000
	v_cvt_pk_bf16_f32 v129, v128, v129
	v_cvt_pk_bf16_f32 v128, v126, v127
	v_cvt_pk_bf16_f32 v125, v124, v125
	v_cvt_pk_bf16_f32 v124, v122, v123
	v_cvt_pk_bf16_f32 v113, v112, v113
	v_cvt_pk_bf16_f32 v112, v110, v111
	global_store_dwordx2 v[156:157], v[108:109], off offset:800
	v_lshl_add_u64 v[106:107], v[138:139], 0, v[106:107]
	v_cvt_pk_bf16_f32 v109, v120, v121
	v_cvt_pk_bf16_f32 v108, v118, v119
	v_cvt_pk_bf16_f32 v93, v92, v93
	v_cvt_pk_bf16_f32 v92, v90, v91
	v_or_b32_e32 v90, 0x10000, v152
	v_mov_b32_e32 v91, v153
	v_cvt_pk_bf16_f32 v69, v68, v69
	v_cvt_pk_bf16_f32 v68, v66, v67
	v_lshl_add_u64 v[66:67], v[154:155], 0, s[12:13]
	s_mov_b64 s[12:13], 0x48000
	global_store_dwordx2 v[156:157], v[128:129], off offset:512
	global_store_dwordx2 v[156:157], v[124:125], off offset:544
	global_store_dwordx2 v[156:157], v[112:113], off offset:768
	global_store_dwordx2 v[106:107], v[108:109], off offset:512
	v_cvt_pk_bf16_f32 v109, v116, v117
	v_cvt_pk_bf16_f32 v108, v114, v115
	v_cvt_pk_bf16_f32 v97, v96, v97
	v_cvt_pk_bf16_f32 v96, v94, v95
	global_store_dwordx2 v[106:107], v[92:93], off offset:800
	v_lshl_add_u64 v[90:91], v[138:139], 0, v[90:91]
	v_cvt_pk_bf16_f32 v93, v104, v105
	v_cvt_pk_bf16_f32 v92, v102, v103
	v_cvt_pk_bf16_f32 v77, v76, v77
	v_cvt_pk_bf16_f32 v76, v74, v75
	v_or_b32_e32 v152, 0x18000, v152
	v_cvt_pk_bf16_f32 v45, v44, v45
	v_cvt_pk_bf16_f32 v44, v42, v43
	v_lshl_add_u64 v[42:43], v[154:155], 0, s[12:13]
	s_mov_b64 s[12:13], 0x50000
	global_store_dwordx2 v[106:107], v[108:109], off offset:544
	global_store_dwordx2 v[106:107], v[96:97], off offset:768
	global_store_dwordx2 v[90:91], v[92:93], off offset:512
	v_cvt_pk_bf16_f32 v93, v100, v101
	v_cvt_pk_bf16_f32 v92, v98, v99
	v_cvt_pk_bf16_f32 v81, v80, v81
	v_cvt_pk_bf16_f32 v80, v78, v79
	global_store_dwordx2 v[90:91], v[76:77], off offset:800
	v_lshl_add_u64 v[74:75], v[138:139], 0, v[152:153]
	v_cvt_pk_bf16_f32 v77, v88, v89
	v_cvt_pk_bf16_f32 v76, v86, v87
	v_mov_b32_e32 v151, v0
	v_cvt_pk_bf16_f32 v29, v28, v29
	v_cvt_pk_bf16_f32 v28, v26, v27
	v_lshl_add_u64 v[26:27], v[154:155], 0, s[12:13]
	s_mov_b64 s[12:13], 0x58000
	global_store_dwordx2 v[90:91], v[92:93], off offset:544
	global_store_dwordx2 v[90:91], v[80:81], off offset:768
	global_store_dwordx2 v[74:75], v[76:77], off offset:512
	v_cvt_pk_bf16_f32 v77, v84, v85
	v_cvt_pk_bf16_f32 v76, v82, v83
	v_cvt_pk_bf16_f32 v73, v72, v73
	v_cvt_pk_bf16_f32 v72, v70, v71
	v_cvt_pk_bf16_f32 v53, v52, v53
	v_cvt_pk_bf16_f32 v52, v50, v51
	v_lshl_add_u64 v[50:51], v[66:67], 0, v[150:151]
	v_cvt_pk_bf16_f32 v33, v32, v33
	v_cvt_pk_bf16_f32 v32, v30, v31
	v_lshl_add_u64 v[30:31], v[42:43], 0, v[150:151]
	v_cvt_pk_bf16_f32 v17, v16, v17
	v_cvt_pk_bf16_f32 v16, v14, v15
	v_lshl_add_u64 v[14:15], v[26:27], 0, v[150:151]
	v_cvt_pk_bf16_f32 v13, v12, v13
	v_cvt_pk_bf16_f32 v12, v10, v11
	v_lshl_add_u64 v[10:11], v[154:155], 0, s[12:13]
	global_store_dwordx2 v[74:75], v[76:77], off offset:544
	global_store_dwordx2 v[74:75], v[72:73], off offset:768
	global_store_dwordx2 v[74:75], v[68:69], off offset:800
	v_mov_b32_e32 v147, v0
	global_store_dwordx2 v[50:51], v[44:45], off offset:512
	v_lshl_add_u64 v[44:45], v[42:43], 0, v[144:145]
	v_cvt_pk_bf16_f32 v51, v56, v57
	v_cvt_pk_bf16_f32 v50, v54, v55
	global_store_dwordx2 v[30:31], v[28:29], off offset:512
	v_lshl_add_u64 v[28:29], v[26:27], 0, v[144:145]
	v_cvt_pk_bf16_f32 v31, v40, v41
	v_cvt_pk_bf16_f32 v30, v38, v39
	global_store_dwordx2 v[14:15], v[12:13], off offset:512
	v_lshl_add_u64 v[12:13], v[10:11], 0, v[144:145]
	v_cvt_pk_bf16_f32 v15, v24, v25
	v_cvt_pk_bf16_f32 v14, v22, v23
	v_mov_b32_e32 v149, v0
	global_store_dwordx2 v[44:45], v[50:51], off offset:512
	v_lshl_add_u64 v[44:45], v[42:43], 0, v[146:147]
	v_cvt_pk_bf16_f32 v49, v48, v49
	v_cvt_pk_bf16_f32 v48, v46, v47
	global_store_dwordx2 v[28:29], v[30:31], off offset:512
	v_lshl_add_u64 v[28:29], v[26:27], 0, v[146:147]
	v_cvt_pk_bf16_f32 v31, v36, v37
	v_cvt_pk_bf16_f32 v30, v34, v35
	global_store_dwordx2 v[12:13], v[14:15], off offset:512
	v_lshl_add_u64 v[12:13], v[10:11], 0, v[146:147]
	v_cvt_pk_bf16_f32 v15, v20, v21
	v_cvt_pk_bf16_f32 v14, v18, v19
	v_lshl_add_u64 v[68:69], v[66:67], 0, v[144:145]
	v_cvt_pk_bf16_f32 v65, v64, v65
	v_cvt_pk_bf16_f32 v64, v62, v63
	v_lshl_add_u64 v[62:63], v[66:67], 0, v[146:147]
	v_cvt_pk_bf16_f32 v61, v60, v61
	v_cvt_pk_bf16_f32 v60, v58, v59
	v_lshl_add_u64 v[58:59], v[66:67], 0, v[148:149]
	global_store_dwordx2 v[44:45], v[48:49], off offset:512
	v_lshl_add_u64 v[44:45], v[42:43], 0, v[148:149]
	global_store_dwordx2 v[28:29], v[30:31], off offset:512
	v_lshl_add_u64 v[28:29], v[26:27], 0, v[148:149]
	global_store_dwordx2 v[12:13], v[14:15], off offset:512
	v_lshl_add_u64 v[12:13], v[10:11], 0, v[148:149]
	v_cvt_pk_bf16_f32 v9, v8, v9
	v_cvt_pk_bf16_f32 v8, v6, v7
	v_lshl_add_u64 v[6:7], v[10:11], 0, v[150:151]
	v_cvt_pk_bf16_f32 v5, v4, v5
	v_cvt_pk_bf16_f32 v4, v2, v3
	s_and_b64 vcc, exec, s[4:5]
	s_mov_b32 s12, s0
	s_mov_b32 s28, s6
	s_mov_b64 s[16:17], s[10:11]
	s_mov_b64 s[14:15], s[8:9]
	global_store_dwordx2 v[68:69], v[64:65], off offset:512
	global_store_dwordx2 v[62:63], v[60:61], off offset:512
	global_store_dwordx2 v[58:59], v[52:53], off offset:512
	global_store_dwordx2 v[44:45], v[32:33], off offset:512
	global_store_dwordx2 v[28:29], v[16:17], off offset:512
	global_store_dwordx2 v[12:13], v[8:9], off offset:512
	global_store_dwordx2 v[6:7], v[4:5], off offset:512
	s_cbranch_vccz .LBB0_1081
	s_waitcnt vmcnt(0)
	s_cmpk_gt_u32 s2, 0xff
	s_movk_i32 s21, 0x210
	s_mov_b32 s26, 0x2aaaaaab
	s_movk_i32 s27, 0xff40
	s_cbranch_scc1 .LBB0_1092
	s_barrier

; #define PG8_STAGE(bufoff, gbase, voff) do { _Pragma("unroll") for (int _i = 0; _i < 2; ++_i) \
;     __builtin_amdgcn_global_load_lds((const unsigned*)((const char*)(gbase) + (voff)[_i]), (PG8_LAS unsigned*)(lds + (bufoff) + ldsw + _i * 8192), 16, 0, 0); } while (0)
; #define PG8_LDA(dst, b, h) do { _Pragma("unroll") for (int m = 0; m < 4; ++m) _Pragma("unroll") for (int k = 0; k < 2; ++k) dst[m][k] = *(const PG8_LAS bf16x8*)(lds + PG8_SA(b, h) + aoff + m * 2048 + k * 1024); } while (0)
; #define PG8_LDB(dst, b, h) do { _Pragma("unroll") for (int n = 0; n < 2; ++n) _Pragma("unroll") for (int k = 0; k < 2; ++k) dst[n][k] = *(const PG8_LAS bf16x8*)(lds + PG8_SB(b, h) + boff + n * 2048 + k * 1024); } while (0)
; #define PG8_MMA(ai, bj, At, Bt) do { __builtin_amdgcn_s_setprio(1); _Pragma("unroll") for (int m = 0; m < 4; ++m) _Pragma("unroll") for (int n = 0; n < 2; ++n) _Pragma("unroll") for (int k = 0; k < 2; ++k) \
;     acc[ai][bj][m][n] = __builtin_amdgcn_mfma_f32_16x16x32_bf16(Bt[n][k], At[m][k], acc[ai][bj][m][n], 0, 0, 0); __builtin_amdgcn_s_setprio(0); } while (0)
; #define PG8_WAIT_L(n) asm volatile("s_waitcnt lgkmcnt(" #n ")" ::: "memory")
; #define PG8_BAR __builtin_amdgcn_s_barrier()
; #define PG8_SCHED __builtin_amdgcn_sched_barrier(0)
; template <class Epi, class Sched>
; __device__ __forceinline__ void gemm_phase(PG8_LAS unsigned char* lds, const int lda, const int ldb, const Sched& S, const Epi& E) {
;     ...
;       PG8_LDB(B0, 0, 0); PG8_SCHED; PG8_LDA(At, 0, 0); PG8_STAGE(PG8_SA(1, 1), a1 + hstepA, voffA);
;       PG8_WAIT_L(8); PG8_BAR; PG8_WAIT_L(0); PG8_MMA(0, 0, At, B0); PG8_BAR; PG8_SCHED;
;       PG8_LDB(B1, 0, 1); PG8_STAGE(PG8_SB(0, 0), b2, voffB);
;       PG8_BAR; PG8_WAIT_L(0); PG8_MMA(0, 1, At, B1); PG8_BAR;
;       PG8_LDA(At, 0, 1); PG8_STAGE(PG8_SA(0, 0), a2, voffA);
;       PG8_BAR; PG8_WAIT_L(0); PG8_MMA(1, 0, At, B0); PG8_BAR; PG8_SCHED;
.LBB0_1412:
	s_add_i32 s33, s18, 2
	s_add_u32 s19, s14, 0xfffc0080
	s_addc_u32 s20, s15, -1
	s_add_i32 s44, 0, 0x10000
	v_add_u32_e32 v152, s44, v131
	ds_read_b128 v[140:143], v152
	ds_read_b128 v[144:147], v152 offset:1024
	ds_read_b128 v[148:151], v152 offset:2048
	ds_read_b128 v[152:155], v152 offset:3072
	s_cmp_eq_u32 s11, s18
	s_cselect_b32 s18, s12, s22
	s_cselect_b32 s21, s7, s20
	s_cselect_b32 s20, s6, s19
	s_cselect_b32 s19, s13, s23
	v_lshl_add_u64 v[182:183], s[14:15], 0, v[136:137]
	s_add_i32 m0, s17, 0xc000
	ds_read_b128 v[156:159], v201
	ds_read_b128 v[160:163], v201 offset:1024
	ds_read_b128 v[164:167], v201 offset:2048
	ds_read_b128 v[168:171], v201 offset:3072
	ds_read_b128 v[172:175], v201 offset:4096
	ds_read_b128 v[202:205], v201 offset:5120
	ds_read_b128 v[206:209], v201 offset:6144
	ds_read_b128 v[210:213], v201 offset:7168
	global_load_lds_dwordx4 v[182:183], off
	v_lshl_add_u64 v[182:183], s[14:15], 0, v[138:139]
	s_add_i32 m0, s17, 0xe000
	s_nop 0
	global_load_lds_dwordx4 v[182:183], off
	s_waitcnt lgkmcnt(8)
	s_barrier
	s_waitcnt lgkmcnt(0)
	v_mfma_f32_16x16x32_bf16 v[126:129], v[140:143], v[156:159], v[126:129]
	v_mfma_f32_16x16x32_bf16 v[122:125], v[148:151], v[156:159], v[122:125]
	v_mfma_f32_16x16x32_bf16 v[118:121], v[140:143], v[164:167], v[118:121]
	v_mfma_f32_16x16x32_bf16 v[114:117], v[148:151], v[164:167], v[114:117]
	v_mfma_f32_16x16x32_bf16 v[110:113], v[140:143], v[172:175], v[110:113]
	v_mfma_f32_16x16x32_bf16 v[106:109], v[148:151], v[172:175], v[106:109]
	v_mfma_f32_16x16x32_bf16 v[102:105], v[140:143], v[206:209], v[102:105]
	v_mfma_f32_16x16x32_bf16 v[98:101], v[148:151], v[206:209], v[98:101]
	v_mfma_f32_16x16x32_bf16 v[126:129], v[144:147], v[160:163], v[126:129]
	v_mfma_f32_16x16x32_bf16 v[122:125], v[152:155], v[160:163], v[122:125]
	v_mfma_f32_16x16x32_bf16 v[118:121], v[144:147], v[168:171], v[118:121]
	v_mfma_f32_16x16x32_bf16 v[114:117], v[152:155], v[168:171], v[114:117]
	v_mfma_f32_16x16x32_bf16 v[110:113], v[144:147], v[202:205], v[110:113]
	v_mfma_f32_16x16x32_bf16 v[106:109], v[152:155], v[202:205], v[106:109]
	v_mfma_f32_16x16x32_bf16 v[102:105], v[144:147], v[210:213], v[102:105]
	v_mfma_f32_16x16x32_bf16 v[98:101], v[152:155], v[210:213], v[98:101]
	s_barrier
	s_add_i32 s46, 0, 0x14000
	v_add_u32_e32 v182, s46, v131
	s_add_i32 s44, s44, s29
	ds_read_b128 v[214:217], v182
	ds_read_b128 v[218:221], v182 offset:1024
	ds_read_b128 v[222:225], v182 offset:2048
	ds_read_b128 v[226:229], v182 offset:3072
	v_lshl_add_u64 v[182:183], s[18:19], 0, v[134:135]
	s_mov_b32 m0, s44
	v_lshl_add_u64 v[184:185], s[18:19], 0, v[132:133]
	global_load_lds_dwordx4 v[182:183], off
	s_add_i32 m0, s44, 0x2000
	s_nop 0
	global_load_lds_dwordx4 v[184:185], off
	s_barrier
	s_waitcnt lgkmcnt(0)
	v_mfma_f32_16x16x32_bf16 v[94:97], v[214:217], v[156:159], v[94:97]
	v_mfma_f32_16x16x32_bf16 v[90:93], v[222:225], v[156:159], v[90:93]
	v_mfma_f32_16x16x32_bf16 v[86:89], v[214:217], v[164:167], v[86:89]
	v_mfma_f32_16x16x32_bf16 v[82:85], v[222:225], v[164:167], v[82:85]
	v_mfma_f32_16x16x32_bf16 v[78:81], v[214:217], v[172:175], v[78:81]
	v_mfma_f32_16x16x32_bf16 v[74:77], v[222:225], v[172:175], v[74:77]
	v_mfma_f32_16x16x32_bf16 v[70:73], v[214:217], v[206:209], v[70:73]
	v_mfma_f32_16x16x32_bf16 v[66:69], v[222:225], v[206:209], v[66:69]
	v_mfma_f32_16x16x32_bf16 v[94:97], v[218:221], v[160:163], v[94:97]
	v_mfma_f32_16x16x32_bf16 v[90:93], v[226:229], v[160:163], v[90:93]
	v_mfma_f32_16x16x32_bf16 v[86:89], v[218:221], v[168:171], v[86:89]
	v_mfma_f32_16x16x32_bf16 v[82:85], v[226:229], v[168:171], v[82:85]
	v_mfma_f32_16x16x32_bf16 v[78:81], v[218:221], v[202:205], v[78:81]
	v_mfma_f32_16x16x32_bf16 v[74:77], v[226:229], v[202:205], v[74:77]
	v_mfma_f32_16x16x32_bf16 v[70:73], v[218:221], v[210:213], v[70:73]
	v_mfma_f32_16x16x32_bf16 v[66:69], v[226:229], v[210:213], v[66:69]
	s_barrier
	s_mov_b32 m0, s17
	v_lshl_add_u64 v[230:231], s[20:21], 0, v[134:135]
	ds_read_b128 v[156:159], v201 offset:16384
	ds_read_b128 v[160:163], v201 offset:17408
	ds_read_b128 v[164:167], v201 offset:18432
	ds_read_b128 v[168:171], v201 offset:19456
	ds_read_b128 v[172:175], v201 offset:20480
	ds_read_b128 v[202:205], v201 offset:21504
	ds_read_b128 v[206:209], v201 offset:22528
	ds_read_b128 v[210:213], v201 offset:23552
	global_load_lds_dwordx4 v[230:231], off
	v_lshl_add_u64 v[232:233], s[20:21], 0, v[132:133]
	s_mov_b32 m0, s34
	s_nop 0
	global_load_lds_dwordx4 v[232:233], off
	s_barrier
	s_waitcnt lgkmcnt(0)
	v_mfma_f32_16x16x32_bf16 v[62:65], v[140:143], v[156:159], v[62:65]
	v_mfma_f32_16x16x32_bf16 v[58:61], v[148:151], v[156:159], v[58:61]
	v_mfma_f32_16x16x32_bf16 v[54:57], v[140:143], v[164:167], v[54:57]
	v_mfma_f32_16x16x32_bf16 v[50:53], v[148:151], v[164:167], v[50:53]
	v_mfma_f32_16x16x32_bf16 v[46:49], v[140:143], v[172:175], v[46:49]
	v_mfma_f32_16x16x32_bf16 v[42:45], v[148:151], v[172:175], v[42:45]
	v_mfma_f32_16x16x32_bf16 v[38:41], v[140:143], v[206:209], v[38:41]
	v_mfma_f32_16x16x32_bf16 v[34:37], v[148:151], v[206:209], v[34:37]
	v_mfma_f32_16x16x32_bf16 v[62:65], v[144:147], v[160:163], v[62:65]
	v_mfma_f32_16x16x32_bf16 v[58:61], v[152:155], v[160:163], v[58:61]
	v_mfma_f32_16x16x32_bf16 v[54:57], v[144:147], v[168:171], v[54:57]
	v_mfma_f32_16x16x32_bf16 v[50:53], v[152:155], v[168:171], v[50:53]
	v_mfma_f32_16x16x32_bf16 v[46:49], v[144:147], v[202:205], v[46:49]
	v_mfma_f32_16x16x32_bf16 v[42:45], v[152:155], v[202:205], v[42:45]
	v_mfma_f32_16x16x32_bf16 v[38:41], v[144:147], v[210:213], v[38:41]
	v_mfma_f32_16x16x32_bf16 v[34:37], v[152:155], v[210:213], v[34:37]
	s_barrier
; #define PG8_STAGE(bufoff, gbase, voff) do { _Pragma("unroll") for (int _i = 0; _i < 2; ++_i) \
;     __builtin_amdgcn_global_load_lds((const unsigned*)((const char*)(gbase) + (voff)[_i]), (PG8_LAS unsigned*)(lds + (bufoff) + ldsw + _i * 8192), 16, 0, 0); } while (0)
; #define PG8_LDA(dst, b, h) do { _Pragma("unroll") for (int m = 0; m < 4; ++m) _Pragma("unroll") for (int k = 0; k < 2; ++k) dst[m][k] = *(const PG8_LAS bf16x8*)(lds + PG8_SA(b, h) + aoff + m * 2048 + k * 1024); } while (0)
; #define PG8_LDB(dst, b, h) do { _Pragma("unroll") for (int n = 0; n < 2; ++n) _Pragma("unroll") for (int k = 0; k < 2; ++k) dst[n][k] = *(const PG8_LAS bf16x8*)(lds + PG8_SB(b, h) + boff + n * 2048 + k * 1024); } while (0)
; #define PG8_MMA(ai, bj, At, Bt) do { __builtin_amdgcn_s_setprio(1); _Pragma("unroll") for (int m = 0; m < 4; ++m) _Pragma("unroll") for (int n = 0; n < 2; ++n) _Pragma("unroll") for (int k = 0; k < 2; ++k) \
;     acc[ai][bj][m][n] = __builtin_amdgcn_mfma_f32_16x16x32_bf16(Bt[n][k], At[m][k], acc[ai][bj][m][n], 0, 0, 0); __builtin_amdgcn_s_setprio(0); } while (0)
; #define PG8_WAIT_V(n) asm volatile("s_waitcnt vmcnt(" #n ")" ::: "memory")
; #define PG8_WAIT_L(n) asm volatile("s_waitcnt lgkmcnt(" #n ")" ::: "memory")
; #define PG8_BAR __builtin_amdgcn_s_barrier()
; #define PG8_SCHED __builtin_amdgcn_sched_barrier(0)
; template <class Epi, class Sched>
; __device__ __forceinline__ void gemm_phase(PG8_LAS unsigned char* lds, const int lda, const int ldb, const Sched& S, const Epi& E) {
;     ...
;       PG8_STAGE(PG8_SB(0, 1), b2 + hstepB, voffB);
;       PG8_WAIT_V(6); PG8_BAR; PG8_MMA(1, 1, At, B1); PG8_BAR;
;       PG8_LDB(B0, 1, 0); PG8_SCHED; PG8_LDA(At, 1, 0); PG8_STAGE(PG8_SA(0, 1), a2 + hstepA, voffA);
;       PG8_WAIT_L(8); PG8_BAR; PG8_WAIT_L(0); PG8_MMA(0, 0, At, B0); PG8_BAR; PG8_SCHED;
;       PG8_LDB(B1, 1, 1); PG8_STAGE(PG8_SB(1, 0), b3, voffB);
;       PG8_BAR; PG8_WAIT_L(0); PG8_MMA(0, 1, At, B1); PG8_BAR;
;       PG8_LDA(At, 1, 1); PG8_STAGE(PG8_SA(1, 0), a3, voffA);
	s_add_u32 s44, s18, 0x40000
	s_addc_u32 s45, s19, 0
	s_add_i32 s46, s46, s29
	v_lshl_add_u64 v[140:141], s[44:45], 0, v[134:135]
	s_mov_b32 m0, s46
	s_nop 0
	global_load_lds_dwordx4 v[140:141], off
	v_lshl_add_u64 v[140:141], s[44:45], 0, v[132:133]
	s_add_i32 m0, s46, 0x2000
	s_nop 0
	global_load_lds_dwordx4 v[140:141], off
	s_waitcnt vmcnt(6)
	s_barrier
	v_mfma_f32_16x16x32_bf16 v[30:33], v[214:217], v[156:159], v[30:33]
	v_mfma_f32_16x16x32_bf16 v[26:29], v[222:225], v[156:159], v[26:29]
	v_mfma_f32_16x16x32_bf16 v[22:25], v[214:217], v[164:167], v[22:25]
	v_mfma_f32_16x16x32_bf16 v[18:21], v[222:225], v[164:167], v[18:21]
	v_mfma_f32_16x16x32_bf16 v[14:17], v[214:217], v[172:175], v[14:17]
	v_mfma_f32_16x16x32_bf16 v[10:13], v[222:225], v[172:175], v[10:13]
	v_mfma_f32_16x16x32_bf16 v[6:9], v[214:217], v[206:209], v[6:9]
	v_mfma_f32_16x16x32_bf16 v[2:5], v[222:225], v[206:209], v[2:5]
	v_mfma_f32_16x16x32_bf16 v[30:33], v[218:221], v[160:163], v[30:33]
	v_mfma_f32_16x16x32_bf16 v[26:29], v[226:229], v[160:163], v[26:29]
	v_mfma_f32_16x16x32_bf16 v[22:25], v[218:221], v[168:171], v[22:25]
	v_mfma_f32_16x16x32_bf16 v[18:21], v[226:229], v[168:171], v[18:21]
	v_mfma_f32_16x16x32_bf16 v[14:17], v[218:221], v[202:205], v[14:17]
	v_mfma_f32_16x16x32_bf16 v[10:13], v[226:229], v[202:205], v[10:13]
	v_mfma_f32_16x16x32_bf16 v[6:9], v[218:221], v[210:213], v[6:9]
	v_mfma_f32_16x16x32_bf16 v[2:5], v[226:229], v[210:213], v[2:5]
	s_barrier
	s_add_i32 s44, 0, 0x18000
	v_add_u32_e32 v152, s44, v131
	ds_read_b128 v[140:143], v152
	ds_read_b128 v[144:147], v152 offset:1024
	ds_read_b128 v[148:151], v152 offset:2048
	ds_read_b128 v[152:155], v152 offset:3072
	s_add_u32 s20, s20, 0x40000
	s_addc_u32 s21, s21, 0
	s_mov_b32 m0, s35
	v_lshl_add_u64 v[214:215], s[20:21], 0, v[134:135]
	ds_read_b128 v[156:159], v201 offset:32768
	ds_read_b128 v[160:163], v201 offset:33792
	ds_read_b128 v[164:167], v201 offset:34816
	ds_read_b128 v[168:171], v201 offset:35840
	ds_read_b128 v[172:175], v201 offset:36864
	ds_read_b128 v[202:205], v201 offset:37888
	ds_read_b128 v[206:209], v201 offset:38912
	ds_read_b128 v[210:213], v201 offset:39936
	global_load_lds_dwordx4 v[214:215], off
	v_lshl_add_u64 v[214:215], s[20:21], 0, v[132:133]
	s_mov_b32 m0, s36
	s_nop 0
	global_load_lds_dwordx4 v[214:215], off
	s_waitcnt lgkmcnt(8)
	s_barrier
	s_waitcnt lgkmcnt(0)
	v_mfma_f32_16x16x32_bf16 v[126:129], v[140:143], v[156:159], v[126:129]
	v_mfma_f32_16x16x32_bf16 v[122:125], v[148:151], v[156:159], v[122:125]
	v_mfma_f32_16x16x32_bf16 v[118:121], v[140:143], v[164:167], v[118:121]
	v_mfma_f32_16x16x32_bf16 v[114:117], v[148:151], v[164:167], v[114:117]
	v_mfma_f32_16x16x32_bf16 v[110:113], v[140:143], v[172:175], v[110:113]
	v_mfma_f32_16x16x32_bf16 v[106:109], v[148:151], v[172:175], v[106:109]
	v_mfma_f32_16x16x32_bf16 v[102:105], v[140:143], v[206:209], v[102:105]
	v_mfma_f32_16x16x32_bf16 v[98:101], v[148:151], v[206:209], v[98:101]
	v_mfma_f32_16x16x32_bf16 v[126:129], v[144:147], v[160:163], v[126:129]
	v_mfma_f32_16x16x32_bf16 v[122:125], v[152:155], v[160:163], v[122:125]
	v_mfma_f32_16x16x32_bf16 v[118:121], v[144:147], v[168:171], v[118:121]
	v_mfma_f32_16x16x32_bf16 v[114:117], v[152:155], v[168:171], v[114:117]
	v_mfma_f32_16x16x32_bf16 v[110:113], v[144:147], v[202:205], v[110:113]
	v_mfma_f32_16x16x32_bf16 v[106:109], v[152:155], v[202:205], v[106:109]
	v_mfma_f32_16x16x32_bf16 v[102:105], v[144:147], v[210:213], v[102:105]
	v_mfma_f32_16x16x32_bf16 v[98:101], v[152:155], v[210:213], v[98:101]
	s_barrier
	s_add_i32 s20, 0, 0x1c000
	s_add_i32 s21, s44, s29
	v_add_u32_e32 v226, s20, v131
	v_lshl_add_u64 v[182:183], v[182:183], 0, s[86:87]
	s_mov_b32 m0, s21
	ds_read_b128 v[214:217], v226
	ds_read_b128 v[218:221], v226 offset:1024
	ds_read_b128 v[222:225], v226 offset:2048
	ds_read_b128 v[226:229], v226 offset:3072
	global_load_lds_dwordx4 v[182:183], off
	v_lshl_add_u64 v[182:183], v[184:185], 0, s[86:87]
	s_add_i32 m0, s21, 0x2000
	s_nop 0
	global_load_lds_dwordx4 v[182:183], off
	s_barrier
; __device__ __forceinline__ int tid_l() { int t = threadIdx.x; asm volatile("" : "+v"(t)); return t; }
; #define PG8_STAGE(bufoff, gbase, voff) do { _Pragma("unroll") for (int _i = 0; _i < 2; ++_i) \
;     __builtin_amdgcn_global_load_lds((const unsigned*)((const char*)(gbase) + (voff)[_i]), (PG8_LAS unsigned*)(lds + (bufoff) + ldsw + _i * 8192), 16, 0, 0); } while (0)
; #define PG8_LDA(dst, b, h) do { _Pragma("unroll") for (int m = 0; m < 4; ++m) _Pragma("unroll") for (int k = 0; k < 2; ++k) dst[m][k] = *(const PG8_LAS bf16x8*)(lds + PG8_SA(b, h) + aoff + m * 2048 + k * 1024); } while (0)
; #define PG8_MMA(ai, bj, At, Bt) do { __builtin_amdgcn_s_setprio(1); _Pragma("unroll") for (int m = 0; m < 4; ++m) _Pragma("unroll") for (int n = 0; n < 2; ++n) _Pragma("unroll") for (int k = 0; k < 2; ++k) \
;     acc[ai][bj][m][n] = __builtin_amdgcn_mfma_f32_16x16x32_bf16(Bt[n][k], At[m][k], acc[ai][bj][m][n], 0, 0, 0); __builtin_amdgcn_s_setprio(0); } while (0)
; #define PG8_WAIT_V(n) asm volatile("s_waitcnt vmcnt(" #n ")" ::: "memory")
; #define PG8_WAIT_L(n) asm volatile("s_waitcnt lgkmcnt(" #n ")" ::: "memory")
; #define PG8_BAR __builtin_amdgcn_s_barrier()
; #define PG8_SCHED __builtin_amdgcn_sched_barrier(0)
; template <class Epi, class Sched>
; __device__ __forceinline__ void gemm_phase(PG8_LAS unsigned char* lds, const int lda, const int ldb, const Sched& S, const Epi& E) {
;     ...
;       PG8_BAR; PG8_WAIT_L(0); PG8_MMA(0, 1, At, B1); PG8_BAR;
;       PG8_LDA(At, 1, 1); PG8_STAGE(PG8_SA(1, 0), a3, voffA);
;       PG8_BAR; PG8_WAIT_L(0); PG8_MMA(1, 0, At, B0); PG8_BAR; PG8_SCHED;
;       PG8_STAGE(PG8_SB(1, 1), b3 + hstepB, voffB);
;       PG8_WAIT_V(6); PG8_BAR; PG8_MMA(1, 1, At, B1); PG8_BAR;
;   __device__ __forceinline__ void operator()(const f32x4 (&acc)[2][2][4][2], const Unit& u, int wr, int wc, int fr, int fq) const {
;     const int s = u.pn & 7, dq = u.pn >> 3;
;     const int tid = tid_l();
;     if (s < 4) {
	s_waitcnt lgkmcnt(0)
	v_mfma_f32_16x16x32_bf16 v[94:97], v[214:217], v[156:159], v[94:97]
	v_mfma_f32_16x16x32_bf16 v[90:93], v[222:225], v[156:159], v[90:93]
	v_mfma_f32_16x16x32_bf16 v[86:89], v[214:217], v[164:167], v[86:89]
	v_mfma_f32_16x16x32_bf16 v[82:85], v[222:225], v[164:167], v[82:85]
	v_mfma_f32_16x16x32_bf16 v[78:81], v[214:217], v[172:175], v[78:81]
	v_mfma_f32_16x16x32_bf16 v[74:77], v[222:225], v[172:175], v[74:77]
	v_mfma_f32_16x16x32_bf16 v[70:73], v[214:217], v[206:209], v[70:73]
	v_mfma_f32_16x16x32_bf16 v[66:69], v[222:225], v[206:209], v[66:69]
	v_mfma_f32_16x16x32_bf16 v[94:97], v[218:221], v[160:163], v[94:97]
	v_mfma_f32_16x16x32_bf16 v[90:93], v[226:229], v[160:163], v[90:93]
	v_mfma_f32_16x16x32_bf16 v[86:89], v[218:221], v[168:171], v[86:89]
	v_mfma_f32_16x16x32_bf16 v[82:85], v[226:229], v[168:171], v[82:85]
	v_mfma_f32_16x16x32_bf16 v[78:81], v[218:221], v[202:205], v[78:81]
	v_mfma_f32_16x16x32_bf16 v[74:77], v[226:229], v[202:205], v[74:77]
	v_mfma_f32_16x16x32_bf16 v[70:73], v[218:221], v[210:213], v[70:73]
	v_mfma_f32_16x16x32_bf16 v[66:69], v[226:229], v[210:213], v[66:69]
	s_barrier
	s_mov_b32 m0, s39
	v_lshl_add_u64 v[182:183], v[230:231], 0, s[86:87]
	ds_read_b128 v[156:159], v201 offset:49152
	ds_read_b128 v[160:163], v201 offset:50176
	ds_read_b128 v[164:167], v201 offset:51200
	ds_read_b128 v[168:171], v201 offset:52224
	ds_read_b128 v[172:175], v201 offset:53248
	ds_read_b128 v[202:205], v201 offset:54272
	ds_read_b128 v[206:209], v201 offset:55296
	ds_read_b128 v[210:213], v201 offset:56320
	global_load_lds_dwordx4 v[182:183], off
	v_lshl_add_u64 v[182:183], v[232:233], 0, s[86:87]
	s_mov_b32 m0, s40
	s_nop 0
	global_load_lds_dwordx4 v[182:183], off
	s_barrier
	s_waitcnt lgkmcnt(0)
	v_mfma_f32_16x16x32_bf16 v[62:65], v[140:143], v[156:159], v[62:65]
	v_mfma_f32_16x16x32_bf16 v[58:61], v[148:151], v[156:159], v[58:61]
	v_mfma_f32_16x16x32_bf16 v[54:57], v[140:143], v[164:167], v[54:57]
	v_mfma_f32_16x16x32_bf16 v[50:53], v[148:151], v[164:167], v[50:53]
	v_mfma_f32_16x16x32_bf16 v[46:49], v[140:143], v[172:175], v[46:49]
	v_mfma_f32_16x16x32_bf16 v[42:45], v[148:151], v[172:175], v[42:45]
	v_mfma_f32_16x16x32_bf16 v[38:41], v[140:143], v[206:209], v[38:41]
	v_mfma_f32_16x16x32_bf16 v[34:37], v[148:151], v[206:209], v[34:37]
	v_mfma_f32_16x16x32_bf16 v[62:65], v[144:147], v[160:163], v[62:65]
	v_mfma_f32_16x16x32_bf16 v[58:61], v[152:155], v[160:163], v[58:61]
	v_mfma_f32_16x16x32_bf16 v[54:57], v[144:147], v[168:171], v[54:57]
	v_mfma_f32_16x16x32_bf16 v[50:53], v[152:155], v[168:171], v[50:53]
	v_mfma_f32_16x16x32_bf16 v[46:49], v[144:147], v[202:205], v[46:49]
	v_mfma_f32_16x16x32_bf16 v[42:45], v[152:155], v[202:205], v[42:45]
	v_mfma_f32_16x16x32_bf16 v[38:41], v[144:147], v[210:213], v[38:41]
	v_mfma_f32_16x16x32_bf16 v[34:37], v[152:155], v[210:213], v[34:37]
	s_barrier
	s_add_u32 s18, s18, 0x40080
	s_addc_u32 s19, s19, 0
	s_add_i32 s20, s20, s29
	v_lshl_add_u64 v[140:141], s[18:19], 0, v[134:135]
	s_mov_b32 m0, s20
	s_nop 0
	global_load_lds_dwordx4 v[140:141], off
	v_lshl_add_u64 v[140:141], s[18:19], 0, v[132:133]
	s_add_i32 m0, s20, 0x2000
	s_nop 0
	global_load_lds_dwordx4 v[140:141], off
	s_waitcnt vmcnt(6)
	s_barrier
	v_mfma_f32_16x16x32_bf16 v[30:33], v[214:217], v[156:159], v[30:33]
	v_mfma_f32_16x16x32_bf16 v[26:29], v[222:225], v[156:159], v[26:29]
	v_mfma_f32_16x16x32_bf16 v[22:25], v[214:217], v[164:167], v[22:25]
	v_mfma_f32_16x16x32_bf16 v[18:21], v[222:225], v[164:167], v[18:21]
	v_mfma_f32_16x16x32_bf16 v[14:17], v[214:217], v[172:175], v[14:17]
	v_mfma_f32_16x16x32_bf16 v[10:13], v[222:225], v[172:175], v[10:13]
	v_mfma_f32_16x16x32_bf16 v[6:9], v[214:217], v[206:209], v[6:9]
	v_mfma_f32_16x16x32_bf16 v[2:5], v[222:225], v[206:209], v[2:5]
	v_mfma_f32_16x16x32_bf16 v[30:33], v[218:221], v[160:163], v[30:33]
	v_mfma_f32_16x16x32_bf16 v[26:29], v[226:229], v[160:163], v[26:29]
	v_mfma_f32_16x16x32_bf16 v[22:25], v[218:221], v[168:171], v[22:25]
	v_mfma_f32_16x16x32_bf16 v[18:21], v[226:229], v[168:171], v[18:21]
	v_mfma_f32_16x16x32_bf16 v[14:17], v[218:221], v[202:205], v[14:17]
	v_mfma_f32_16x16x32_bf16 v[10:13], v[226:229], v[202:205], v[10:13]
	v_mfma_f32_16x16x32_bf16 v[6:9], v[218:221], v[210:213], v[6:9]
	v_mfma_f32_16x16x32_bf16 v[2:5], v[226:229], v[210:213], v[2:5]
	s_add_u32 s14, s14, 0x100
	s_addc_u32 s15, s15, 0
	s_add_u32 s22, s22, 0x100
	s_addc_u32 s23, s23, 0
	s_cmp_ge_u32 s33, s43
	s_mov_b32 s18, s33
	s_barrier
	s_cbranch_scc0 .LBB0_1412
	s_and_b32 s11, s2, 7
	v_mov_b32_e32 v140, v176
	s_mov_b64 s[14:15], -1
	s_cmp_gt_u32 s11, 3
	v_ashrrev_i32_e32 v141, 31, v140
	s_cbranch_scc1 .LBB0_1416
	s_andn2_b64 vcc, exec, s[14:15]
	s_cbranch_vccz .LBB0_1417

; #define PG8_STAGE(bufoff, gbase, voff) do { _Pragma("unroll") for (int _i = 0; _i < 2; ++_i) \
;     __builtin_amdgcn_global_load_lds((const unsigned*)((const char*)(gbase) + (voff)[_i]), (PG8_LAS unsigned*)(lds + (bufoff) + ldsw + _i * 8192), 16, 0, 0); } while (0)
; #define PG8_LDA(dst, b, h) do { _Pragma("unroll") for (int m = 0; m < 4; ++m) _Pragma("unroll") for (int k = 0; k < 2; ++k) dst[m][k] = *(const PG8_LAS bf16x8*)(lds + PG8_SA(b, h) + aoff + m * 2048 + k * 1024); } while (0)
; #define PG8_LDB(dst, b, h) do { _Pragma("unroll") for (int n = 0; n < 2; ++n) _Pragma("unroll") for (int k = 0; k < 2; ++k) dst[n][k] = *(const PG8_LAS bf16x8*)(lds + PG8_SB(b, h) + boff + n * 2048 + k * 1024); } while (0)
; #define PG8_MMA(ai, bj, At, Bt) do { __builtin_amdgcn_s_setprio(1); _Pragma("unroll") for (int m = 0; m < 4; ++m) _Pragma("unroll") for (int n = 0; n < 2; ++n) _Pragma("unroll") for (int k = 0; k < 2; ++k) \
;     acc[ai][bj][m][n] = __builtin_amdgcn_mfma_f32_16x16x32_bf16(Bt[n][k], At[m][k], acc[ai][bj][m][n], 0, 0, 0); __builtin_amdgcn_s_setprio(0); } while (0)
; #define PG8_WAIT_L(n) asm volatile("s_waitcnt lgkmcnt(" #n ")" ::: "memory")
; #define PG8_BAR __builtin_amdgcn_s_barrier()
; #define PG8_SCHED __builtin_amdgcn_sched_barrier(0)
; template <class Epi, class Sched>
; __device__ __forceinline__ void gemm_phase(PG8_LAS unsigned char* lds, const int lda, const int ldb, const Sched& S, const Epi& E) {
;     ...
;       PG8_LDB(B0, 0, 0); PG8_SCHED; PG8_LDA(At, 0, 0); PG8_STAGE(PG8_SA(1, 1), a1 + hstepA, voffA);
;       PG8_WAIT_L(8); PG8_BAR; PG8_WAIT_L(0); PG8_MMA(0, 0, At, B0); PG8_BAR; PG8_SCHED;
;       PG8_LDB(B1, 0, 1); PG8_STAGE(PG8_SB(0, 0), b2, voffB);
;       PG8_BAR; PG8_WAIT_L(0); PG8_MMA(0, 1, At, B1); PG8_BAR;
;       PG8_LDA(At, 0, 1); PG8_STAGE(PG8_SA(0, 0), a2, voffA);
;       PG8_BAR; PG8_WAIT_L(0); PG8_MMA(1, 0, At, B0); PG8_BAR; PG8_SCHED;
.LBB0_1482:
	s_add_u32 s20, s18, 0x100
	s_addc_u32 s21, s19, 0
	s_add_i32 s33, 0, 0x10000
	v_add_u32_e32 v154, s33, v131
	ds_read_b128 v[140:143], v154
	ds_read_b128 v[146:149], v154 offset:1024
	ds_read_b128 v[150:153], v154 offset:2048
	ds_read_b128 v[154:157], v154 offset:3072
	s_cmp_eq_u32 s54, 12
	s_cselect_b32 s25, s11, s21
	s_cselect_b32 s24, s50, s20
	s_cselect_b32 s23, s1, s53
	s_cselect_b32 s22, s51, s52
	v_lshl_add_u64 v[174:175], s[18:19], 0, v[136:137]
	s_add_i32 m0, s17, 0xc000
	ds_read_b128 v[158:161], v145
	ds_read_b128 v[162:165], v145 offset:1024
	ds_read_b128 v[166:169], v145 offset:2048
	ds_read_b128 v[170:173], v145 offset:3072
	ds_read_b128 v[200:203], v145 offset:4096
	ds_read_b128 v[204:207], v145 offset:5120
	ds_read_b128 v[208:211], v145 offset:6144
	ds_read_b128 v[212:215], v145 offset:7168
	global_load_lds_dwordx4 v[174:175], off
	v_lshl_add_u64 v[174:175], s[18:19], 0, v[138:139]
	s_add_i32 m0, s17, 0xe000
	s_nop 0
	global_load_lds_dwordx4 v[174:175], off
	s_waitcnt lgkmcnt(8)
	s_barrier
	s_waitcnt lgkmcnt(0)
	v_mfma_f32_16x16x32_bf16 v[126:129], v[140:143], v[158:161], v[126:129]
	v_mfma_f32_16x16x32_bf16 v[122:125], v[150:153], v[158:161], v[122:125]
	v_mfma_f32_16x16x32_bf16 v[110:113], v[140:143], v[166:169], v[110:113]
	v_mfma_f32_16x16x32_bf16 v[106:109], v[150:153], v[166:169], v[106:109]
	v_mfma_f32_16x16x32_bf16 v[94:97], v[140:143], v[200:203], v[94:97]
	v_mfma_f32_16x16x32_bf16 v[90:93], v[150:153], v[200:203], v[90:93]
	v_mfma_f32_16x16x32_bf16 v[78:81], v[140:143], v[208:211], v[78:81]
	v_mfma_f32_16x16x32_bf16 v[74:77], v[150:153], v[208:211], v[74:77]
	v_mfma_f32_16x16x32_bf16 v[126:129], v[146:149], v[162:165], v[126:129]
	v_mfma_f32_16x16x32_bf16 v[122:125], v[154:157], v[162:165], v[122:125]
	v_mfma_f32_16x16x32_bf16 v[110:113], v[146:149], v[170:173], v[110:113]
	v_mfma_f32_16x16x32_bf16 v[106:109], v[154:157], v[170:173], v[106:109]
	v_mfma_f32_16x16x32_bf16 v[94:97], v[146:149], v[204:207], v[94:97]
	v_mfma_f32_16x16x32_bf16 v[90:93], v[154:157], v[204:207], v[90:93]
	v_mfma_f32_16x16x32_bf16 v[78:81], v[146:149], v[212:215], v[78:81]
	v_mfma_f32_16x16x32_bf16 v[74:77], v[154:157], v[212:215], v[74:77]
	s_barrier
	s_add_i32 s55, 0, 0x14000
	v_add_u32_e32 v174, s55, v131
	s_add_i32 s18, s33, s34
	ds_read_b128 v[216:219], v174
	ds_read_b128 v[220:223], v174 offset:1024
	ds_read_b128 v[224:227], v174 offset:2048
	ds_read_b128 v[228:231], v174 offset:3072
	v_lshl_add_u64 v[174:175], s[22:23], 0, v[134:135]
	s_mov_b32 m0, s18
	v_lshl_add_u64 v[182:183], s[22:23], 0, v[132:133]
	global_load_lds_dwordx4 v[174:175], off
	s_add_i32 m0, s18, 0x2000
	s_nop 0
	global_load_lds_dwordx4 v[182:183], off
	s_barrier
	s_waitcnt lgkmcnt(0)
	v_mfma_f32_16x16x32_bf16 v[118:121], v[216:219], v[158:161], v[118:121]
	v_mfma_f32_16x16x32_bf16 v[114:117], v[224:227], v[158:161], v[114:117]
	v_mfma_f32_16x16x32_bf16 v[102:105], v[216:219], v[166:169], v[102:105]
	v_mfma_f32_16x16x32_bf16 v[98:101], v[224:227], v[166:169], v[98:101]
	v_mfma_f32_16x16x32_bf16 v[86:89], v[216:219], v[200:203], v[86:89]
	v_mfma_f32_16x16x32_bf16 v[82:85], v[224:227], v[200:203], v[82:85]
	v_mfma_f32_16x16x32_bf16 v[70:73], v[216:219], v[208:211], v[70:73]
	v_mfma_f32_16x16x32_bf16 v[66:69], v[224:227], v[208:211], v[66:69]
	v_mfma_f32_16x16x32_bf16 v[118:121], v[220:223], v[162:165], v[118:121]
	v_mfma_f32_16x16x32_bf16 v[114:117], v[228:231], v[162:165], v[114:117]
	v_mfma_f32_16x16x32_bf16 v[102:105], v[220:223], v[170:173], v[102:105]
	v_mfma_f32_16x16x32_bf16 v[98:101], v[228:231], v[170:173], v[98:101]
	v_mfma_f32_16x16x32_bf16 v[86:89], v[220:223], v[204:207], v[86:89]
	v_mfma_f32_16x16x32_bf16 v[82:85], v[228:231], v[204:207], v[82:85]
	v_mfma_f32_16x16x32_bf16 v[70:73], v[220:223], v[212:215], v[70:73]
	v_mfma_f32_16x16x32_bf16 v[66:69], v[228:231], v[212:215], v[66:69]
	s_barrier
	s_mov_b32 m0, s17
	v_lshl_add_u64 v[184:185], s[24:25], 0, v[134:135]
	ds_read_b128 v[158:161], v145 offset:16384
	ds_read_b128 v[162:165], v145 offset:17408
	ds_read_b128 v[166:169], v145 offset:18432
	ds_read_b128 v[170:173], v145 offset:19456
	ds_read_b128 v[200:203], v145 offset:20480
	ds_read_b128 v[204:207], v145 offset:21504
	ds_read_b128 v[208:211], v145 offset:22528
	ds_read_b128 v[212:215], v145 offset:23552
	global_load_lds_dwordx4 v[184:185], off
	v_lshl_add_u64 v[232:233], s[24:25], 0, v[132:133]
	s_mov_b32 m0, s37
	s_nop 0
	global_load_lds_dwordx4 v[232:233], off
	s_barrier
	s_waitcnt lgkmcnt(0)
	v_mfma_f32_16x16x32_bf16 v[62:65], v[140:143], v[158:161], v[62:65]
	v_mfma_f32_16x16x32_bf16 v[58:61], v[150:153], v[158:161], v[58:61]
	v_mfma_f32_16x16x32_bf16 v[46:49], v[140:143], v[166:169], v[46:49]
	v_mfma_f32_16x16x32_bf16 v[42:45], v[150:153], v[166:169], v[42:45]
	v_mfma_f32_16x16x32_bf16 v[30:33], v[140:143], v[200:203], v[30:33]
	v_mfma_f32_16x16x32_bf16 v[26:29], v[150:153], v[200:203], v[26:29]
	v_mfma_f32_16x16x32_bf16 v[14:17], v[140:143], v[208:211], v[14:17]
	v_mfma_f32_16x16x32_bf16 v[10:13], v[150:153], v[208:211], v[10:13]
	v_mfma_f32_16x16x32_bf16 v[62:65], v[146:149], v[162:165], v[62:65]
	v_mfma_f32_16x16x32_bf16 v[58:61], v[154:157], v[162:165], v[58:61]
	v_mfma_f32_16x16x32_bf16 v[46:49], v[146:149], v[170:173], v[46:49]
	v_mfma_f32_16x16x32_bf16 v[42:45], v[154:157], v[170:173], v[42:45]
	v_mfma_f32_16x16x32_bf16 v[30:33], v[146:149], v[204:207], v[30:33]
	v_mfma_f32_16x16x32_bf16 v[26:29], v[154:157], v[204:207], v[26:29]
	v_mfma_f32_16x16x32_bf16 v[14:17], v[146:149], v[212:215], v[14:17]
	v_mfma_f32_16x16x32_bf16 v[10:13], v[154:157], v[212:215], v[10:13]
	s_barrier
; #define PG8_STAGE(bufoff, gbase, voff) do { _Pragma("unroll") for (int _i = 0; _i < 2; ++_i) \
;     __builtin_amdgcn_global_load_lds((const unsigned*)((const char*)(gbase) + (voff)[_i]), (PG8_LAS unsigned*)(lds + (bufoff) + ldsw + _i * 8192), 16, 0, 0); } while (0)
; #define PG8_LDA(dst, b, h) do { _Pragma("unroll") for (int m = 0; m < 4; ++m) _Pragma("unroll") for (int k = 0; k < 2; ++k) dst[m][k] = *(const PG8_LAS bf16x8*)(lds + PG8_SA(b, h) + aoff + m * 2048 + k * 1024); } while (0)
; #define PG8_LDB(dst, b, h) do { _Pragma("unroll") for (int n = 0; n < 2; ++n) _Pragma("unroll") for (int k = 0; k < 2; ++k) dst[n][k] = *(const PG8_LAS bf16x8*)(lds + PG8_SB(b, h) + boff + n * 2048 + k * 1024); } while (0)
; #define PG8_MMA(ai, bj, At, Bt) do { __builtin_amdgcn_s_setprio(1); _Pragma("unroll") for (int m = 0; m < 4; ++m) _Pragma("unroll") for (int n = 0; n < 2; ++n) _Pragma("unroll") for (int k = 0; k < 2; ++k) \
;     acc[ai][bj][m][n] = __builtin_amdgcn_mfma_f32_16x16x32_bf16(Bt[n][k], At[m][k], acc[ai][bj][m][n], 0, 0, 0); __builtin_amdgcn_s_setprio(0); } while (0)
; #define PG8_WAIT_V(n) asm volatile("s_waitcnt vmcnt(" #n ")" ::: "memory")
; #define PG8_WAIT_L(n) asm volatile("s_waitcnt lgkmcnt(" #n ")" ::: "memory")
; #define PG8_BAR __builtin_amdgcn_s_barrier()
; #define PG8_SCHED __builtin_amdgcn_sched_barrier(0)
; template <class Epi, class Sched>
; __device__ __forceinline__ void gemm_phase(PG8_LAS unsigned char* lds, const int lda, const int ldb, const Sched& S, const Epi& E) {
;     ...
;       PG8_STAGE(PG8_SB(0, 1), b2 + hstepB, voffB);
;       PG8_WAIT_V(6); PG8_BAR; PG8_MMA(1, 1, At, B1); PG8_BAR;
;       PG8_LDB(B0, 1, 0); PG8_SCHED; PG8_LDA(At, 1, 0); PG8_STAGE(PG8_SA(0, 1), a2 + hstepA, voffA);
;       PG8_WAIT_L(8); PG8_BAR; PG8_WAIT_L(0); PG8_MMA(0, 0, At, B0); PG8_BAR; PG8_SCHED;
;       PG8_LDB(B1, 1, 1); PG8_STAGE(PG8_SB(1, 0), b3, voffB);
;       PG8_BAR; PG8_WAIT_L(0); PG8_MMA(0, 1, At, B1); PG8_BAR;
;       PG8_LDA(At, 1, 1); PG8_STAGE(PG8_SA(1, 0), a3, voffA);
	s_add_u32 s18, s22, 0x40000
	s_addc_u32 s19, s23, 0
	s_add_i32 s33, s55, s34
	v_lshl_add_u64 v[140:141], s[18:19], 0, v[134:135]
	s_mov_b32 m0, s33
	s_nop 0
	global_load_lds_dwordx4 v[140:141], off
	v_lshl_add_u64 v[140:141], s[18:19], 0, v[132:133]
	s_add_i32 m0, s33, 0x2000
	s_nop 0
	global_load_lds_dwordx4 v[140:141], off
	s_waitcnt vmcnt(6)
	s_barrier
	v_mfma_f32_16x16x32_bf16 v[54:57], v[216:219], v[158:161], v[54:57]
	v_mfma_f32_16x16x32_bf16 v[50:53], v[224:227], v[158:161], v[50:53]
	v_mfma_f32_16x16x32_bf16 v[38:41], v[216:219], v[166:169], v[38:41]
	v_mfma_f32_16x16x32_bf16 v[34:37], v[224:227], v[166:169], v[34:37]
	v_mfma_f32_16x16x32_bf16 v[22:25], v[216:219], v[200:203], v[22:25]
	v_mfma_f32_16x16x32_bf16 v[18:21], v[224:227], v[200:203], v[18:21]
	v_mfma_f32_16x16x32_bf16 v[6:9], v[216:219], v[208:211], v[6:9]
	v_mfma_f32_16x16x32_bf16 v[2:5], v[224:227], v[208:211], v[2:5]
	v_mfma_f32_16x16x32_bf16 v[54:57], v[220:223], v[162:165], v[54:57]
	v_mfma_f32_16x16x32_bf16 v[50:53], v[228:231], v[162:165], v[50:53]
	v_mfma_f32_16x16x32_bf16 v[38:41], v[220:223], v[170:173], v[38:41]
	v_mfma_f32_16x16x32_bf16 v[34:37], v[228:231], v[170:173], v[34:37]
	v_mfma_f32_16x16x32_bf16 v[22:25], v[220:223], v[204:207], v[22:25]
	v_mfma_f32_16x16x32_bf16 v[18:21], v[228:231], v[204:207], v[18:21]
	v_mfma_f32_16x16x32_bf16 v[6:9], v[220:223], v[212:215], v[6:9]
	v_mfma_f32_16x16x32_bf16 v[2:5], v[228:231], v[212:215], v[2:5]
	s_barrier
	s_add_i32 s33, 0, 0x18000
	v_add_u32_e32 v154, s33, v131
	ds_read_b128 v[140:143], v154
	ds_read_b128 v[146:149], v154 offset:1024
	ds_read_b128 v[150:153], v154 offset:2048
	ds_read_b128 v[154:157], v154 offset:3072
	s_add_u32 s18, s24, 0x40000
	s_addc_u32 s19, s25, 0
	s_mov_b32 m0, s38
	v_lshl_add_u64 v[216:217], s[18:19], 0, v[134:135]
	ds_read_b128 v[158:161], v145 offset:32768
	ds_read_b128 v[162:165], v145 offset:33792
	ds_read_b128 v[166:169], v145 offset:34816
	ds_read_b128 v[170:173], v145 offset:35840
	ds_read_b128 v[200:203], v145 offset:36864
	ds_read_b128 v[204:207], v145 offset:37888
	ds_read_b128 v[208:211], v145 offset:38912
	ds_read_b128 v[212:215], v145 offset:39936
	global_load_lds_dwordx4 v[216:217], off
	v_lshl_add_u64 v[216:217], s[18:19], 0, v[132:133]
	s_mov_b32 m0, s39
	s_nop 0
	global_load_lds_dwordx4 v[216:217], off
	s_waitcnt lgkmcnt(8)
	s_barrier
	s_waitcnt lgkmcnt(0)
	v_mfma_f32_16x16x32_bf16 v[126:129], v[140:143], v[158:161], v[126:129]
	v_mfma_f32_16x16x32_bf16 v[122:125], v[150:153], v[158:161], v[122:125]
	v_mfma_f32_16x16x32_bf16 v[110:113], v[140:143], v[166:169], v[110:113]
	v_mfma_f32_16x16x32_bf16 v[106:109], v[150:153], v[166:169], v[106:109]
	v_mfma_f32_16x16x32_bf16 v[94:97], v[140:143], v[200:203], v[94:97]
	v_mfma_f32_16x16x32_bf16 v[90:93], v[150:153], v[200:203], v[90:93]
	v_mfma_f32_16x16x32_bf16 v[78:81], v[140:143], v[208:211], v[78:81]
	v_mfma_f32_16x16x32_bf16 v[74:77], v[150:153], v[208:211], v[74:77]
	v_mfma_f32_16x16x32_bf16 v[126:129], v[146:149], v[162:165], v[126:129]
	v_mfma_f32_16x16x32_bf16 v[122:125], v[154:157], v[162:165], v[122:125]
	v_mfma_f32_16x16x32_bf16 v[110:113], v[146:149], v[170:173], v[110:113]
	v_mfma_f32_16x16x32_bf16 v[106:109], v[154:157], v[170:173], v[106:109]
	v_mfma_f32_16x16x32_bf16 v[94:97], v[146:149], v[204:207], v[94:97]
	v_mfma_f32_16x16x32_bf16 v[90:93], v[154:157], v[204:207], v[90:93]
	v_mfma_f32_16x16x32_bf16 v[78:81], v[146:149], v[212:215], v[78:81]
	v_mfma_f32_16x16x32_bf16 v[74:77], v[154:157], v[212:215], v[74:77]
	s_barrier
	s_add_i32 s24, 0, 0x1c000
	s_add_i32 s18, s33, s34
	v_add_u32_e32 v228, s24, v131
	v_lshl_add_u64 v[174:175], v[174:175], 0, s[86:87]
	s_mov_b32 m0, s18
	ds_read_b128 v[216:219], v228
	ds_read_b128 v[220:223], v228 offset:1024
	ds_read_b128 v[224:227], v228 offset:2048
	ds_read_b128 v[228:231], v228 offset:3072
	global_load_lds_dwordx4 v[174:175], off
	v_lshl_add_u64 v[174:175], v[182:183], 0, s[86:87]
	s_add_i32 m0, s18, 0x2000
	s_nop 0
	global_load_lds_dwordx4 v[174:175], off
	s_barrier
; #define PG8_STAGE(bufoff, gbase, voff) do { _Pragma("unroll") for (int _i = 0; _i < 2; ++_i) \
;     __builtin_amdgcn_global_load_lds((const unsigned*)((const char*)(gbase) + (voff)[_i]), (PG8_LAS unsigned*)(lds + (bufoff) + ldsw + _i * 8192), 16, 0, 0); } while (0)
; #define PG8_LDA(dst, b, h) do { _Pragma("unroll") for (int m = 0; m < 4; ++m) _Pragma("unroll") for (int k = 0; k < 2; ++k) dst[m][k] = *(const PG8_LAS bf16x8*)(lds + PG8_SA(b, h) + aoff + m * 2048 + k * 1024); } while (0)
; #define PG8_MMA(ai, bj, At, Bt) do { __builtin_amdgcn_s_setprio(1); _Pragma("unroll") for (int m = 0; m < 4; ++m) _Pragma("unroll") for (int n = 0; n < 2; ++n) _Pragma("unroll") for (int k = 0; k < 2; ++k) \
;     acc[ai][bj][m][n] = __builtin_amdgcn_mfma_f32_16x16x32_bf16(Bt[n][k], At[m][k], acc[ai][bj][m][n], 0, 0, 0); __builtin_amdgcn_s_setprio(0); } while (0)
; #define PG8_WAIT_V(n) asm volatile("s_waitcnt vmcnt(" #n ")" ::: "memory")
; #define PG8_WAIT_L(n) asm volatile("s_waitcnt lgkmcnt(" #n ")" ::: "memory")
; #define PG8_BAR __builtin_amdgcn_s_barrier()
; #define PG8_SCHED __builtin_amdgcn_sched_barrier(0)
; template <class Epi, class Sched>
; __device__ __forceinline__ void gemm_phase(PG8_LAS unsigned char* lds, const int lda, const int ldb, const Sched& S, const Epi& E) {
;     ...
;       PG8_BAR; PG8_WAIT_L(0); PG8_MMA(0, 1, At, B1); PG8_BAR;
;       PG8_LDA(At, 1, 1); PG8_STAGE(PG8_SA(1, 0), a3, voffA);
;       PG8_BAR; PG8_WAIT_L(0); PG8_MMA(1, 0, At, B0); PG8_BAR; PG8_SCHED;
;       PG8_STAGE(PG8_SB(1, 1), b3 + hstepB, voffB);
;       PG8_WAIT_V(6); PG8_BAR; PG8_MMA(1, 1, At, B1); PG8_BAR;
;   __device__ __forceinline__ void operator()(const f32x4 (&acc)[2][2][4][2], const Unit& u, int wr, int wc, int fr, int fq) const {
;     const int mr = (u.pm * 256 < ML) ? ((u.pm * 256) >> 11) : 32;
;     const float* gp = mod + (size_t)mr * 6144 + gate_off;
	s_waitcnt lgkmcnt(0)
	v_mfma_f32_16x16x32_bf16 v[118:121], v[216:219], v[158:161], v[118:121]
	v_mfma_f32_16x16x32_bf16 v[114:117], v[224:227], v[158:161], v[114:117]
	v_mfma_f32_16x16x32_bf16 v[102:105], v[216:219], v[166:169], v[102:105]
	v_mfma_f32_16x16x32_bf16 v[98:101], v[224:227], v[166:169], v[98:101]
	v_mfma_f32_16x16x32_bf16 v[86:89], v[216:219], v[200:203], v[86:89]
	v_mfma_f32_16x16x32_bf16 v[82:85], v[224:227], v[200:203], v[82:85]
	v_mfma_f32_16x16x32_bf16 v[70:73], v[216:219], v[208:211], v[70:73]
	v_mfma_f32_16x16x32_bf16 v[66:69], v[224:227], v[208:211], v[66:69]
	v_mfma_f32_16x16x32_bf16 v[118:121], v[220:223], v[162:165], v[118:121]
	v_mfma_f32_16x16x32_bf16 v[114:117], v[228:231], v[162:165], v[114:117]
	v_mfma_f32_16x16x32_bf16 v[102:105], v[220:223], v[170:173], v[102:105]
	v_mfma_f32_16x16x32_bf16 v[98:101], v[228:231], v[170:173], v[98:101]
	v_mfma_f32_16x16x32_bf16 v[86:89], v[220:223], v[204:207], v[86:89]
	v_mfma_f32_16x16x32_bf16 v[82:85], v[228:231], v[204:207], v[82:85]
	v_mfma_f32_16x16x32_bf16 v[70:73], v[220:223], v[212:215], v[70:73]
	v_mfma_f32_16x16x32_bf16 v[66:69], v[228:231], v[212:215], v[66:69]
	s_barrier
	s_mov_b32 m0, s44
	v_lshl_add_u64 v[174:175], v[184:185], 0, s[86:87]
	ds_read_b128 v[158:161], v145 offset:49152
	ds_read_b128 v[162:165], v145 offset:50176
	ds_read_b128 v[166:169], v145 offset:51200
	ds_read_b128 v[170:173], v145 offset:52224
	ds_read_b128 v[200:203], v145 offset:53248
	ds_read_b128 v[204:207], v145 offset:54272
	ds_read_b128 v[208:211], v145 offset:55296
	ds_read_b128 v[212:215], v145 offset:56320
	global_load_lds_dwordx4 v[174:175], off
	v_lshl_add_u64 v[174:175], v[232:233], 0, s[86:87]
	s_mov_b32 m0, s45
	s_nop 0
	global_load_lds_dwordx4 v[174:175], off
	s_barrier
	s_waitcnt lgkmcnt(0)
	v_mfma_f32_16x16x32_bf16 v[62:65], v[140:143], v[158:161], v[62:65]
	v_mfma_f32_16x16x32_bf16 v[58:61], v[150:153], v[158:161], v[58:61]
	v_mfma_f32_16x16x32_bf16 v[46:49], v[140:143], v[166:169], v[46:49]
	v_mfma_f32_16x16x32_bf16 v[42:45], v[150:153], v[166:169], v[42:45]
	v_mfma_f32_16x16x32_bf16 v[30:33], v[140:143], v[200:203], v[30:33]
	v_mfma_f32_16x16x32_bf16 v[26:29], v[150:153], v[200:203], v[26:29]
	v_mfma_f32_16x16x32_bf16 v[14:17], v[140:143], v[208:211], v[14:17]
	v_mfma_f32_16x16x32_bf16 v[10:13], v[150:153], v[208:211], v[10:13]
	v_mfma_f32_16x16x32_bf16 v[62:65], v[146:149], v[162:165], v[62:65]
	v_mfma_f32_16x16x32_bf16 v[58:61], v[154:157], v[162:165], v[58:61]
	v_mfma_f32_16x16x32_bf16 v[46:49], v[146:149], v[170:173], v[46:49]
	v_mfma_f32_16x16x32_bf16 v[42:45], v[154:157], v[170:173], v[42:45]
	v_mfma_f32_16x16x32_bf16 v[30:33], v[146:149], v[204:207], v[30:33]
	v_mfma_f32_16x16x32_bf16 v[26:29], v[154:157], v[204:207], v[26:29]
	v_mfma_f32_16x16x32_bf16 v[14:17], v[146:149], v[212:215], v[14:17]
	v_mfma_f32_16x16x32_bf16 v[10:13], v[154:157], v[212:215], v[10:13]
	s_barrier
	s_add_u32 s18, s22, 0x40080
	s_addc_u32 s19, s23, 0
	s_add_i32 s22, s24, s34
	v_lshl_add_u64 v[140:141], s[18:19], 0, v[134:135]
	s_mov_b32 m0, s22
	s_nop 0
	global_load_lds_dwordx4 v[140:141], off
	v_lshl_add_u64 v[140:141], s[18:19], 0, v[132:133]
	s_add_i32 m0, s22, 0x2000
	s_nop 0
	global_load_lds_dwordx4 v[140:141], off
	s_waitcnt vmcnt(6)
	s_barrier
	v_mfma_f32_16x16x32_bf16 v[54:57], v[216:219], v[158:161], v[54:57]
	v_mfma_f32_16x16x32_bf16 v[50:53], v[224:227], v[158:161], v[50:53]
	v_mfma_f32_16x16x32_bf16 v[38:41], v[216:219], v[166:169], v[38:41]
	v_mfma_f32_16x16x32_bf16 v[34:37], v[224:227], v[166:169], v[34:37]
	v_mfma_f32_16x16x32_bf16 v[22:25], v[216:219], v[200:203], v[22:25]
	v_mfma_f32_16x16x32_bf16 v[18:21], v[224:227], v[200:203], v[18:21]
	v_mfma_f32_16x16x32_bf16 v[6:9], v[216:219], v[208:211], v[6:9]
	v_mfma_f32_16x16x32_bf16 v[2:5], v[224:227], v[208:211], v[2:5]
	v_mfma_f32_16x16x32_bf16 v[54:57], v[220:223], v[162:165], v[54:57]
	v_mfma_f32_16x16x32_bf16 v[50:53], v[228:231], v[162:165], v[50:53]
	v_mfma_f32_16x16x32_bf16 v[38:41], v[220:223], v[170:173], v[38:41]
	v_mfma_f32_16x16x32_bf16 v[34:37], v[228:231], v[170:173], v[34:37]
	v_mfma_f32_16x16x32_bf16 v[22:25], v[220:223], v[204:207], v[22:25]
	v_mfma_f32_16x16x32_bf16 v[18:21], v[228:231], v[204:207], v[18:21]
	v_mfma_f32_16x16x32_bf16 v[6:9], v[220:223], v[212:215], v[6:9]
	v_mfma_f32_16x16x32_bf16 v[2:5], v[228:231], v[212:215], v[2:5]
	s_add_i32 s54, s54, 2
	s_add_u32 s52, s52, 0x100
	s_addc_u32 s53, s53, 0
	s_cmp_gt_u32 s54, 13
	s_mov_b64 s[18:19], s[20:21]
	s_barrier
	s_cbranch_scc0 .LBB0_1482
	s_cmpk_gt_i32 s16, 0xff
	s_mov_b64 s[18:19], 0x30000
	s_cbranch_scc1 .LBB0_1478
	s_ashr_i32 s1, s16, 3
	s_mul_hi_i32 s19, s1, 0x1800
	s_mul_i32 s18, s1, 0x1800
	s_branch .LBB0_1478

; #define PG8_STAGE(bufoff, gbase, voff) do { _Pragma("unroll") for (int _i = 0; _i < 2; ++_i) \
;     __builtin_amdgcn_global_load_lds((const unsigned*)((const char*)(gbase) + (voff)[_i]), (PG8_LAS unsigned*)(lds + (bufoff) + ldsw + _i * 8192), 16, 0, 0); } while (0)
; #define PG8_LDA(dst, b, h) do { _Pragma("unroll") for (int m = 0; m < 4; ++m) _Pragma("unroll") for (int k = 0; k < 2; ++k) dst[m][k] = *(const PG8_LAS bf16x8*)(lds + PG8_SA(b, h) + aoff + m * 2048 + k * 1024); } while (0)
; #define PG8_LDB(dst, b, h) do { _Pragma("unroll") for (int n = 0; n < 2; ++n) _Pragma("unroll") for (int k = 0; k < 2; ++k) dst[n][k] = *(const PG8_LAS bf16x8*)(lds + PG8_SB(b, h) + boff + n * 2048 + k * 1024); } while (0)
; #define PG8_MMA(ai, bj, At, Bt) do { __builtin_amdgcn_s_setprio(1); _Pragma("unroll") for (int m = 0; m < 4; ++m) _Pragma("unroll") for (int n = 0; n < 2; ++n) _Pragma("unroll") for (int k = 0; k < 2; ++k) \
;     acc[ai][bj][m][n] = __builtin_amdgcn_mfma_f32_16x16x32_bf16(Bt[n][k], At[m][k], acc[ai][bj][m][n], 0, 0, 0); __builtin_amdgcn_s_setprio(0); } while (0)
; #define PG8_WAIT_L(n) asm volatile("s_waitcnt lgkmcnt(" #n ")" ::: "memory")
; #define PG8_BAR __builtin_amdgcn_s_barrier()
; #define PG8_SCHED __builtin_amdgcn_sched_barrier(0)
; template <class Epi, class Sched>
; __device__ __forceinline__ void gemm_phase(PG8_LAS unsigned char* lds, const int lda, const int ldb, const Sched& S, const Epi& E) {
;     ...
;       PG8_LDB(B0, 0, 0); PG8_SCHED; PG8_LDA(At, 0, 0); PG8_STAGE(PG8_SA(1, 1), a1 + hstepA, voffA);
;       PG8_WAIT_L(8); PG8_BAR; PG8_WAIT_L(0); PG8_MMA(0, 0, At, B0); PG8_BAR; PG8_SCHED;
;       PG8_LDB(B1, 0, 1); PG8_STAGE(PG8_SB(0, 0), b2, voffB);
;       PG8_BAR; PG8_WAIT_L(0); PG8_MMA(0, 1, At, B1); PG8_BAR;
;       PG8_LDA(At, 0, 1); PG8_STAGE(PG8_SA(0, 0), a2, voffA);
;       PG8_BAR; PG8_WAIT_L(0); PG8_MMA(1, 0, At, B0); PG8_BAR; PG8_SCHED;
.LBB0_1604:
	s_add_u32 s20, s18, 0xfffc0080
	s_addc_u32 s21, s19, -1
	s_add_i32 s33, 0, 0x10000
	v_add_u32_e32 v154, s33, v131
	ds_read_b128 v[142:145], v154
	ds_read_b128 v[146:149], v154 offset:1024
	ds_read_b128 v[150:153], v154 offset:2048
	ds_read_b128 v[154:157], v154 offset:3072
	s_cmp_eq_u32 s46, 12
	s_cselect_b32 s23, s11, s21
	s_cselect_b32 s22, s42, s20
	s_cselect_b32 s21, s1, s45
	s_cselect_b32 s20, s43, s44
	v_lshl_add_u64 v[174:175], s[18:19], 0, v[136:137]
	s_add_i32 m0, s17, 0xc000
	ds_read_b128 v[158:161], v141
	ds_read_b128 v[162:165], v141 offset:1024
	ds_read_b128 v[166:169], v141 offset:2048
	ds_read_b128 v[170:173], v141 offset:3072
	ds_read_b128 v[200:203], v141 offset:4096
	ds_read_b128 v[204:207], v141 offset:5120
	ds_read_b128 v[208:211], v141 offset:6144
	ds_read_b128 v[212:215], v141 offset:7168
	global_load_lds_dwordx4 v[174:175], off
	v_lshl_add_u64 v[174:175], s[18:19], 0, v[138:139]
	s_add_i32 m0, s17, 0xe000
	s_nop 0
	global_load_lds_dwordx4 v[174:175], off
	s_waitcnt lgkmcnt(8)
	s_barrier
	s_waitcnt lgkmcnt(0)
	v_mfma_f32_16x16x32_bf16 v[126:129], v[142:145], v[158:161], v[126:129]
	v_mfma_f32_16x16x32_bf16 v[118:121], v[150:153], v[158:161], v[118:121]
	v_mfma_f32_16x16x32_bf16 v[110:113], v[142:145], v[166:169], v[110:113]
	v_mfma_f32_16x16x32_bf16 v[102:105], v[150:153], v[166:169], v[102:105]
	v_mfma_f32_16x16x32_bf16 v[94:97], v[142:145], v[200:203], v[94:97]
	v_mfma_f32_16x16x32_bf16 v[86:89], v[150:153], v[200:203], v[86:89]
	v_mfma_f32_16x16x32_bf16 v[78:81], v[142:145], v[208:211], v[78:81]
	v_mfma_f32_16x16x32_bf16 v[70:73], v[150:153], v[208:211], v[70:73]
	v_mfma_f32_16x16x32_bf16 v[126:129], v[146:149], v[162:165], v[126:129]
	v_mfma_f32_16x16x32_bf16 v[118:121], v[154:157], v[162:165], v[118:121]
	v_mfma_f32_16x16x32_bf16 v[110:113], v[146:149], v[170:173], v[110:113]
	v_mfma_f32_16x16x32_bf16 v[102:105], v[154:157], v[170:173], v[102:105]
	v_mfma_f32_16x16x32_bf16 v[94:97], v[146:149], v[204:207], v[94:97]
	v_mfma_f32_16x16x32_bf16 v[86:89], v[154:157], v[204:207], v[86:89]
	v_mfma_f32_16x16x32_bf16 v[78:81], v[146:149], v[212:215], v[78:81]
	v_mfma_f32_16x16x32_bf16 v[70:73], v[154:157], v[212:215], v[70:73]
	s_barrier
	s_add_i32 s47, 0, 0x14000
	v_add_u32_e32 v174, s47, v131
	s_add_i32 s33, s33, s30
	ds_read_b128 v[216:219], v174
	ds_read_b128 v[220:223], v174 offset:1024
	ds_read_b128 v[224:227], v174 offset:2048
	ds_read_b128 v[228:231], v174 offset:3072
	v_lshl_add_u64 v[174:175], s[20:21], 0, v[134:135]
	s_mov_b32 m0, s33
	v_lshl_add_u64 v[182:183], s[20:21], 0, v[132:133]
	global_load_lds_dwordx4 v[174:175], off
	s_add_i32 m0, s33, 0x2000
	s_nop 0
	global_load_lds_dwordx4 v[182:183], off
	s_barrier
	s_waitcnt lgkmcnt(0)
	v_mfma_f32_16x16x32_bf16 v[122:125], v[216:219], v[158:161], v[122:125]
	v_mfma_f32_16x16x32_bf16 v[114:117], v[224:227], v[158:161], v[114:117]
	v_mfma_f32_16x16x32_bf16 v[106:109], v[216:219], v[166:169], v[106:109]
	v_mfma_f32_16x16x32_bf16 v[98:101], v[224:227], v[166:169], v[98:101]
	v_mfma_f32_16x16x32_bf16 v[90:93], v[216:219], v[200:203], v[90:93]
	v_mfma_f32_16x16x32_bf16 v[82:85], v[224:227], v[200:203], v[82:85]
	v_mfma_f32_16x16x32_bf16 v[74:77], v[216:219], v[208:211], v[74:77]
	v_mfma_f32_16x16x32_bf16 v[66:69], v[224:227], v[208:211], v[66:69]
	v_mfma_f32_16x16x32_bf16 v[122:125], v[220:223], v[162:165], v[122:125]
	v_mfma_f32_16x16x32_bf16 v[114:117], v[228:231], v[162:165], v[114:117]
	v_mfma_f32_16x16x32_bf16 v[106:109], v[220:223], v[170:173], v[106:109]
	v_mfma_f32_16x16x32_bf16 v[98:101], v[228:231], v[170:173], v[98:101]
	v_mfma_f32_16x16x32_bf16 v[90:93], v[220:223], v[204:207], v[90:93]
	v_mfma_f32_16x16x32_bf16 v[82:85], v[228:231], v[204:207], v[82:85]
	v_mfma_f32_16x16x32_bf16 v[74:77], v[220:223], v[212:215], v[74:77]
	v_mfma_f32_16x16x32_bf16 v[66:69], v[228:231], v[212:215], v[66:69]
	s_barrier
	s_mov_b32 m0, s17
	v_lshl_add_u64 v[184:185], s[22:23], 0, v[134:135]
	ds_read_b128 v[158:161], v141 offset:16384
	ds_read_b128 v[162:165], v141 offset:17408
	ds_read_b128 v[166:169], v141 offset:18432
	ds_read_b128 v[170:173], v141 offset:19456
	ds_read_b128 v[200:203], v141 offset:20480
	ds_read_b128 v[204:207], v141 offset:21504
	ds_read_b128 v[208:211], v141 offset:22528
	ds_read_b128 v[212:215], v141 offset:23552
	global_load_lds_dwordx4 v[184:185], off
	v_lshl_add_u64 v[232:233], s[22:23], 0, v[132:133]
	s_mov_b32 m0, s35
	s_nop 0
	global_load_lds_dwordx4 v[232:233], off
	s_barrier
	s_waitcnt lgkmcnt(0)
	v_mfma_f32_16x16x32_bf16 v[62:65], v[142:145], v[158:161], v[62:65]
	v_mfma_f32_16x16x32_bf16 v[54:57], v[150:153], v[158:161], v[54:57]
	v_mfma_f32_16x16x32_bf16 v[46:49], v[142:145], v[166:169], v[46:49]
	v_mfma_f32_16x16x32_bf16 v[38:41], v[150:153], v[166:169], v[38:41]
	v_mfma_f32_16x16x32_bf16 v[30:33], v[142:145], v[200:203], v[30:33]
	v_mfma_f32_16x16x32_bf16 v[22:25], v[150:153], v[200:203], v[22:25]
	v_mfma_f32_16x16x32_bf16 v[14:17], v[142:145], v[208:211], v[14:17]
	v_mfma_f32_16x16x32_bf16 v[6:9], v[150:153], v[208:211], v[6:9]
	v_mfma_f32_16x16x32_bf16 v[62:65], v[146:149], v[162:165], v[62:65]
	v_mfma_f32_16x16x32_bf16 v[54:57], v[154:157], v[162:165], v[54:57]
	v_mfma_f32_16x16x32_bf16 v[46:49], v[146:149], v[170:173], v[46:49]
	v_mfma_f32_16x16x32_bf16 v[38:41], v[154:157], v[170:173], v[38:41]
	v_mfma_f32_16x16x32_bf16 v[30:33], v[146:149], v[204:207], v[30:33]
	v_mfma_f32_16x16x32_bf16 v[22:25], v[154:157], v[204:207], v[22:25]
	v_mfma_f32_16x16x32_bf16 v[14:17], v[146:149], v[212:215], v[14:17]
	v_mfma_f32_16x16x32_bf16 v[6:9], v[154:157], v[212:215], v[6:9]
	s_barrier
; #define PG8_STAGE(bufoff, gbase, voff) do { _Pragma("unroll") for (int _i = 0; _i < 2; ++_i) \
;     __builtin_amdgcn_global_load_lds((const unsigned*)((const char*)(gbase) + (voff)[_i]), (PG8_LAS unsigned*)(lds + (bufoff) + ldsw + _i * 8192), 16, 0, 0); } while (0)
; #define PG8_LDA(dst, b, h) do { _Pragma("unroll") for (int m = 0; m < 4; ++m) _Pragma("unroll") for (int k = 0; k < 2; ++k) dst[m][k] = *(const PG8_LAS bf16x8*)(lds + PG8_SA(b, h) + aoff + m * 2048 + k * 1024); } while (0)
; #define PG8_LDB(dst, b, h) do { _Pragma("unroll") for (int n = 0; n < 2; ++n) _Pragma("unroll") for (int k = 0; k < 2; ++k) dst[n][k] = *(const PG8_LAS bf16x8*)(lds + PG8_SB(b, h) + boff + n * 2048 + k * 1024); } while (0)
; #define PG8_MMA(ai, bj, At, Bt) do { __builtin_amdgcn_s_setprio(1); _Pragma("unroll") for (int m = 0; m < 4; ++m) _Pragma("unroll") for (int n = 0; n < 2; ++n) _Pragma("unroll") for (int k = 0; k < 2; ++k) \
;     acc[ai][bj][m][n] = __builtin_amdgcn_mfma_f32_16x16x32_bf16(Bt[n][k], At[m][k], acc[ai][bj][m][n], 0, 0, 0); __builtin_amdgcn_s_setprio(0); } while (0)
; #define PG8_WAIT_V(n) asm volatile("s_waitcnt vmcnt(" #n ")" ::: "memory")
; #define PG8_WAIT_L(n) asm volatile("s_waitcnt lgkmcnt(" #n ")" ::: "memory")
; #define PG8_BAR __builtin_amdgcn_s_barrier()
; #define PG8_SCHED __builtin_amdgcn_sched_barrier(0)
; template <class Epi, class Sched>
; __device__ __forceinline__ void gemm_phase(PG8_LAS unsigned char* lds, const int lda, const int ldb, const Sched& S, const Epi& E) {
;     ...
;       PG8_STAGE(PG8_SB(0, 1), b2 + hstepB, voffB);
;       PG8_WAIT_V(6); PG8_BAR; PG8_MMA(1, 1, At, B1); PG8_BAR;
;       PG8_LDB(B0, 1, 0); PG8_SCHED; PG8_LDA(At, 1, 0); PG8_STAGE(PG8_SA(0, 1), a2 + hstepA, voffA);
;       PG8_WAIT_L(8); PG8_BAR; PG8_WAIT_L(0); PG8_MMA(0, 0, At, B0); PG8_BAR; PG8_SCHED;
;       PG8_LDB(B1, 1, 1); PG8_STAGE(PG8_SB(1, 0), b3, voffB);
;       PG8_BAR; PG8_WAIT_L(0); PG8_MMA(0, 1, At, B1); PG8_BAR;
;       PG8_LDA(At, 1, 1); PG8_STAGE(PG8_SA(1, 0), a3, voffA);
	s_add_u32 s48, s20, 0x40000
	s_addc_u32 s49, s21, 0
	s_add_i32 s33, s47, s30
	v_lshl_add_u64 v[142:143], s[48:49], 0, v[134:135]
	s_mov_b32 m0, s33
	s_nop 0
	global_load_lds_dwordx4 v[142:143], off
	v_lshl_add_u64 v[142:143], s[48:49], 0, v[132:133]
	s_add_i32 m0, s33, 0x2000
	s_nop 0
	global_load_lds_dwordx4 v[142:143], off
	s_waitcnt vmcnt(6)
	s_barrier
	v_mfma_f32_16x16x32_bf16 v[58:61], v[216:219], v[158:161], v[58:61]
	v_mfma_f32_16x16x32_bf16 v[50:53], v[224:227], v[158:161], v[50:53]
	v_mfma_f32_16x16x32_bf16 v[42:45], v[216:219], v[166:169], v[42:45]
	v_mfma_f32_16x16x32_bf16 v[34:37], v[224:227], v[166:169], v[34:37]
	v_mfma_f32_16x16x32_bf16 v[26:29], v[216:219], v[200:203], v[26:29]
	v_mfma_f32_16x16x32_bf16 v[18:21], v[224:227], v[200:203], v[18:21]
	v_mfma_f32_16x16x32_bf16 v[10:13], v[216:219], v[208:211], v[10:13]
	v_mfma_f32_16x16x32_bf16 v[2:5], v[224:227], v[208:211], v[2:5]
	v_mfma_f32_16x16x32_bf16 v[58:61], v[220:223], v[162:165], v[58:61]
	v_mfma_f32_16x16x32_bf16 v[50:53], v[228:231], v[162:165], v[50:53]
	v_mfma_f32_16x16x32_bf16 v[42:45], v[220:223], v[170:173], v[42:45]
	v_mfma_f32_16x16x32_bf16 v[34:37], v[228:231], v[170:173], v[34:37]
	v_mfma_f32_16x16x32_bf16 v[26:29], v[220:223], v[204:207], v[26:29]
	v_mfma_f32_16x16x32_bf16 v[18:21], v[228:231], v[204:207], v[18:21]
	v_mfma_f32_16x16x32_bf16 v[10:13], v[220:223], v[212:215], v[10:13]
	v_mfma_f32_16x16x32_bf16 v[2:5], v[228:231], v[212:215], v[2:5]
	s_barrier
	s_add_i32 s33, 0, 0x18000
	v_add_u32_e32 v154, s33, v131
	ds_read_b128 v[142:145], v154
	ds_read_b128 v[146:149], v154 offset:1024
	ds_read_b128 v[150:153], v154 offset:2048
	ds_read_b128 v[154:157], v154 offset:3072
	s_add_u32 s22, s22, 0x40000
	s_addc_u32 s23, s23, 0
	s_mov_b32 m0, s36
	v_lshl_add_u64 v[216:217], s[22:23], 0, v[134:135]
	ds_read_b128 v[158:161], v141 offset:32768
	ds_read_b128 v[162:165], v141 offset:33792
	ds_read_b128 v[166:169], v141 offset:34816
	ds_read_b128 v[170:173], v141 offset:35840
	ds_read_b128 v[200:203], v141 offset:36864
	ds_read_b128 v[204:207], v141 offset:37888
	ds_read_b128 v[208:211], v141 offset:38912
	ds_read_b128 v[212:215], v141 offset:39936
	global_load_lds_dwordx4 v[216:217], off
	v_lshl_add_u64 v[216:217], s[22:23], 0, v[132:133]
	s_mov_b32 m0, s37
	s_nop 0
	global_load_lds_dwordx4 v[216:217], off
	s_waitcnt lgkmcnt(8)
	s_barrier
	s_waitcnt lgkmcnt(0)
	v_mfma_f32_16x16x32_bf16 v[126:129], v[142:145], v[158:161], v[126:129]
	v_mfma_f32_16x16x32_bf16 v[118:121], v[150:153], v[158:161], v[118:121]
	v_mfma_f32_16x16x32_bf16 v[110:113], v[142:145], v[166:169], v[110:113]
	v_mfma_f32_16x16x32_bf16 v[102:105], v[150:153], v[166:169], v[102:105]
	v_mfma_f32_16x16x32_bf16 v[94:97], v[142:145], v[200:203], v[94:97]
	v_mfma_f32_16x16x32_bf16 v[86:89], v[150:153], v[200:203], v[86:89]
	v_mfma_f32_16x16x32_bf16 v[78:81], v[142:145], v[208:211], v[78:81]
	v_mfma_f32_16x16x32_bf16 v[70:73], v[150:153], v[208:211], v[70:73]
	v_mfma_f32_16x16x32_bf16 v[126:129], v[146:149], v[162:165], v[126:129]
	v_mfma_f32_16x16x32_bf16 v[118:121], v[154:157], v[162:165], v[118:121]
	v_mfma_f32_16x16x32_bf16 v[110:113], v[146:149], v[170:173], v[110:113]
	v_mfma_f32_16x16x32_bf16 v[102:105], v[154:157], v[170:173], v[102:105]
	v_mfma_f32_16x16x32_bf16 v[94:97], v[146:149], v[204:207], v[94:97]
	v_mfma_f32_16x16x32_bf16 v[86:89], v[154:157], v[204:207], v[86:89]
	v_mfma_f32_16x16x32_bf16 v[78:81], v[146:149], v[212:215], v[78:81]
	v_mfma_f32_16x16x32_bf16 v[70:73], v[154:157], v[212:215], v[70:73]
	s_barrier
	s_add_i32 s22, 0, 0x1c000
	s_add_i32 s23, s33, s30
	v_add_u32_e32 v228, s22, v131
	v_lshl_add_u64 v[174:175], v[174:175], 0, s[86:87]
	s_mov_b32 m0, s23
	ds_read_b128 v[216:219], v228
	ds_read_b128 v[220:223], v228 offset:1024
	ds_read_b128 v[224:227], v228 offset:2048
	ds_read_b128 v[228:231], v228 offset:3072
	global_load_lds_dwordx4 v[174:175], off
	v_lshl_add_u64 v[174:175], v[182:183], 0, s[86:87]
	s_add_i32 m0, s23, 0x2000
	s_nop 0
	global_load_lds_dwordx4 v[174:175], off
	s_barrier
	s_waitcnt lgkmcnt(0)
	v_mfma_f32_16x16x32_bf16 v[122:125], v[216:219], v[158:161], v[122:125]
	v_mfma_f32_16x16x32_bf16 v[114:117], v[224:227], v[158:161], v[114:117]
	v_mfma_f32_16x16x32_bf16 v[106:109], v[216:219], v[166:169], v[106:109]
	v_mfma_f32_16x16x32_bf16 v[98:101], v[224:227], v[166:169], v[98:101]
	v_mfma_f32_16x16x32_bf16 v[90:93], v[216:219], v[200:203], v[90:93]
	v_mfma_f32_16x16x32_bf16 v[82:85], v[224:227], v[200:203], v[82:85]
	v_mfma_f32_16x16x32_bf16 v[74:77], v[216:219], v[208:211], v[74:77]
	v_mfma_f32_16x16x32_bf16 v[66:69], v[224:227], v[208:211], v[66:69]
	v_mfma_f32_16x16x32_bf16 v[122:125], v[220:223], v[162:165], v[122:125]
	v_mfma_f32_16x16x32_bf16 v[114:117], v[228:231], v[162:165], v[114:117]
	v_mfma_f32_16x16x32_bf16 v[106:109], v[220:223], v[170:173], v[106:109]
	v_mfma_f32_16x16x32_bf16 v[98:101], v[228:231], v[170:173], v[98:101]
	v_mfma_f32_16x16x32_bf16 v[90:93], v[220:223], v[204:207], v[90:93]
	v_mfma_f32_16x16x32_bf16 v[82:85], v[228:231], v[204:207], v[82:85]
	v_mfma_f32_16x16x32_bf16 v[74:77], v[220:223], v[212:215], v[74:77]
	v_mfma_f32_16x16x32_bf16 v[66:69], v[228:231], v[212:215], v[66:69]
	s_barrier
	s_mov_b32 m0, s38
	v_lshl_add_u64 v[174:175], v[184:185], 0, s[86:87]
	ds_read_b128 v[158:161], v141 offset:49152
	ds_read_b128 v[162:165], v141 offset:50176
	ds_read_b128 v[166:169], v141 offset:51200
	ds_read_b128 v[170:173], v141 offset:52224
	ds_read_b128 v[200:203], v141 offset:53248
	ds_read_b128 v[204:207], v141 offset:54272
	ds_read_b128 v[208:211], v141 offset:55296
	ds_read_b128 v[212:215], v141 offset:56320
	global_load_lds_dwordx4 v[174:175], off
	v_lshl_add_u64 v[174:175], v[232:233], 0, s[86:87]
	s_mov_b32 m0, s39
	s_nop 0
	global_load_lds_dwordx4 v[174:175], off
	s_barrier
; __device__ __forceinline__ float silu_f(float x) { return x * sigm(x); }
; #define PG8_STAGE(bufoff, gbase, voff) do { _Pragma("unroll") for (int _i = 0; _i < 2; ++_i) \
;     __builtin_amdgcn_global_load_lds((const unsigned*)((const char*)(gbase) + (voff)[_i]), (PG8_LAS unsigned*)(lds + (bufoff) + ldsw + _i * 8192), 16, 0, 0); } while (0)
; #define PG8_MMA(ai, bj, At, Bt) do { __builtin_amdgcn_s_setprio(1); _Pragma("unroll") for (int m = 0; m < 4; ++m) _Pragma("unroll") for (int n = 0; n < 2; ++n) _Pragma("unroll") for (int k = 0; k < 2; ++k) \
;     acc[ai][bj][m][n] = __builtin_amdgcn_mfma_f32_16x16x32_bf16(Bt[n][k], At[m][k], acc[ai][bj][m][n], 0, 0, 0); __builtin_amdgcn_s_setprio(0); } while (0)
; #define PG8_WAIT_V(n) asm volatile("s_waitcnt vmcnt(" #n ")" ::: "memory")
; #define PG8_WAIT_L(n) asm volatile("s_waitcnt lgkmcnt(" #n ")" ::: "memory")
; #define PG8_BAR __builtin_amdgcn_s_barrier()
; #define PG8_SCHED __builtin_amdgcn_sched_barrier(0)
; template <class Epi, class Sched>
; __device__ __forceinline__ void gemm_phase(PG8_LAS unsigned char* lds, const int lda, const int ldb, const Sched& S, const Epi& E) {
;     ...
;       PG8_BAR; PG8_WAIT_L(0); PG8_MMA(1, 0, At, B0); PG8_BAR; PG8_SCHED;
;       PG8_STAGE(PG8_SB(1, 1), b3 + hstepB, voffB);
;       PG8_WAIT_V(6); PG8_BAR; PG8_MMA(1, 1, At, B1); PG8_BAR;
;   __device__ __forceinline__ void operator()(const f32x4 (&acc)[2][2][4][2], const Unit& u, int wr, int wc, int fr, int fq) const {
;     ...
;         const int r = u.pm * 256 + ai * 128 + wr * 64 + m * 16 + fr;
; #pragma unroll
;         for (int n = 0; n < 2; ++n) {
;           const f32x4 g = acc[ai][0][m][n], up = acc[ai][1][m][n];
;           const int c = u.pn * 128 + wc * 32 + n * 16 + 4 * fq;
;           uint2 w;
;           w.x = pack2(silu_f(g[0]) * up[0], silu_f(g[1]) * up[1]);
;           w.y = pack2(silu_f(g[2]) * up[2], silu_f(g[3]) * up[3]);
;           *reinterpret_cast<uint2*>(HID + (size_t)r * DFF + c) = w;
	s_waitcnt lgkmcnt(0)
	v_mfma_f32_16x16x32_bf16 v[62:65], v[142:145], v[158:161], v[62:65]
	v_mfma_f32_16x16x32_bf16 v[54:57], v[150:153], v[158:161], v[54:57]
	v_mfma_f32_16x16x32_bf16 v[46:49], v[142:145], v[166:169], v[46:49]
	v_mfma_f32_16x16x32_bf16 v[38:41], v[150:153], v[166:169], v[38:41]
	v_mfma_f32_16x16x32_bf16 v[30:33], v[142:145], v[200:203], v[30:33]
	v_mfma_f32_16x16x32_bf16 v[22:25], v[150:153], v[200:203], v[22:25]
	v_mfma_f32_16x16x32_bf16 v[14:17], v[142:145], v[208:211], v[14:17]
	v_mfma_f32_16x16x32_bf16 v[6:9], v[150:153], v[208:211], v[6:9]
	v_mfma_f32_16x16x32_bf16 v[62:65], v[146:149], v[162:165], v[62:65]
	v_mfma_f32_16x16x32_bf16 v[54:57], v[154:157], v[162:165], v[54:57]
	v_mfma_f32_16x16x32_bf16 v[46:49], v[146:149], v[170:173], v[46:49]
	v_mfma_f32_16x16x32_bf16 v[38:41], v[154:157], v[170:173], v[38:41]
	v_mfma_f32_16x16x32_bf16 v[30:33], v[146:149], v[204:207], v[30:33]
	v_mfma_f32_16x16x32_bf16 v[22:25], v[154:157], v[204:207], v[22:25]
	v_mfma_f32_16x16x32_bf16 v[14:17], v[146:149], v[212:215], v[14:17]
	v_mfma_f32_16x16x32_bf16 v[6:9], v[154:157], v[212:215], v[6:9]
	s_barrier
	s_add_u32 s20, s20, 0x40080
	s_addc_u32 s21, s21, 0
	s_add_i32 s22, s22, s30
	v_lshl_add_u64 v[142:143], s[20:21], 0, v[134:135]
	s_mov_b32 m0, s22
	s_nop 0
	global_load_lds_dwordx4 v[142:143], off
	v_lshl_add_u64 v[142:143], s[20:21], 0, v[132:133]
	s_add_i32 m0, s22, 0x2000
	s_nop 0
	global_load_lds_dwordx4 v[142:143], off
	s_waitcnt vmcnt(6)
	s_barrier
	v_mfma_f32_16x16x32_bf16 v[58:61], v[216:219], v[158:161], v[58:61]
	v_mfma_f32_16x16x32_bf16 v[50:53], v[224:227], v[158:161], v[50:53]
	v_mfma_f32_16x16x32_bf16 v[42:45], v[216:219], v[166:169], v[42:45]
	v_mfma_f32_16x16x32_bf16 v[34:37], v[224:227], v[166:169], v[34:37]
	v_mfma_f32_16x16x32_bf16 v[26:29], v[216:219], v[200:203], v[26:29]
	v_mfma_f32_16x16x32_bf16 v[18:21], v[224:227], v[200:203], v[18:21]
	v_mfma_f32_16x16x32_bf16 v[10:13], v[216:219], v[208:211], v[10:13]
	v_mfma_f32_16x16x32_bf16 v[2:5], v[224:227], v[208:211], v[2:5]
	v_mfma_f32_16x16x32_bf16 v[58:61], v[220:223], v[162:165], v[58:61]
	v_mfma_f32_16x16x32_bf16 v[50:53], v[228:231], v[162:165], v[50:53]
	v_mfma_f32_16x16x32_bf16 v[42:45], v[220:223], v[170:173], v[42:45]
	v_mfma_f32_16x16x32_bf16 v[34:37], v[228:231], v[170:173], v[34:37]
	v_mfma_f32_16x16x32_bf16 v[26:29], v[220:223], v[204:207], v[26:29]
	v_mfma_f32_16x16x32_bf16 v[18:21], v[228:231], v[204:207], v[18:21]
	v_mfma_f32_16x16x32_bf16 v[10:13], v[220:223], v[212:215], v[10:13]
	v_mfma_f32_16x16x32_bf16 v[2:5], v[228:231], v[212:215], v[2:5]
	s_add_i32 s46, s46, 2
	s_add_u32 s18, s18, 0x100
	s_addc_u32 s19, s19, 0
	s_add_u32 s44, s44, 0x100
	s_addc_u32 s45, s45, 0
	s_cmp_gt_u32 s46, 13
	s_barrier
	s_cbranch_scc0 .LBB0_1604
	v_mul_f32_e32 v143, 0xbfb8aa3b, v126
	v_exp_f32_e32 v143, v143
	v_lshl_or_b32 v144, s41, 7, v140
	v_lshl_add_u32 v142, s16, 8, v1
	v_ashrrev_i32_e32 v145, 31, v144
	v_add_f32_e32 v143, 1.0, v143
	v_rcp_f32_e32 v146, v143
	v_mul_f32_e32 v143, 0xbfb8aa3b, v127
	v_exp_f32_e32 v143, v143
	s_and_b64 vcc, exec, s[6:7]
	s_mov_b32 s41, s0
	s_mov_b32 s16, s10
	v_add_f32_e32 v143, 1.0, v143
	v_rcp_f32_e32 v147, v143
	s_mov_b64 s[20:21], s[14:15]
	v_pk_mul_f32 v[126:127], v[126:127], v[146:147]
	s_nop 0
	v_pk_mul_f32 v[122:123], v[126:127], v[122:123]
	s_nop 0
	v_cvt_pk_bf16_f32 v126, v122, v123
	v_mul_f32_e32 v122, 0xbfb8aa3b, v128
	v_mul_f32_e32 v123, 0xbfb8aa3b, v129
	v_exp_f32_e32 v122, v122
	v_exp_f32_e32 v123, v123
	v_add_f32_e32 v122, 1.0, v122
	v_add_f32_e32 v123, 1.0, v123
	v_rcp_f32_e32 v122, v122
	v_rcp_f32_e32 v123, v123
	s_nop 0
	v_pk_mul_f32 v[122:123], v[128:129], v[122:123]
	s_nop 0
	v_pk_mul_f32 v[122:123], v[122:123], v[124:125]
	v_lshlrev_b64 v[124:125], 1, v[144:145]
	v_cvt_pk_bf16_f32 v127, v122, v123
	v_mov_b64_e32 v[122:123], s[84:85]
	v_mad_i64_i32 v[128:129], s[18:19], v142, s50, v[122:123]
	v_lshl_add_u64 v[128:129], v[128:129], 0, v[124:125]
	global_store_dwordx2 v[128:129], v[126:127], off
	v_mul_f32_e32 v126, 0xbfb8aa3b, v118
	v_mul_f32_e32 v127, 0xbfb8aa3b, v119
	v_exp_f32_e32 v126, v126
	v_exp_f32_e32 v127, v127
	v_add_f32_e32 v126, 1.0, v126
	v_add_f32_e32 v127, 1.0, v127
	v_rcp_f32_e32 v126, v126
	v_rcp_f32_e32 v127, v127
	s_nop 0
	v_pk_mul_f32 v[118:119], v[118:119], v[126:127]
	s_nop 0
	v_pk_mul_f32 v[114:115], v[118:119], v[114:115]
	s_nop 0
	v_cvt_pk_bf16_f32 v114, v114, v115
	v_mul_f32_e32 v115, 0xbfb8aa3b, v120
	v_exp_f32_e32 v115, v115
	s_nop 0
	v_add_f32_e32 v115, 1.0, v115
	v_rcp_f32_e32 v118, v115
	v_mul_f32_e32 v115, 0xbfb8aa3b, v121
	v_exp_f32_e32 v115, v115
	s_nop 0
	v_add_f32_e32 v115, 1.0, v115
	v_rcp_f32_e32 v119, v115
	s_nop 0
	v_pk_mul_f32 v[118:119], v[120:121], v[118:119]
	s_nop 0
	v_pk_mul_f32 v[116:117], v[118:119], v[116:117]
	s_nop 0
	v_cvt_pk_bf16_f32 v115, v116, v117
	global_store_dwordx2 v[128:129], v[114:115], off offset:32
	v_mul_f32_e32 v114, 0xbfb8aa3b, v110
	v_mul_f32_e32 v115, 0xbfb8aa3b, v111
	v_exp_f32_e32 v114, v114
	v_exp_f32_e32 v115, v115
	v_or_b32_e32 v116, 16, v142
	v_add_f32_e32 v114, 1.0, v114
	v_add_f32_e32 v115, 1.0, v115
	v_rcp_f32_e32 v114, v114
	v_rcp_f32_e32 v115, v115
	s_nop 0
	v_pk_mul_f32 v[110:111], v[110:111], v[114:115]
	s_nop 0
	v_pk_mul_f32 v[106:107], v[110:111], v[106:107]
	s_nop 0
	v_cvt_pk_bf16_f32 v106, v106, v107
	v_mul_f32_e32 v107, 0xbfb8aa3b, v112
	v_exp_f32_e32 v107, v107
	s_nop 0
	v_add_f32_e32 v107, 1.0, v107
	v_rcp_f32_e32 v110, v107
	v_mul_f32_e32 v107, 0xbfb8aa3b, v113
	v_exp_f32_e32 v107, v107
	s_nop 0
	v_add_f32_e32 v107, 1.0, v107
	v_rcp_f32_e32 v111, v107
	s_nop 0
	v_pk_mul_f32 v[110:111], v[112:113], v[110:111]
	s_nop 0
; __device__ __forceinline__ float silu_f(float x) { return x * sigm(x); }
;   __device__ __forceinline__ void operator()(const f32x4 (&acc)[2][2][4][2], const Unit& u, int wr, int wc, int fr, int fq) const {
;     ...
;         const int r = u.pm * 256 + ai * 128 + wr * 64 + m * 16 + fr;
; #pragma unroll
;         for (int n = 0; n < 2; ++n) {
;           const f32x4 g = acc[ai][0][m][n], up = acc[ai][1][m][n];
;           const int c = u.pn * 128 + wc * 32 + n * 16 + 4 * fq;
;           uint2 w;
;           w.x = pack2(silu_f(g[0]) * up[0], silu_f(g[1]) * up[1]);
;           w.y = pack2(silu_f(g[2]) * up[2], silu_f(g[3]) * up[3]);
;           *reinterpret_cast<uint2*>(HID + (size_t)r * DFF + c) = w;
	v_pk_mul_f32 v[108:109], v[110:111], v[108:109]
	s_nop 0
	v_cvt_pk_bf16_f32 v107, v108, v109
	v_mad_i64_i32 v[108:109], s[18:19], v116, s50, v[122:123]
	v_lshl_add_u64 v[108:109], v[108:109], 0, v[124:125]
	global_store_dwordx2 v[108:109], v[106:107], off
	v_mul_f32_e32 v106, 0xbfb8aa3b, v102
	v_mul_f32_e32 v107, 0xbfb8aa3b, v103
	v_exp_f32_e32 v106, v106
	v_exp_f32_e32 v107, v107
	v_add_f32_e32 v106, 1.0, v106
	v_add_f32_e32 v107, 1.0, v107
	v_rcp_f32_e32 v106, v106
	v_rcp_f32_e32 v107, v107
	s_nop 0
	v_pk_mul_f32 v[102:103], v[102:103], v[106:107]
	s_nop 0
	v_pk_mul_f32 v[98:99], v[102:103], v[98:99]
	s_nop 0
	v_cvt_pk_bf16_f32 v98, v98, v99
	v_mul_f32_e32 v99, 0xbfb8aa3b, v104
	v_exp_f32_e32 v99, v99
	s_nop 0
	v_add_f32_e32 v99, 1.0, v99
	v_rcp_f32_e32 v102, v99
	v_mul_f32_e32 v99, 0xbfb8aa3b, v105
	v_exp_f32_e32 v99, v99
	s_nop 0
	v_add_f32_e32 v99, 1.0, v99
	v_rcp_f32_e32 v103, v99
	s_nop 0
	v_pk_mul_f32 v[102:103], v[104:105], v[102:103]
	s_nop 0
	v_pk_mul_f32 v[100:101], v[102:103], v[100:101]
	s_nop 0
	v_cvt_pk_bf16_f32 v99, v100, v101
	global_store_dwordx2 v[108:109], v[98:99], off offset:32
	v_mul_f32_e32 v98, 0xbfb8aa3b, v94
	v_mul_f32_e32 v99, 0xbfb8aa3b, v95
	v_exp_f32_e32 v98, v98
	v_exp_f32_e32 v99, v99
	v_or_b32_e32 v100, 32, v142
	v_add_f32_e32 v98, 1.0, v98
	v_add_f32_e32 v99, 1.0, v99
	v_rcp_f32_e32 v98, v98
	v_rcp_f32_e32 v99, v99
	s_nop 0
	v_pk_mul_f32 v[94:95], v[94:95], v[98:99]
	s_nop 0
	v_pk_mul_f32 v[90:91], v[94:95], v[90:91]
	s_nop 0
	v_cvt_pk_bf16_f32 v90, v90, v91
	v_mul_f32_e32 v91, 0xbfb8aa3b, v96
	v_exp_f32_e32 v91, v91
	s_nop 0
	v_add_f32_e32 v91, 1.0, v91
	v_rcp_f32_e32 v94, v91
	v_mul_f32_e32 v91, 0xbfb8aa3b, v97
	v_exp_f32_e32 v91, v91
	s_nop 0
	v_add_f32_e32 v91, 1.0, v91
	v_rcp_f32_e32 v95, v91
	s_nop 0
	v_pk_mul_f32 v[94:95], v[96:97], v[94:95]
	s_nop 0
	v_pk_mul_f32 v[92:93], v[94:95], v[92:93]
	s_nop 0
	v_cvt_pk_bf16_f32 v91, v92, v93
	v_mad_i64_i32 v[92:93], s[18:19], v100, s50, v[122:123]
	v_lshl_add_u64 v[92:93], v[92:93], 0, v[124:125]
	global_store_dwordx2 v[92:93], v[90:91], off
	v_mul_f32_e32 v90, 0xbfb8aa3b, v86
	v_mul_f32_e32 v91, 0xbfb8aa3b, v87
	v_exp_f32_e32 v90, v90
	v_exp_f32_e32 v91, v91
	v_add_f32_e32 v90, 1.0, v90
	v_add_f32_e32 v91, 1.0, v91
	v_rcp_f32_e32 v90, v90
	v_rcp_f32_e32 v91, v91
	s_nop 0
	v_pk_mul_f32 v[86:87], v[86:87], v[90:91]
	s_nop 0
	v_pk_mul_f32 v[82:83], v[86:87], v[82:83]
	s_nop 0
	v_cvt_pk_bf16_f32 v82, v82, v83
	v_mul_f32_e32 v83, 0xbfb8aa3b, v88
	v_exp_f32_e32 v83, v83
	s_nop 0
	v_add_f32_e32 v83, 1.0, v83
	v_rcp_f32_e32 v86, v83
	v_mul_f32_e32 v83, 0xbfb8aa3b, v89
	v_exp_f32_e32 v83, v83
	s_nop 0
	v_add_f32_e32 v83, 1.0, v83
	v_rcp_f32_e32 v87, v83
	s_nop 0
	v_pk_mul_f32 v[86:87], v[88:89], v[86:87]
	s_nop 0
	v_pk_mul_f32 v[84:85], v[86:87], v[84:85]
	s_nop 0
	v_cvt_pk_bf16_f32 v83, v84, v85
	global_store_dwordx2 v[92:93], v[82:83], off offset:32
	v_mul_f32_e32 v82, 0xbfb8aa3b, v78
	v_mul_f32_e32 v83, 0xbfb8aa3b, v79
	v_exp_f32_e32 v82, v82
	v_exp_f32_e32 v83, v83
	v_or_b32_e32 v84, 48, v142
	v_add_f32_e32 v82, 1.0, v82
	v_add_f32_e32 v83, 1.0, v83
	v_rcp_f32_e32 v82, v82
	v_rcp_f32_e32 v83, v83
	s_nop 0
	v_pk_mul_f32 v[78:79], v[78:79], v[82:83]
	s_nop 0
	v_pk_mul_f32 v[74:75], v[78:79], v[74:75]
	s_nop 0
	v_cvt_pk_bf16_f32 v74, v74, v75
	v_mul_f32_e32 v75, 0xbfb8aa3b, v80
	v_exp_f32_e32 v75, v75
	s_nop 0
	v_add_f32_e32 v75, 1.0, v75
	v_rcp_f32_e32 v78, v75
	v_mul_f32_e32 v75, 0xbfb8aa3b, v81
	v_exp_f32_e32 v75, v75
	s_nop 0
	v_add_f32_e32 v75, 1.0, v75
	v_rcp_f32_e32 v79, v75
	s_nop 0
	v_pk_mul_f32 v[78:79], v[80:81], v[78:79]
	s_nop 0
	v_pk_mul_f32 v[76:77], v[78:79], v[76:77]
	s_nop 0
	v_cvt_pk_bf16_f32 v75, v76, v77
	v_mad_i64_i32 v[76:77], s[18:19], v84, s50, v[122:123]
	v_lshl_add_u64 v[76:77], v[76:77], 0, v[124:125]
	global_store_dwordx2 v[76:77], v[74:75], off
	v_mul_f32_e32 v74, 0xbfb8aa3b, v70
	v_mul_f32_e32 v75, 0xbfb8aa3b, v71
	v_exp_f32_e32 v74, v74
	v_exp_f32_e32 v75, v75
	v_add_f32_e32 v74, 1.0, v74
	v_add_f32_e32 v75, 1.0, v75
	v_rcp_f32_e32 v74, v74
	v_rcp_f32_e32 v75, v75
	s_nop 0
	v_pk_mul_f32 v[70:71], v[70:71], v[74:75]
	s_nop 0
	v_pk_mul_f32 v[66:67], v[70:71], v[66:67]
	s_nop 0
	v_cvt_pk_bf16_f32 v66, v66, v67
	v_mul_f32_e32 v67, 0xbfb8aa3b, v72
	v_exp_f32_e32 v67, v67
	s_nop 0
	v_add_f32_e32 v67, 1.0, v67
	v_rcp_f32_e32 v70, v67
	v_mul_f32_e32 v67, 0xbfb8aa3b, v73
	v_exp_f32_e32 v67, v67
	s_nop 0
	v_add_f32_e32 v67, 1.0, v67
	v_rcp_f32_e32 v71, v67
	s_nop 0
	v_pk_mul_f32 v[70:71], v[72:73], v[70:71]
	s_nop 0
	v_pk_mul_f32 v[68:69], v[70:71], v[68:69]
	s_nop 0
	v_cvt_pk_bf16_f32 v67, v68, v69
	global_store_dwordx2 v[76:77], v[66:67], off offset:32
	v_mul_f32_e32 v66, 0xbfb8aa3b, v62
	v_mul_f32_e32 v67, 0xbfb8aa3b, v63
	v_exp_f32_e32 v66, v66
	v_exp_f32_e32 v67, v67
	v_add_u32_e32 v68, 0x80, v142
	v_add_f32_e32 v66, 1.0, v66
	v_add_f32_e32 v67, 1.0, v67
	v_rcp_f32_e32 v66, v66
	v_rcp_f32_e32 v67, v67
	s_nop 0
	v_pk_mul_f32 v[62:63], v[62:63], v[66:67]
	s_nop 0
	v_pk_mul_f32 v[58:59], v[62:63], v[58:59]
	s_nop 0
	v_cvt_pk_bf16_f32 v58, v58, v59
	v_mul_f32_e32 v59, 0xbfb8aa3b, v64
	v_exp_f32_e32 v59, v59
	s_nop 0
	v_add_f32_e32 v59, 1.0, v59
	v_rcp_f32_e32 v62, v59
	v_mul_f32_e32 v59, 0xbfb8aa3b, v65
	v_exp_f32_e32 v59, v59
	s_nop 0
	v_add_f32_e32 v59, 1.0, v59
	v_rcp_f32_e32 v63, v59
	s_nop 0
	v_pk_mul_f32 v[62:63], v[64:65], v[62:63]
	s_nop 0
	v_pk_mul_f32 v[60:61], v[62:63], v[60:61]
	s_nop 0
	v_cvt_pk_bf16_f32 v59, v60, v61
	v_mad_i64_i32 v[60:61], s[18:19], v68, s50, v[122:123]
	v_lshl_add_u64 v[60:61], v[60:61], 0, v[124:125]
	global_store_dwordx2 v[60:61], v[58:59], off
	v_mul_f32_e32 v58, 0xbfb8aa3b, v54
; __device__ __forceinline__ float silu_f(float x) { return x * sigm(x); }
; #define PG8_WAIT_V(n) asm volatile("s_waitcnt vmcnt(" #n ")" ::: "memory")
; #define PG8_BAR __builtin_amdgcn_s_barrier()
; template <class Epi, class Sched>
; __device__ __forceinline__ void gemm_phase(PG8_LAS unsigned char* lds, const int lda, const int ldb, const Sched& S, const Epi& E) {
;     ...
;   PG8_WAIT_V(0);
;   if (wr == 0) PG8_BAR;
;   __device__ __forceinline__ void operator()(const f32x4 (&acc)[2][2][4][2], const Unit& u, int wr, int wc, int fr, int fq) const {
;     ...
;           const f32x4 g = acc[ai][0][m][n], up = acc[ai][1][m][n];
;           const int c = u.pn * 128 + wc * 32 + n * 16 + 4 * fq;
;           uint2 w;
;           w.x = pack2(silu_f(g[0]) * up[0], silu_f(g[1]) * up[1]);
;           w.y = pack2(silu_f(g[2]) * up[2], silu_f(g[3]) * up[3]);
;           *reinterpret_cast<uint2*>(HID + (size_t)r * DFF + c) = w;
	v_mul_f32_e32 v59, 0xbfb8aa3b, v55
	v_exp_f32_e32 v58, v58
	v_exp_f32_e32 v59, v59
	v_add_f32_e32 v58, 1.0, v58
	v_add_f32_e32 v59, 1.0, v59
	v_rcp_f32_e32 v58, v58
	v_rcp_f32_e32 v59, v59
	s_nop 0
	v_pk_mul_f32 v[54:55], v[54:55], v[58:59]
	s_nop 0
	v_pk_mul_f32 v[50:51], v[54:55], v[50:51]
	s_nop 0
	v_cvt_pk_bf16_f32 v50, v50, v51
	v_mul_f32_e32 v51, 0xbfb8aa3b, v56
	v_exp_f32_e32 v51, v51
	s_nop 0
	v_add_f32_e32 v51, 1.0, v51
	v_rcp_f32_e32 v54, v51
	v_mul_f32_e32 v51, 0xbfb8aa3b, v57
	v_exp_f32_e32 v51, v51
	s_nop 0
	v_add_f32_e32 v51, 1.0, v51
	v_rcp_f32_e32 v55, v51
	s_nop 0
	v_pk_mul_f32 v[54:55], v[56:57], v[54:55]
	s_nop 0
	v_pk_mul_f32 v[52:53], v[54:55], v[52:53]
	s_nop 0
	v_cvt_pk_bf16_f32 v51, v52, v53
	global_store_dwordx2 v[60:61], v[50:51], off offset:32
	v_mul_f32_e32 v50, 0xbfb8aa3b, v46
	v_mul_f32_e32 v51, 0xbfb8aa3b, v47
	v_exp_f32_e32 v50, v50
	v_exp_f32_e32 v51, v51
	v_add_u32_e32 v52, 0x90, v142
	v_add_f32_e32 v50, 1.0, v50
	v_add_f32_e32 v51, 1.0, v51
	v_rcp_f32_e32 v50, v50
	v_rcp_f32_e32 v51, v51
	s_nop 0
	v_pk_mul_f32 v[46:47], v[46:47], v[50:51]
	s_nop 0
	v_pk_mul_f32 v[42:43], v[46:47], v[42:43]
	s_nop 0
	v_cvt_pk_bf16_f32 v42, v42, v43
	v_mul_f32_e32 v43, 0xbfb8aa3b, v48
	v_exp_f32_e32 v43, v43
	s_nop 0
	v_add_f32_e32 v43, 1.0, v43
	v_rcp_f32_e32 v46, v43
	v_mul_f32_e32 v43, 0xbfb8aa3b, v49
	v_exp_f32_e32 v43, v43
	s_nop 0
	v_add_f32_e32 v43, 1.0, v43
	v_rcp_f32_e32 v47, v43
	s_nop 0
	v_pk_mul_f32 v[46:47], v[48:49], v[46:47]
	s_nop 0
	v_pk_mul_f32 v[44:45], v[46:47], v[44:45]
	s_nop 0
	v_cvt_pk_bf16_f32 v43, v44, v45
	v_mad_i64_i32 v[44:45], s[18:19], v52, s50, v[122:123]
	v_lshl_add_u64 v[44:45], v[44:45], 0, v[124:125]
	global_store_dwordx2 v[44:45], v[42:43], off
	v_mul_f32_e32 v42, 0xbfb8aa3b, v38
	v_mul_f32_e32 v43, 0xbfb8aa3b, v39
	v_exp_f32_e32 v42, v42
	v_exp_f32_e32 v43, v43
	v_add_f32_e32 v42, 1.0, v42
	v_add_f32_e32 v43, 1.0, v43
	v_rcp_f32_e32 v42, v42
	v_rcp_f32_e32 v43, v43
	s_nop 0
	v_pk_mul_f32 v[38:39], v[38:39], v[42:43]
	s_nop 0
	v_pk_mul_f32 v[34:35], v[38:39], v[34:35]
	s_nop 0
	v_cvt_pk_bf16_f32 v34, v34, v35
	v_mul_f32_e32 v35, 0xbfb8aa3b, v40
	v_exp_f32_e32 v35, v35
	s_nop 0
	v_add_f32_e32 v35, 1.0, v35
	v_rcp_f32_e32 v38, v35
	v_mul_f32_e32 v35, 0xbfb8aa3b, v41
	v_exp_f32_e32 v35, v35
	s_nop 0
	v_add_f32_e32 v35, 1.0, v35
	v_rcp_f32_e32 v39, v35
	s_nop 0
	v_pk_mul_f32 v[38:39], v[40:41], v[38:39]
	s_nop 0
	v_pk_mul_f32 v[36:37], v[38:39], v[36:37]
	s_nop 0
	v_cvt_pk_bf16_f32 v35, v36, v37
	global_store_dwordx2 v[44:45], v[34:35], off offset:32
	v_mul_f32_e32 v34, 0xbfb8aa3b, v30
	v_mul_f32_e32 v35, 0xbfb8aa3b, v31
	v_exp_f32_e32 v34, v34
	v_exp_f32_e32 v35, v35
	v_add_u32_e32 v36, 0xa0, v142
	v_add_f32_e32 v34, 1.0, v34
	v_add_f32_e32 v35, 1.0, v35
	v_rcp_f32_e32 v34, v34
	v_rcp_f32_e32 v35, v35
	s_nop 0
	v_pk_mul_f32 v[30:31], v[30:31], v[34:35]
	s_nop 0
	v_pk_mul_f32 v[26:27], v[30:31], v[26:27]
	s_nop 0
	v_cvt_pk_bf16_f32 v26, v26, v27
	v_mul_f32_e32 v27, 0xbfb8aa3b, v32
	v_exp_f32_e32 v27, v27
	s_nop 0
	v_add_f32_e32 v27, 1.0, v27
	v_rcp_f32_e32 v30, v27
	v_mul_f32_e32 v27, 0xbfb8aa3b, v33
	v_exp_f32_e32 v27, v27
	s_nop 0
	v_add_f32_e32 v27, 1.0, v27
	v_rcp_f32_e32 v31, v27
	s_nop 0
	v_pk_mul_f32 v[30:31], v[32:33], v[30:31]
	s_nop 0
	v_pk_mul_f32 v[28:29], v[30:31], v[28:29]
	s_nop 0
	v_cvt_pk_bf16_f32 v27, v28, v29
	v_mad_i64_i32 v[28:29], s[18:19], v36, s50, v[122:123]
	v_lshl_add_u64 v[28:29], v[28:29], 0, v[124:125]
	global_store_dwordx2 v[28:29], v[26:27], off
	v_mul_f32_e32 v26, 0xbfb8aa3b, v22
	v_mul_f32_e32 v27, 0xbfb8aa3b, v23
	v_exp_f32_e32 v26, v26
	v_exp_f32_e32 v27, v27
	v_add_f32_e32 v26, 1.0, v26
	v_add_f32_e32 v27, 1.0, v27
	v_rcp_f32_e32 v26, v26
	v_rcp_f32_e32 v27, v27
	s_nop 0
	v_pk_mul_f32 v[22:23], v[22:23], v[26:27]
	s_nop 0
	v_pk_mul_f32 v[18:19], v[22:23], v[18:19]
	s_nop 0
	v_cvt_pk_bf16_f32 v18, v18, v19
	v_mul_f32_e32 v19, 0xbfb8aa3b, v24
	v_exp_f32_e32 v19, v19
	s_nop 0
	v_add_f32_e32 v19, 1.0, v19
	v_rcp_f32_e32 v22, v19
	v_mul_f32_e32 v19, 0xbfb8aa3b, v25
	v_exp_f32_e32 v19, v19
	s_nop 0
	v_add_f32_e32 v19, 1.0, v19
	v_rcp_f32_e32 v23, v19
	s_nop 0
	v_pk_mul_f32 v[22:23], v[24:25], v[22:23]
	s_nop 0
	v_pk_mul_f32 v[20:21], v[22:23], v[20:21]
	s_nop 0
	v_cvt_pk_bf16_f32 v19, v20, v21
	global_store_dwordx2 v[28:29], v[18:19], off offset:32
	v_mul_f32_e32 v18, 0xbfb8aa3b, v14
	v_mul_f32_e32 v19, 0xbfb8aa3b, v15
	v_exp_f32_e32 v18, v18
	v_exp_f32_e32 v19, v19
	v_add_u32_e32 v20, 0xb0, v142
	v_add_f32_e32 v18, 1.0, v18
	v_add_f32_e32 v19, 1.0, v19
	v_rcp_f32_e32 v18, v18
	v_rcp_f32_e32 v19, v19
	s_nop 0
	v_pk_mul_f32 v[14:15], v[14:15], v[18:19]
	s_nop 0
	v_pk_mul_f32 v[10:11], v[14:15], v[10:11]
	s_nop 0
	v_cvt_pk_bf16_f32 v10, v10, v11
	v_mul_f32_e32 v11, 0xbfb8aa3b, v16
	v_exp_f32_e32 v11, v11
	s_nop 0
	v_add_f32_e32 v11, 1.0, v11
	v_rcp_f32_e32 v14, v11
	v_mul_f32_e32 v11, 0xbfb8aa3b, v17
	v_exp_f32_e32 v11, v11
	s_nop 0
	v_add_f32_e32 v11, 1.0, v11
	v_rcp_f32_e32 v15, v11
	s_nop 0
	v_pk_mul_f32 v[14:15], v[16:17], v[14:15]
	s_nop 0
	v_pk_mul_f32 v[12:13], v[14:15], v[12:13]
	s_nop 0
	v_cvt_pk_bf16_f32 v11, v12, v13
	v_mad_i64_i32 v[12:13], s[18:19], v20, s50, v[122:123]
	v_lshl_add_u64 v[12:13], v[12:13], 0, v[124:125]
	global_store_dwordx2 v[12:13], v[10:11], off
	v_mul_f32_e32 v10, 0xbfb8aa3b, v6
	v_mul_f32_e32 v11, 0xbfb8aa3b, v7
	v_exp_f32_e32 v10, v10
	v_exp_f32_e32 v11, v11
	s_mov_b64 s[18:19], s[12:13]
	v_add_f32_e32 v10, 1.0, v10
	v_add_f32_e32 v11, 1.0, v11
	v_rcp_f32_e32 v10, v10
	v_rcp_f32_e32 v11, v11
	s_nop 0
	v_pk_mul_f32 v[6:7], v[6:7], v[10:11]
	s_nop 0
	v_pk_mul_f32 v[2:3], v[6:7], v[2:3]
	s_nop 0
	v_cvt_pk_bf16_f32 v2, v2, v3
	v_mul_f32_e32 v3, 0xbfb8aa3b, v8
	v_exp_f32_e32 v3, v3
	s_nop 0
	v_add_f32_e32 v3, 1.0, v3
	v_rcp_f32_e32 v6, v3
	v_mul_f32_e32 v3, 0xbfb8aa3b, v9
	v_exp_f32_e32 v3, v3
	s_nop 0
	v_add_f32_e32 v3, 1.0, v3
	v_rcp_f32_e32 v7, v3
	s_nop 0
	v_pk_mul_f32 v[6:7], v[8:9], v[6:7]
	s_nop 0
	v_pk_mul_f32 v[4:5], v[6:7], v[4:5]
	s_nop 0
	v_cvt_pk_bf16_f32 v3, v4, v5
	global_store_dwordx2 v[12:13], v[2:3], off offset:32
	s_cbranch_vccz .LBB0_1601
	s_waitcnt vmcnt(0)
	v_readlane_b32 s40, v253, 12
	s_cmpk_gt_u32 s9, 0xff
	v_readlane_b32 s41, v253, 13
	v_readlane_b32 s44, v253, 16
	v_readlane_b32 s45, v253, 17
	v_readlane_b32 s52, v253, 24
	v_readlane_b32 s53, v253, 25
	v_readlane_b32 s54, v253, 26
	v_readlane_b32 s55, v253, 27
	v_readlane_b32 s38, v255, 23
	v_readlane_b32 s42, v253, 14
	v_readlane_b32 s43, v253, 15
	v_readlane_b32 s46, v253, 18
	v_readlane_b32 s47, v253, 19
	v_readlane_b32 s48, v253, 20
	v_readlane_b32 s49, v253, 21
	v_readlane_b32 s50, v253, 22
	v_readlane_b32 s51, v253, 23
	v_readlane_b32 s39, v255, 24
	s_cbranch_scc1 .LBB0_1608
	s_barrier

; #define PG8_STAGE(bufoff, gbase, voff) do { _Pragma("unroll") for (int _i = 0; _i < 2; ++_i) \
;     __builtin_amdgcn_global_load_lds((const unsigned*)((const char*)(gbase) + (voff)[_i]), (PG8_LAS unsigned*)(lds + (bufoff) + ldsw + _i * 8192), 16, 0, 0); } while (0)
; #define PG8_LDA(dst, b, h) do { _Pragma("unroll") for (int m = 0; m < 4; ++m) _Pragma("unroll") for (int k = 0; k < 2; ++k) dst[m][k] = *(const PG8_LAS bf16x8*)(lds + PG8_SA(b, h) + aoff + m * 2048 + k * 1024); } while (0)
; #define PG8_LDB(dst, b, h) do { _Pragma("unroll") for (int n = 0; n < 2; ++n) _Pragma("unroll") for (int k = 0; k < 2; ++k) dst[n][k] = *(const PG8_LAS bf16x8*)(lds + PG8_SB(b, h) + boff + n * 2048 + k * 1024); } while (0)
; #define PG8_MMA(ai, bj, At, Bt) do { __builtin_amdgcn_s_setprio(1); _Pragma("unroll") for (int m = 0; m < 4; ++m) _Pragma("unroll") for (int n = 0; n < 2; ++n) _Pragma("unroll") for (int k = 0; k < 2; ++k) \
;     acc[ai][bj][m][n] = __builtin_amdgcn_mfma_f32_16x16x32_bf16(Bt[n][k], At[m][k], acc[ai][bj][m][n], 0, 0, 0); __builtin_amdgcn_s_setprio(0); } while (0)
; #define PG8_WAIT_L(n) asm volatile("s_waitcnt lgkmcnt(" #n ")" ::: "memory")
; #define PG8_BAR __builtin_amdgcn_s_barrier()
; #define PG8_SCHED __builtin_amdgcn_sched_barrier(0)
; template <class Epi, class Sched>
; __device__ __forceinline__ void gemm_phase(PG8_LAS unsigned char* lds, const int lda, const int ldb, const Sched& S, const Epi& E) {
;     ...
;       PG8_LDB(B0, 0, 0); PG8_SCHED; PG8_LDA(At, 0, 0); PG8_STAGE(PG8_SA(1, 1), a1 + hstepA, voffA);
;       PG8_WAIT_L(8); PG8_BAR; PG8_WAIT_L(0); PG8_MMA(0, 0, At, B0); PG8_BAR; PG8_SCHED;
;       PG8_LDB(B1, 0, 1); PG8_STAGE(PG8_SB(0, 0), b2, voffB);
;       PG8_BAR; PG8_WAIT_L(0); PG8_MMA(0, 1, At, B1); PG8_BAR;
;       PG8_LDA(At, 0, 1); PG8_STAGE(PG8_SA(0, 0), a2, voffA);
;       PG8_BAR; PG8_WAIT_L(0); PG8_MMA(1, 0, At, B0); PG8_BAR; PG8_SCHED;
.LBB0_1673:
	s_add_u32 s12, s10, 0x100
	s_addc_u32 s13, s11, 0
	s_add_i32 s33, 0, 0x10000
	v_add_u32_e32 v154, s33, v131
	ds_read_b128 v[140:143], v154
	ds_read_b128 v[146:149], v154 offset:1024
	ds_read_b128 v[150:153], v154 offset:2048
	ds_read_b128 v[154:157], v154 offset:3072
	s_cmp_eq_u32 s41, 40
	s_cselect_b32 s17, s7, s13
	s_cselect_b32 s16, s6, s12
	s_cselect_b32 s15, s1, s40
	s_cselect_b32 s14, s0, s39
	v_lshl_add_u64 v[174:175], s[10:11], 0, v[136:137]
	s_add_i32 m0, s23, 0xc000
	ds_read_b128 v[158:161], v145
	ds_read_b128 v[162:165], v145 offset:1024
	ds_read_b128 v[166:169], v145 offset:2048
	ds_read_b128 v[170:173], v145 offset:3072
	ds_read_b128 v[200:203], v145 offset:4096
	ds_read_b128 v[204:207], v145 offset:5120
	ds_read_b128 v[208:211], v145 offset:6144
	ds_read_b128 v[212:215], v145 offset:7168
	global_load_lds_dwordx4 v[174:175], off
	v_lshl_add_u64 v[174:175], s[10:11], 0, v[138:139]
	s_add_i32 m0, s23, 0xe000
	s_nop 0
	global_load_lds_dwordx4 v[174:175], off
	s_waitcnt lgkmcnt(8)
	s_barrier
	s_waitcnt lgkmcnt(0)
	v_mfma_f32_16x16x32_bf16 v[126:129], v[140:143], v[158:161], v[126:129]
	v_mfma_f32_16x16x32_bf16 v[122:125], v[150:153], v[158:161], v[122:125]
	v_mfma_f32_16x16x32_bf16 v[110:113], v[140:143], v[166:169], v[110:113]
	v_mfma_f32_16x16x32_bf16 v[106:109], v[150:153], v[166:169], v[106:109]
	v_mfma_f32_16x16x32_bf16 v[94:97], v[140:143], v[200:203], v[94:97]
	v_mfma_f32_16x16x32_bf16 v[90:93], v[150:153], v[200:203], v[90:93]
	v_mfma_f32_16x16x32_bf16 v[78:81], v[140:143], v[208:211], v[78:81]
	v_mfma_f32_16x16x32_bf16 v[74:77], v[150:153], v[208:211], v[74:77]
	v_mfma_f32_16x16x32_bf16 v[126:129], v[146:149], v[162:165], v[126:129]
	v_mfma_f32_16x16x32_bf16 v[122:125], v[154:157], v[162:165], v[122:125]
	v_mfma_f32_16x16x32_bf16 v[110:113], v[146:149], v[170:173], v[110:113]
	v_mfma_f32_16x16x32_bf16 v[106:109], v[154:157], v[170:173], v[106:109]
	v_mfma_f32_16x16x32_bf16 v[94:97], v[146:149], v[204:207], v[94:97]
	v_mfma_f32_16x16x32_bf16 v[90:93], v[154:157], v[204:207], v[90:93]
	v_mfma_f32_16x16x32_bf16 v[78:81], v[146:149], v[212:215], v[78:81]
	v_mfma_f32_16x16x32_bf16 v[74:77], v[154:157], v[212:215], v[74:77]
	s_barrier
	s_add_i32 s42, 0, 0x14000
	v_add_u32_e32 v174, s42, v131
	s_add_i32 s10, s33, s20
	ds_read_b128 v[216:219], v174
	ds_read_b128 v[220:223], v174 offset:1024
	ds_read_b128 v[224:227], v174 offset:2048
	ds_read_b128 v[228:231], v174 offset:3072
	v_lshl_add_u64 v[174:175], s[14:15], 0, v[134:135]
	s_mov_b32 m0, s10
	v_lshl_add_u64 v[182:183], s[14:15], 0, v[132:133]
	global_load_lds_dwordx4 v[174:175], off
	s_add_i32 m0, s10, 0x2000
	s_nop 0
	global_load_lds_dwordx4 v[182:183], off
	s_barrier
	s_waitcnt lgkmcnt(0)
	v_mfma_f32_16x16x32_bf16 v[118:121], v[216:219], v[158:161], v[118:121]
	v_mfma_f32_16x16x32_bf16 v[114:117], v[224:227], v[158:161], v[114:117]
	v_mfma_f32_16x16x32_bf16 v[102:105], v[216:219], v[166:169], v[102:105]
	v_mfma_f32_16x16x32_bf16 v[98:101], v[224:227], v[166:169], v[98:101]
	v_mfma_f32_16x16x32_bf16 v[86:89], v[216:219], v[200:203], v[86:89]
	v_mfma_f32_16x16x32_bf16 v[82:85], v[224:227], v[200:203], v[82:85]
	v_mfma_f32_16x16x32_bf16 v[70:73], v[216:219], v[208:211], v[70:73]
	v_mfma_f32_16x16x32_bf16 v[66:69], v[224:227], v[208:211], v[66:69]
	v_mfma_f32_16x16x32_bf16 v[118:121], v[220:223], v[162:165], v[118:121]
	v_mfma_f32_16x16x32_bf16 v[114:117], v[228:231], v[162:165], v[114:117]
	v_mfma_f32_16x16x32_bf16 v[102:105], v[220:223], v[170:173], v[102:105]
	v_mfma_f32_16x16x32_bf16 v[98:101], v[228:231], v[170:173], v[98:101]
	v_mfma_f32_16x16x32_bf16 v[86:89], v[220:223], v[204:207], v[86:89]
	v_mfma_f32_16x16x32_bf16 v[82:85], v[228:231], v[204:207], v[82:85]
	v_mfma_f32_16x16x32_bf16 v[70:73], v[220:223], v[212:215], v[70:73]
	v_mfma_f32_16x16x32_bf16 v[66:69], v[228:231], v[212:215], v[66:69]
	s_barrier
	s_mov_b32 m0, s23
	v_lshl_add_u64 v[184:185], s[16:17], 0, v[134:135]
	ds_read_b128 v[158:161], v145 offset:16384
	ds_read_b128 v[162:165], v145 offset:17408
	ds_read_b128 v[166:169], v145 offset:18432
	ds_read_b128 v[170:173], v145 offset:19456
	ds_read_b128 v[200:203], v145 offset:20480
	ds_read_b128 v[204:207], v145 offset:21504
	ds_read_b128 v[208:211], v145 offset:22528
	ds_read_b128 v[212:215], v145 offset:23552
	global_load_lds_dwordx4 v[184:185], off
	v_lshl_add_u64 v[232:233], s[16:17], 0, v[132:133]
	s_mov_b32 m0, s24
	s_nop 0
	global_load_lds_dwordx4 v[232:233], off
	s_barrier
	s_waitcnt lgkmcnt(0)
	v_mfma_f32_16x16x32_bf16 v[62:65], v[140:143], v[158:161], v[62:65]
	v_mfma_f32_16x16x32_bf16 v[58:61], v[150:153], v[158:161], v[58:61]
	v_mfma_f32_16x16x32_bf16 v[46:49], v[140:143], v[166:169], v[46:49]
	v_mfma_f32_16x16x32_bf16 v[42:45], v[150:153], v[166:169], v[42:45]
	v_mfma_f32_16x16x32_bf16 v[30:33], v[140:143], v[200:203], v[30:33]
	v_mfma_f32_16x16x32_bf16 v[26:29], v[150:153], v[200:203], v[26:29]
	v_mfma_f32_16x16x32_bf16 v[14:17], v[140:143], v[208:211], v[14:17]
	v_mfma_f32_16x16x32_bf16 v[10:13], v[150:153], v[208:211], v[10:13]
	v_mfma_f32_16x16x32_bf16 v[62:65], v[146:149], v[162:165], v[62:65]
	v_mfma_f32_16x16x32_bf16 v[58:61], v[154:157], v[162:165], v[58:61]
	v_mfma_f32_16x16x32_bf16 v[46:49], v[146:149], v[170:173], v[46:49]
	v_mfma_f32_16x16x32_bf16 v[42:45], v[154:157], v[170:173], v[42:45]
	v_mfma_f32_16x16x32_bf16 v[30:33], v[146:149], v[204:207], v[30:33]
	v_mfma_f32_16x16x32_bf16 v[26:29], v[154:157], v[204:207], v[26:29]
	v_mfma_f32_16x16x32_bf16 v[14:17], v[146:149], v[212:215], v[14:17]
	v_mfma_f32_16x16x32_bf16 v[10:13], v[154:157], v[212:215], v[10:13]
	s_barrier
; #define PG8_STAGE(bufoff, gbase, voff) do { _Pragma("unroll") for (int _i = 0; _i < 2; ++_i) \
;     __builtin_amdgcn_global_load_lds((const unsigned*)((const char*)(gbase) + (voff)[_i]), (PG8_LAS unsigned*)(lds + (bufoff) + ldsw + _i * 8192), 16, 0, 0); } while (0)
; #define PG8_LDA(dst, b, h) do { _Pragma("unroll") for (int m = 0; m < 4; ++m) _Pragma("unroll") for (int k = 0; k < 2; ++k) dst[m][k] = *(const PG8_LAS bf16x8*)(lds + PG8_SA(b, h) + aoff + m * 2048 + k * 1024); } while (0)
; #define PG8_LDB(dst, b, h) do { _Pragma("unroll") for (int n = 0; n < 2; ++n) _Pragma("unroll") for (int k = 0; k < 2; ++k) dst[n][k] = *(const PG8_LAS bf16x8*)(lds + PG8_SB(b, h) + boff + n * 2048 + k * 1024); } while (0)
; #define PG8_MMA(ai, bj, At, Bt) do { __builtin_amdgcn_s_setprio(1); _Pragma("unroll") for (int m = 0; m < 4; ++m) _Pragma("unroll") for (int n = 0; n < 2; ++n) _Pragma("unroll") for (int k = 0; k < 2; ++k) \
;     acc[ai][bj][m][n] = __builtin_amdgcn_mfma_f32_16x16x32_bf16(Bt[n][k], At[m][k], acc[ai][bj][m][n], 0, 0, 0); __builtin_amdgcn_s_setprio(0); } while (0)
; #define PG8_WAIT_V(n) asm volatile("s_waitcnt vmcnt(" #n ")" ::: "memory")
; #define PG8_WAIT_L(n) asm volatile("s_waitcnt lgkmcnt(" #n ")" ::: "memory")
; #define PG8_BAR __builtin_amdgcn_s_barrier()
; #define PG8_SCHED __builtin_amdgcn_sched_barrier(0)
; template <class Epi, class Sched>
; __device__ __forceinline__ void gemm_phase(PG8_LAS unsigned char* lds, const int lda, const int ldb, const Sched& S, const Epi& E) {
;     ...
;       PG8_STAGE(PG8_SB(0, 1), b2 + hstepB, voffB);
;       PG8_WAIT_V(6); PG8_BAR; PG8_MMA(1, 1, At, B1); PG8_BAR;
;       PG8_LDB(B0, 1, 0); PG8_SCHED; PG8_LDA(At, 1, 0); PG8_STAGE(PG8_SA(0, 1), a2 + hstepA, voffA);
;       PG8_WAIT_L(8); PG8_BAR; PG8_WAIT_L(0); PG8_MMA(0, 0, At, B0); PG8_BAR; PG8_SCHED;
;       PG8_LDB(B1, 1, 1); PG8_STAGE(PG8_SB(1, 0), b3, voffB);
;       PG8_BAR; PG8_WAIT_L(0); PG8_MMA(0, 1, At, B1); PG8_BAR;
;       PG8_LDA(At, 1, 1); PG8_STAGE(PG8_SA(1, 0), a3, voffA);
	s_add_u32 s10, s14, 0xb0000
	s_addc_u32 s11, s15, 0
	s_add_i32 s33, s42, s20
	v_lshl_add_u64 v[140:141], s[10:11], 0, v[134:135]
	s_mov_b32 m0, s33
	s_nop 0
	global_load_lds_dwordx4 v[140:141], off
	v_lshl_add_u64 v[140:141], s[10:11], 0, v[132:133]
	s_add_i32 m0, s33, 0x2000
	s_nop 0
	global_load_lds_dwordx4 v[140:141], off
	s_waitcnt vmcnt(6)
	s_barrier
	v_mfma_f32_16x16x32_bf16 v[54:57], v[216:219], v[158:161], v[54:57]
	v_mfma_f32_16x16x32_bf16 v[50:53], v[224:227], v[158:161], v[50:53]
	v_mfma_f32_16x16x32_bf16 v[38:41], v[216:219], v[166:169], v[38:41]
	v_mfma_f32_16x16x32_bf16 v[34:37], v[224:227], v[166:169], v[34:37]
	v_mfma_f32_16x16x32_bf16 v[22:25], v[216:219], v[200:203], v[22:25]
	v_mfma_f32_16x16x32_bf16 v[18:21], v[224:227], v[200:203], v[18:21]
	v_mfma_f32_16x16x32_bf16 v[6:9], v[216:219], v[208:211], v[6:9]
	v_mfma_f32_16x16x32_bf16 v[2:5], v[224:227], v[208:211], v[2:5]
	v_mfma_f32_16x16x32_bf16 v[54:57], v[220:223], v[162:165], v[54:57]
	v_mfma_f32_16x16x32_bf16 v[50:53], v[228:231], v[162:165], v[50:53]
	v_mfma_f32_16x16x32_bf16 v[38:41], v[220:223], v[170:173], v[38:41]
	v_mfma_f32_16x16x32_bf16 v[34:37], v[228:231], v[170:173], v[34:37]
	v_mfma_f32_16x16x32_bf16 v[22:25], v[220:223], v[204:207], v[22:25]
	v_mfma_f32_16x16x32_bf16 v[18:21], v[228:231], v[204:207], v[18:21]
	v_mfma_f32_16x16x32_bf16 v[6:9], v[220:223], v[212:215], v[6:9]
	v_mfma_f32_16x16x32_bf16 v[2:5], v[228:231], v[212:215], v[2:5]
	s_barrier
	s_add_i32 s33, 0, 0x18000
	v_add_u32_e32 v154, s33, v131
	ds_read_b128 v[140:143], v154
	ds_read_b128 v[146:149], v154 offset:1024
	ds_read_b128 v[150:153], v154 offset:2048
	ds_read_b128 v[154:157], v154 offset:3072
	s_add_u32 s10, s16, 0xb0000
	s_addc_u32 s11, s17, 0
	s_mov_b32 m0, s25
	v_lshl_add_u64 v[216:217], s[10:11], 0, v[134:135]
	ds_read_b128 v[158:161], v145 offset:32768
	ds_read_b128 v[162:165], v145 offset:33792
	ds_read_b128 v[166:169], v145 offset:34816
	ds_read_b128 v[170:173], v145 offset:35840
	ds_read_b128 v[200:203], v145 offset:36864
	ds_read_b128 v[204:207], v145 offset:37888
	ds_read_b128 v[208:211], v145 offset:38912
	ds_read_b128 v[212:215], v145 offset:39936
	global_load_lds_dwordx4 v[216:217], off
	v_lshl_add_u64 v[216:217], s[10:11], 0, v[132:133]
	s_mov_b32 m0, s26
	s_nop 0
	global_load_lds_dwordx4 v[216:217], off
	s_waitcnt lgkmcnt(8)
	s_barrier
	s_waitcnt lgkmcnt(0)
	v_mfma_f32_16x16x32_bf16 v[126:129], v[140:143], v[158:161], v[126:129]
	v_mfma_f32_16x16x32_bf16 v[122:125], v[150:153], v[158:161], v[122:125]
	v_mfma_f32_16x16x32_bf16 v[110:113], v[140:143], v[166:169], v[110:113]
	v_mfma_f32_16x16x32_bf16 v[106:109], v[150:153], v[166:169], v[106:109]
	v_mfma_f32_16x16x32_bf16 v[94:97], v[140:143], v[200:203], v[94:97]
	v_mfma_f32_16x16x32_bf16 v[90:93], v[150:153], v[200:203], v[90:93]
	v_mfma_f32_16x16x32_bf16 v[78:81], v[140:143], v[208:211], v[78:81]
	v_mfma_f32_16x16x32_bf16 v[74:77], v[150:153], v[208:211], v[74:77]
	v_mfma_f32_16x16x32_bf16 v[126:129], v[146:149], v[162:165], v[126:129]
	v_mfma_f32_16x16x32_bf16 v[122:125], v[154:157], v[162:165], v[122:125]
	v_mfma_f32_16x16x32_bf16 v[110:113], v[146:149], v[170:173], v[110:113]
	v_mfma_f32_16x16x32_bf16 v[106:109], v[154:157], v[170:173], v[106:109]
	v_mfma_f32_16x16x32_bf16 v[94:97], v[146:149], v[204:207], v[94:97]
	v_mfma_f32_16x16x32_bf16 v[90:93], v[154:157], v[204:207], v[90:93]
	v_mfma_f32_16x16x32_bf16 v[78:81], v[146:149], v[212:215], v[78:81]
	v_mfma_f32_16x16x32_bf16 v[74:77], v[154:157], v[212:215], v[74:77]
	s_barrier
	s_add_i32 s16, 0, 0x1c000
	s_add_i32 s10, s33, s20
	v_add_u32_e32 v228, s16, v131
	v_lshl_add_u64 v[174:175], v[174:175], 0, s[86:87]
	s_mov_b32 m0, s10
	ds_read_b128 v[216:219], v228
	ds_read_b128 v[220:223], v228 offset:1024
	ds_read_b128 v[224:227], v228 offset:2048
	ds_read_b128 v[228:231], v228 offset:3072
	global_load_lds_dwordx4 v[174:175], off
	v_lshl_add_u64 v[174:175], v[182:183], 0, s[86:87]
	s_add_i32 m0, s10, 0x2000
	s_nop 0
	global_load_lds_dwordx4 v[174:175], off
	s_barrier
; #define PG8_STAGE(bufoff, gbase, voff) do { _Pragma("unroll") for (int _i = 0; _i < 2; ++_i) \
;     __builtin_amdgcn_global_load_lds((const unsigned*)((const char*)(gbase) + (voff)[_i]), (PG8_LAS unsigned*)(lds + (bufoff) + ldsw + _i * 8192), 16, 0, 0); } while (0)
; #define PG8_LDA(dst, b, h) do { _Pragma("unroll") for (int m = 0; m < 4; ++m) _Pragma("unroll") for (int k = 0; k < 2; ++k) dst[m][k] = *(const PG8_LAS bf16x8*)(lds + PG8_SA(b, h) + aoff + m * 2048 + k * 1024); } while (0)
; #define PG8_MMA(ai, bj, At, Bt) do { __builtin_amdgcn_s_setprio(1); _Pragma("unroll") for (int m = 0; m < 4; ++m) _Pragma("unroll") for (int n = 0; n < 2; ++n) _Pragma("unroll") for (int k = 0; k < 2; ++k) \
;     acc[ai][bj][m][n] = __builtin_amdgcn_mfma_f32_16x16x32_bf16(Bt[n][k], At[m][k], acc[ai][bj][m][n], 0, 0, 0); __builtin_amdgcn_s_setprio(0); } while (0)
; #define PG8_WAIT_V(n) asm volatile("s_waitcnt vmcnt(" #n ")" ::: "memory")
; #define PG8_WAIT_L(n) asm volatile("s_waitcnt lgkmcnt(" #n ")" ::: "memory")
; #define PG8_BAR __builtin_amdgcn_s_barrier()
; #define PG8_SCHED __builtin_amdgcn_sched_barrier(0)
; template <class Epi, class Sched>
; __device__ __forceinline__ void gemm_phase(PG8_LAS unsigned char* lds, const int lda, const int ldb, const Sched& S, const Epi& E) {
;     ...
;       PG8_BAR; PG8_WAIT_L(0); PG8_MMA(0, 1, At, B1); PG8_BAR;
;       PG8_LDA(At, 1, 1); PG8_STAGE(PG8_SA(1, 0), a3, voffA);
;       PG8_BAR; PG8_WAIT_L(0); PG8_MMA(1, 0, At, B0); PG8_BAR; PG8_SCHED;
;       PG8_STAGE(PG8_SB(1, 1), b3 + hstepB, voffB);
;       PG8_WAIT_V(6); PG8_BAR; PG8_MMA(1, 1, At, B1); PG8_BAR;
;   __device__ __forceinline__ void operator()(const f32x4 (&acc)[2][2][4][2], const Unit& u, int wr, int wc, int fr, int fq) const {
;     const int mr = (u.pm * 256 < ML) ? ((u.pm * 256) >> 11) : 32;
;     const float* gp = mod + (size_t)mr * 6144 + gate_off;
	s_waitcnt lgkmcnt(0)
	v_mfma_f32_16x16x32_bf16 v[118:121], v[216:219], v[158:161], v[118:121]
	v_mfma_f32_16x16x32_bf16 v[114:117], v[224:227], v[158:161], v[114:117]
	v_mfma_f32_16x16x32_bf16 v[102:105], v[216:219], v[166:169], v[102:105]
	v_mfma_f32_16x16x32_bf16 v[98:101], v[224:227], v[166:169], v[98:101]
	v_mfma_f32_16x16x32_bf16 v[86:89], v[216:219], v[200:203], v[86:89]
	v_mfma_f32_16x16x32_bf16 v[82:85], v[224:227], v[200:203], v[82:85]
	v_mfma_f32_16x16x32_bf16 v[70:73], v[216:219], v[208:211], v[70:73]
	v_mfma_f32_16x16x32_bf16 v[66:69], v[224:227], v[208:211], v[66:69]
	v_mfma_f32_16x16x32_bf16 v[118:121], v[220:223], v[162:165], v[118:121]
	v_mfma_f32_16x16x32_bf16 v[114:117], v[228:231], v[162:165], v[114:117]
	v_mfma_f32_16x16x32_bf16 v[102:105], v[220:223], v[170:173], v[102:105]
	v_mfma_f32_16x16x32_bf16 v[98:101], v[228:231], v[170:173], v[98:101]
	v_mfma_f32_16x16x32_bf16 v[86:89], v[220:223], v[204:207], v[86:89]
	v_mfma_f32_16x16x32_bf16 v[82:85], v[228:231], v[204:207], v[82:85]
	v_mfma_f32_16x16x32_bf16 v[70:73], v[220:223], v[212:215], v[70:73]
	v_mfma_f32_16x16x32_bf16 v[66:69], v[228:231], v[212:215], v[66:69]
	s_barrier
	s_mov_b32 m0, s28
	v_lshl_add_u64 v[174:175], v[184:185], 0, s[86:87]
	ds_read_b128 v[158:161], v145 offset:49152
	ds_read_b128 v[162:165], v145 offset:50176
	ds_read_b128 v[166:169], v145 offset:51200
	ds_read_b128 v[170:173], v145 offset:52224
	ds_read_b128 v[200:203], v145 offset:53248
	ds_read_b128 v[204:207], v145 offset:54272
	ds_read_b128 v[208:211], v145 offset:55296
	ds_read_b128 v[212:215], v145 offset:56320
	global_load_lds_dwordx4 v[174:175], off
	v_lshl_add_u64 v[174:175], v[232:233], 0, s[86:87]
	s_mov_b32 m0, s29
	s_nop 0
	global_load_lds_dwordx4 v[174:175], off
	s_barrier
	s_waitcnt lgkmcnt(0)
	v_mfma_f32_16x16x32_bf16 v[62:65], v[140:143], v[158:161], v[62:65]
	v_mfma_f32_16x16x32_bf16 v[58:61], v[150:153], v[158:161], v[58:61]
	v_mfma_f32_16x16x32_bf16 v[46:49], v[140:143], v[166:169], v[46:49]
	v_mfma_f32_16x16x32_bf16 v[42:45], v[150:153], v[166:169], v[42:45]
	v_mfma_f32_16x16x32_bf16 v[30:33], v[140:143], v[200:203], v[30:33]
	v_mfma_f32_16x16x32_bf16 v[26:29], v[150:153], v[200:203], v[26:29]
	v_mfma_f32_16x16x32_bf16 v[14:17], v[140:143], v[208:211], v[14:17]
	v_mfma_f32_16x16x32_bf16 v[10:13], v[150:153], v[208:211], v[10:13]
	v_mfma_f32_16x16x32_bf16 v[62:65], v[146:149], v[162:165], v[62:65]
	v_mfma_f32_16x16x32_bf16 v[58:61], v[154:157], v[162:165], v[58:61]
	v_mfma_f32_16x16x32_bf16 v[46:49], v[146:149], v[170:173], v[46:49]
	v_mfma_f32_16x16x32_bf16 v[42:45], v[154:157], v[170:173], v[42:45]
	v_mfma_f32_16x16x32_bf16 v[30:33], v[146:149], v[204:207], v[30:33]
	v_mfma_f32_16x16x32_bf16 v[26:29], v[154:157], v[204:207], v[26:29]
	v_mfma_f32_16x16x32_bf16 v[14:17], v[146:149], v[212:215], v[14:17]
	v_mfma_f32_16x16x32_bf16 v[10:13], v[154:157], v[212:215], v[10:13]
	s_barrier
	s_add_u32 s10, s14, 0xb0080
	s_addc_u32 s11, s15, 0
	s_add_i32 s14, s16, s20
	v_lshl_add_u64 v[140:141], s[10:11], 0, v[134:135]
	s_mov_b32 m0, s14
	s_nop 0
	global_load_lds_dwordx4 v[140:141], off
	v_lshl_add_u64 v[140:141], s[10:11], 0, v[132:133]
	s_add_i32 m0, s14, 0x2000
	s_nop 0
	global_load_lds_dwordx4 v[140:141], off
	s_waitcnt vmcnt(6)
	s_barrier
	v_mfma_f32_16x16x32_bf16 v[54:57], v[216:219], v[158:161], v[54:57]
	v_mfma_f32_16x16x32_bf16 v[50:53], v[224:227], v[158:161], v[50:53]
	v_mfma_f32_16x16x32_bf16 v[38:41], v[216:219], v[166:169], v[38:41]
	v_mfma_f32_16x16x32_bf16 v[34:37], v[224:227], v[166:169], v[34:37]
	v_mfma_f32_16x16x32_bf16 v[22:25], v[216:219], v[200:203], v[22:25]
	v_mfma_f32_16x16x32_bf16 v[18:21], v[224:227], v[200:203], v[18:21]
	v_mfma_f32_16x16x32_bf16 v[6:9], v[216:219], v[208:211], v[6:9]
	v_mfma_f32_16x16x32_bf16 v[2:5], v[224:227], v[208:211], v[2:5]
	v_mfma_f32_16x16x32_bf16 v[54:57], v[220:223], v[162:165], v[54:57]
	v_mfma_f32_16x16x32_bf16 v[50:53], v[228:231], v[162:165], v[50:53]
	v_mfma_f32_16x16x32_bf16 v[38:41], v[220:223], v[170:173], v[38:41]
	v_mfma_f32_16x16x32_bf16 v[34:37], v[228:231], v[170:173], v[34:37]
	v_mfma_f32_16x16x32_bf16 v[22:25], v[220:223], v[204:207], v[22:25]
	v_mfma_f32_16x16x32_bf16 v[18:21], v[228:231], v[204:207], v[18:21]
	v_mfma_f32_16x16x32_bf16 v[6:9], v[220:223], v[212:215], v[6:9]
	v_mfma_f32_16x16x32_bf16 v[2:5], v[228:231], v[212:215], v[2:5]
	s_add_i32 s41, s41, 2
	s_add_u32 s39, s39, 0x100
	s_addc_u32 s40, s40, 0
	s_cmp_gt_u32 s41, 41
	s_mov_b64 s[10:11], s[12:13]
	s_barrier
	s_cbranch_scc0 .LBB0_1673
	s_cmpk_gt_i32 s37, 0xff
	s_mov_b64 s[10:11], 0x30000
	s_cbranch_scc1 .LBB0_1665
	s_ashr_i32 s10, s37, 3
	s_mul_hi_i32 s11, s10, 0x1800
	s_mulk_i32 s10, 0x1800
	s_branch .LBB0_1665
